# combo12 + DPP instead of LDS round trips: 8-lane sum-of-squares butterflies in the mixer store epilogues and xor 1/2/4/8 steps of the SG row LayerNorm reductions use v_mov_b32_dpp
# speedup vs baseline: 1.0087x; 1.0057x over previous
; __device__ __forceinline__ int crow(int r, int hi) { return (r & 3) + 8 * (r >> 2) + 4 * hi; }
; __device__ __forceinline__ unsigned cvtpk_s(float lo, float hi) { typedef __bf16 bf16x2_t __attribute__((ext_vector_type(2))); f32x2 v = {lo, hi}; bf16x2_t b = __builtin_convertvector(v, bf16x2_t); return __builtin_bit_cast(unsigned, b); }
; __device__ __forceinline__ void store_tile(const f32x16* o, const float* rli, bf16_t* stg, bf16_t* Ow, int pitch, float* ss, int lane, int r32, int hi) {
; #pragma unroll
;     for (int r = 0; r < 16; ++r) { const int orow = crow(r, hi);
; #pragma unroll
;         for (int d0 = 0; d0 < 2; ++d0) stg[orow * 64 + d0 * 32 + r32] = (bf16_t)(cvtpk_s(o[d0][r] * rli[r], 0.f) & 0xffffu); }
;     asm volatile("s_waitcnt lgkmcnt(0)" ::: "memory");
; #pragma unroll
;     for (int i = 0; i < 4; ++i) { const int row = i * 8 + (lane >> 3), ch = lane & 7; const u32x4 v = *(const u32x4*)(stg + row * 64 + ch * 8);
;         { const bf16_t* gp_ = Ow + (long)row * pitch + ch * 8; asm volatile("global_store_dwordx4 %0, %1, off sc0 sc1\n\ts_nop 1" :: "v"(gp_), "v"(v) : "memory"); }
;         float s = 0.f;
; #pragma unroll
;         for (int j = 0; j < 4; ++j) { const float a = __uint_as_float(v[j] << 16), b = __uint_as_float(v[j] & 0xffff0000u); s += a * a + b * b; }
;         s += __shfl_xor(s, 1); s += __shfl_xor(s, 2); s += __shfl_xor(s, 4);
;         if (ch == 0) atomicAdd(ss + (long)row * 4, s); }
;     ...
;     if (hi == 0) wsf[32 + r32] = l_reg; asm volatile("s_waitcnt lgkmcnt(0)" ::: "memory");
;     float rli[16];
; #pragma unroll
;     for (int r = 0; r < 16; ++r) rli[r] = __builtin_amdgcn_rcpf(wsf[32 + crow(r, hi)]);
;     at::store_tile(o, rli, (bf16_t*)(shm + LDS_OST) + wid * 2048, O + (long)(wid * QBLK) * OPITCH, OPITCH, ss + (long)(wid * QBLK) * 4, lane, r32, hi);
.LBB0_544:
	s_or_b64 exec, exec, s[14:15]
	s_and_b64 s[4:5], s[6:7], exec
	s_cselect_b32 s6, 0, 8
	s_cselect_b32 s7, 0, 0x500
	s_lshl_b64 s[4:5], s[8:9], 11
	s_waitcnt lgkmcnt(0)
	s_waitcnt lgkmcnt(0)
	v_add_u32_e32 v0, s18, v98
	s_add_u32 s4, s12, s4
	ds_read_b128 v[6:9], v0 offset:32896
	ds_read_b128 v[10:13], v0 offset:32928
	s_addc_u32 s5, s13, s5
	s_add_u32 s7, s4, s7
	s_addc_u32 s12, s5, 0
	s_lshl_b64 s[4:5], s[8:9], 4
	s_add_u32 s4, s10, s4
	s_addc_u32 s5, s11, s5
	s_lshl_b32 s1, s1, 1
	s_waitcnt lgkmcnt(1)
	v_rcp_f32_e32 v2, v6
	v_rcp_f32_e32 v3, v7
	v_rcp_f32_e32 v5, v8
	v_rcp_f32_e32 v14, v9
	s_waitcnt lgkmcnt(0)
	v_rcp_f32_e32 v15, v10
	ds_read_b128 v[6:9], v0 offset:32960
	v_rcp_f32_e32 v50, v11
	v_rcp_f32_e32 v51, v12
	v_rcp_f32_e32 v52, v13
	ds_read_b128 v[10:13], v0 offset:32992
	s_add_u32 s7, s7, s1
	s_addc_u32 s8, s12, 0
	s_add_u32 s9, s4, s6
	s_addc_u32 s10, s5, 0
	s_lshl_b32 s1, s3, 12
	s_waitcnt lgkmcnt(1)
	v_rcp_f32_e32 v0, v6
	v_rcp_f32_e32 v6, v7
	v_rcp_f32_e32 v7, v8
	v_rcp_f32_e32 v8, v9
	s_waitcnt lgkmcnt(0)
	v_rcp_f32_e32 v9, v10
	v_rcp_f32_e32 v10, v11
	v_rcp_f32_e32 v11, v12
	v_rcp_f32_e32 v12, v13
	s_add_i32 s3, s1, 0
	v_mul_f32_e32 v13, v34, v2
	v_lshlrev_b32_e32 v34, 1, v99
	v_lshlrev_b32_e32 v53, 1, v105
	v_mul_f32_e32 v2, v18, v2
	v_add3_u32 v34, s3, v34, v53
	v_cvt_pk_bf16_f32 v2, v2, s0
	ds_write_b16 v34, v2 offset:34880
	v_mul_f32_e32 v2, v35, v3
	v_cvt_pk_bf16_f32 v2, v2, s0
	ds_write_b16 v34, v2 offset:34944
	v_mul_f32_e32 v2, v19, v3
	v_cvt_pk_bf16_f32 v2, v2, s0
	ds_write_b16 v34, v2 offset:35008
	v_mul_f32_e32 v2, v36, v5
	v_cvt_pk_bf16_f32 v2, v2, s0
	ds_write_b16 v34, v2 offset:35072
	v_mul_f32_e32 v2, v20, v5
	v_cvt_pk_bf16_f32 v2, v2, s0
	ds_write_b16 v34, v2 offset:35136
	v_mul_f32_e32 v2, v37, v14
	v_cvt_pk_bf16_f32 v2, v2, s0
	ds_write_b16 v34, v2 offset:35200
	v_mul_f32_e32 v2, v21, v14
	v_cvt_pk_bf16_f32 v2, v2, s0
	ds_write_b16 v34, v2 offset:35264
	v_mul_f32_e32 v2, v38, v15
	v_cvt_pk_bf16_f32 v2, v2, s0
	ds_write_b16 v34, v2 offset:35840
	v_mul_f32_e32 v2, v22, v15
	v_cvt_pk_bf16_f32 v2, v2, s0
	ds_write_b16 v34, v2 offset:35904
	v_mul_f32_e32 v2, v39, v50
	v_cvt_pk_bf16_f32 v2, v2, s0
	ds_write_b16 v34, v2 offset:35968
	v_mul_f32_e32 v2, v23, v50
	v_cvt_pk_bf16_f32 v2, v2, s0
	ds_write_b16 v34, v2 offset:36032
	v_mul_f32_e32 v2, v40, v51
	v_cvt_pk_bf16_f32 v2, v2, s0
	ds_write_b16 v34, v2 offset:36096
	v_mul_f32_e32 v2, v24, v51
	v_cvt_pk_bf16_f32 v2, v2, s0
	ds_write_b16 v34, v2 offset:36160
	v_mul_f32_e32 v2, v41, v52
	v_cvt_pk_bf16_f32 v2, v2, s0
	ds_write_b16 v34, v2 offset:36224
	v_mul_f32_e32 v2, v25, v52
	v_cvt_pk_bf16_f32 v2, v2, s0
	ds_write_b16 v34, v2 offset:36288
	v_mul_f32_e32 v2, v42, v0
	v_mul_f32_e32 v0, v26, v0
	v_cvt_pk_bf16_f32 v0, v0, s0
	ds_write_b16 v34, v0 offset:36928
	v_mul_f32_e32 v0, v43, v6
	v_cvt_pk_bf16_f32 v0, v0, s0
	ds_write_b16 v34, v0 offset:36992
	v_mul_f32_e32 v0, v27, v6
	v_cvt_pk_bf16_f32 v0, v0, s0
	ds_write_b16 v34, v0 offset:37056
	v_mul_f32_e32 v0, v44, v7
	v_cvt_pk_bf16_f32 v0, v0, s0
	ds_write_b16 v34, v0 offset:37120
	v_mul_f32_e32 v0, v28, v7
	v_cvt_pk_bf16_f32 v0, v0, s0
	ds_write_b16 v34, v0 offset:37184
	v_mul_f32_e32 v0, v45, v8
	v_cvt_pk_bf16_f32 v0, v0, s0
	ds_write_b16 v34, v0 offset:37248
	v_mul_f32_e32 v0, v29, v8
	v_cvt_pk_bf16_f32 v0, v0, s0
	ds_write_b16 v34, v0 offset:37312
	v_mul_f32_e32 v0, v46, v9
	v_cvt_pk_bf16_f32 v0, v0, s0
	ds_write_b16 v34, v0 offset:37888
	v_mul_f32_e32 v0, v30, v9
	v_cvt_pk_bf16_f32 v0, v0, s0
	ds_write_b16 v34, v0 offset:37952
	v_mul_f32_e32 v0, v47, v10
	v_cvt_pk_bf16_f32 v0, v0, s0
	ds_write_b16 v34, v0 offset:38016
	v_mul_f32_e32 v0, v31, v10
	v_cvt_pk_bf16_f32 v0, v0, s0
	ds_write_b16 v34, v0 offset:38080
	v_mul_f32_e32 v0, v48, v11
	v_cvt_pk_bf16_f32 v0, v0, s0
	ds_write_b16 v34, v0 offset:38144
	v_mul_f32_e32 v0, v32, v11
	v_cvt_pk_bf16_f32 v0, v0, s0
	ds_write_b16 v34, v0 offset:38208
	v_mul_f32_e32 v0, v49, v12
	v_cvt_pk_bf16_f32 v0, v0, s0
	ds_write_b16 v34, v0 offset:38272
	v_mul_f32_e32 v0, v33, v12
	v_cvt_pk_bf16_f32 v0, v0, s0
	v_and_b32_e32 v9, 7, v17
	v_cvt_pk_bf16_f32 v13, v13, s0
	v_cvt_pk_bf16_f32 v2, v2, s0
	ds_write_b16 v34, v0 offset:38336
	v_lshlrev_b32_e32 v0, 4, v9
	ds_write_b16 v34, v13 offset:34816
	ds_write_b16 v34, v2 offset:36864
	v_lshrrev_b32_e32 v7, 3, v104
	v_add_u32_e32 v8, s3, v0
	s_waitcnt lgkmcnt(0)
	v_lshl_add_u32 v2, v7, 7, v8
	ds_read_b128 v[12:15], v2 offset:34816
	s_ashr_i32 s1, s0, 31
	s_lshl_b64 s[4:5], s[0:1], 11
	s_add_u32 s6, s7, s4
	s_addc_u32 s7, s8, s5
	s_waitcnt lgkmcnt(0)
	v_and_b32_e32 v3, 0xffff0000, v12
	v_lshlrev_b32_e32 v2, 16, v12
	v_mul_f32_e32 v3, v3, v3
	v_and_b32_e32 v5, 0xffff0000, v13
	v_fmac_f32_e32 v3, v2, v2
	v_lshlrev_b32_e32 v2, 16, v13
	v_mul_f32_e32 v5, v5, v5
	v_fmac_f32_e32 v5, v2, v2
	v_add_f32_e32 v2, v3, v5
	v_and_b32_e32 v5, 0xffff0000, v14
	v_lshlrev_b32_e32 v3, 16, v14
	v_mul_f32_e32 v5, v5, v5
	v_fmac_f32_e32 v5, v3, v3
	v_add_f32_e32 v2, v5, v2
	v_and_b32_e32 v5, 0xffff0000, v15
	v_lshlrev_b32_e32 v3, 16, v15
	v_mul_f32_e32 v5, v5, v5
	v_fmac_f32_e32 v5, v3, v3
	v_add_f32_e32 v6, v5, v2
	v_xor_b32_e32 v2, 1, v220
	v_cmp_lt_i32_e32 vcc, v2, v4
	s_lshl_b64 s[0:1], s[0:1], 4
	s_add_u32 s0, s9, s0
	v_cndmask_b32_e32 v2, v220, v2, vcc
	v_lshlrev_b32_e32 v5, 2, v2
	s_nop 1
	v_mov_b32_dpp v10, v6 quad_perm:[1,0,3,2] row_mask:0xf bank_mask:0xf
	v_lshl_add_u64 v[2:3], s[6:7], 0, v[0:1]
	v_xor_b32_e32 v0, 2, v220
	v_cmp_lt_i32_e32 vcc, v0, v4
	s_addc_u32 s1, s10, s1
	s_add_u32 s4, s0, 0x200000
	v_cndmask_b32_e32 v0, v220, v0, vcc
	s_waitcnt lgkmcnt(0)
	v_add_f32_e32 v10, v6, v10
	v_lshlrev_b32_e32 v6, 2, v0
	s_addc_u32 s5, s1, 0
	s_nop 1
	v_mov_b32_dpp v11, v10 quad_perm:[2,3,0,1] row_mask:0xf bank_mask:0xf
	s_mov_b64 s[0:1], 0x12e40000
	v_lshl_add_u64 v[2:3], v[2:3], 0, s[0:1]
	v_lshlrev_b32_e32 v0, 11, v7
	v_lshl_add_u64 v[18:19], v[2:3], 0, v[0:1]
	v_xor_b32_e32 v0, 4, v220
	v_cmp_lt_i32_e64 s[0:1], v0, v4
	v_cmp_eq_u32_e32 vcc, 0, v9
	s_waitcnt lgkmcnt(0)
	v_add_f32_e32 v9, v10, v11
	v_cndmask_b32_e64 v0, v220, v0, s[0:1]
	v_lshlrev_b32_e32 v4, 2, v0
	s_nop 1
	v_mov_b32_dpp v10, v9 row_half_mirror row_mask:0xf bank_mask:0xf
	global_store_dwordx4 v[18:19], v[12:15], off sc0 sc1
	s_nop 1
	s_and_saveexec_b64 s[0:1], vcc
	s_cbranch_execz .LBB0_546
	v_lshlrev_b32_e32 v0, 4, v7
	v_lshl_add_u64 v[12:13], s[4:5], 0, v[0:1]
	s_waitcnt lgkmcnt(0)
	v_add_f32_e32 v0, v9, v10
	flat_atomic_add_f32 v[12:13], v0
; __device__ __forceinline__ void store_tile(const f32x16* o, const float* rli, bf16_t* stg, bf16_t* Ow, int pitch, float* ss, int lane, int r32, int hi) {
;     ...
;     for (int i = 0; i < 4; ++i) { const int row = i * 8 + (lane >> 3), ch = lane & 7; const u32x4 v = *(const u32x4*)(stg + row * 64 + ch * 8);
;         { const bf16_t* gp_ = Ow + (long)row * pitch + ch * 8; asm volatile("global_store_dwordx4 %0, %1, off sc0 sc1\n\ts_nop 1" :: "v"(gp_), "v"(v) : "memory"); }
;         float s = 0.f;
; #pragma unroll
;         for (int j = 0; j < 4; ++j) { const float a = __uint_as_float(v[j] << 16), b = __uint_as_float(v[j] & 0xffff0000u); s += a * a + b * b; }
;         s += __shfl_xor(s, 1); s += __shfl_xor(s, 2); s += __shfl_xor(s, 4);
;         if (ch == 0) atomicAdd(ss + (long)row * 4, s); }
.LBB0_546:
	s_or_b64 exec, exec, s[0:1]
	v_or_b32_e32 v9, 8, v7
	v_lshl_add_u32 v0, v9, 7, v8
	s_waitcnt lgkmcnt(0)
	ds_read_b128 v[10:13], v0 offset:34816
	v_lshlrev_b32_e32 v0, 11, v9
	v_lshl_add_u64 v[14:15], v[2:3], 0, v[0:1]
	s_waitcnt lgkmcnt(0)
	global_store_dwordx4 v[14:15], v[10:13], off sc0 sc1
	s_nop 1
	v_lshlrev_b32_e32 v0, 16, v10
	v_and_b32_e32 v10, 0xffff0000, v10
	v_mul_f32_e32 v10, v10, v10
	v_fmac_f32_e32 v10, v0, v0
	v_lshlrev_b32_e32 v0, 16, v11
	v_and_b32_e32 v11, 0xffff0000, v11
	v_mul_f32_e32 v11, v11, v11
	v_fmac_f32_e32 v11, v0, v0
	v_add_f32_e32 v0, v10, v11
	v_and_b32_e32 v11, 0xffff0000, v12
	v_lshlrev_b32_e32 v10, 16, v12
	v_mul_f32_e32 v11, v11, v11
	v_fmac_f32_e32 v11, v10, v10
	v_add_f32_e32 v0, v11, v0
	v_and_b32_e32 v11, 0xffff0000, v13
	v_lshlrev_b32_e32 v10, 16, v13
	v_mul_f32_e32 v11, v11, v11
	v_fmac_f32_e32 v11, v10, v10
	v_add_f32_e32 v0, v11, v0
	s_nop 1
	v_mov_b32_dpp v10, v0 quad_perm:[1,0,3,2] row_mask:0xf bank_mask:0xf
	s_waitcnt lgkmcnt(0)
	v_add_f32_e32 v0, v0, v10
	s_nop 1
	v_mov_b32_dpp v10, v0 quad_perm:[2,3,0,1] row_mask:0xf bank_mask:0xf
	s_waitcnt lgkmcnt(0)
	v_add_f32_e32 v10, v0, v10
	s_nop 1
	v_mov_b32_dpp v11, v10 row_half_mirror row_mask:0xf bank_mask:0xf
	s_and_saveexec_b64 s[0:1], vcc
	s_cbranch_execz .LBB0_548
	v_lshlrev_b32_e32 v0, 4, v9
	v_lshl_add_u64 v[12:13], s[4:5], 0, v[0:1]
	s_waitcnt lgkmcnt(0)
	v_add_f32_e32 v0, v10, v11
	flat_atomic_add_f32 v[12:13], v0
.LBB0_548:
	s_or_b64 exec, exec, s[0:1]
	v_or_b32_e32 v9, 16, v7
	v_lshl_add_u32 v0, v9, 7, v8
	s_waitcnt lgkmcnt(0)
	ds_read_b128 v[10:13], v0 offset:34816
	v_lshlrev_b32_e32 v0, 11, v9
	v_lshl_add_u64 v[14:15], v[2:3], 0, v[0:1]
	s_waitcnt lgkmcnt(0)
	global_store_dwordx4 v[14:15], v[10:13], off sc0 sc1
	s_nop 1
	v_lshlrev_b32_e32 v0, 16, v10
	v_and_b32_e32 v10, 0xffff0000, v10
	v_mul_f32_e32 v10, v10, v10
	v_fmac_f32_e32 v10, v0, v0
	v_lshlrev_b32_e32 v0, 16, v11
	v_and_b32_e32 v11, 0xffff0000, v11
	v_mul_f32_e32 v11, v11, v11
	v_fmac_f32_e32 v11, v0, v0
	v_add_f32_e32 v0, v10, v11
	v_and_b32_e32 v11, 0xffff0000, v12
	v_lshlrev_b32_e32 v10, 16, v12
	v_mul_f32_e32 v11, v11, v11
	v_fmac_f32_e32 v11, v10, v10
	v_add_f32_e32 v0, v11, v0
	v_and_b32_e32 v11, 0xffff0000, v13
	v_lshlrev_b32_e32 v10, 16, v13
	v_mul_f32_e32 v11, v11, v11
	v_fmac_f32_e32 v11, v10, v10
	v_add_f32_e32 v0, v11, v0
	s_nop 1
	v_mov_b32_dpp v10, v0 quad_perm:[1,0,3,2] row_mask:0xf bank_mask:0xf
	s_waitcnt lgkmcnt(0)
	v_add_f32_e32 v0, v0, v10
	s_nop 1
	v_mov_b32_dpp v10, v0 quad_perm:[2,3,0,1] row_mask:0xf bank_mask:0xf
	s_waitcnt lgkmcnt(0)
	v_add_f32_e32 v10, v0, v10
	s_nop 1
	v_mov_b32_dpp v11, v10 row_half_mirror row_mask:0xf bank_mask:0xf
	s_and_saveexec_b64 s[0:1], vcc
	s_cbranch_execz .LBB0_550
	v_lshlrev_b32_e32 v0, 4, v9
	v_lshl_add_u64 v[12:13], s[4:5], 0, v[0:1]
	s_waitcnt lgkmcnt(0)
	v_add_f32_e32 v0, v10, v11
	flat_atomic_add_f32 v[12:13], v0
.LBB0_550:
	s_or_b64 exec, exec, s[0:1]
	v_or_b32_e32 v7, 24, v7
	v_lshl_add_u32 v0, v7, 7, v8
	s_waitcnt lgkmcnt(0)
	ds_read_b128 v[8:11], v0 offset:34816
	v_lshlrev_b32_e32 v0, 11, v7
	v_lshl_add_u64 v[2:3], v[2:3], 0, v[0:1]
	s_waitcnt lgkmcnt(0)
	global_store_dwordx4 v[2:3], v[8:11], off sc0 sc1
	s_nop 1
	v_and_b32_e32 v2, 0xffff0000, v8
	v_lshlrev_b32_e32 v0, 16, v8
	v_mul_f32_e32 v2, v2, v2
	v_and_b32_e32 v3, 0xffff0000, v9
	v_fmac_f32_e32 v2, v0, v0
	v_lshlrev_b32_e32 v0, 16, v9
	v_mul_f32_e32 v3, v3, v3
	v_fmac_f32_e32 v3, v0, v0
	v_add_f32_e32 v0, v2, v3
	v_and_b32_e32 v3, 0xffff0000, v10
	v_lshlrev_b32_e32 v2, 16, v10
	v_mul_f32_e32 v3, v3, v3
	v_fmac_f32_e32 v3, v2, v2
	v_add_f32_e32 v0, v3, v0
	v_and_b32_e32 v3, 0xffff0000, v11
	v_lshlrev_b32_e32 v2, 16, v11
	v_mul_f32_e32 v3, v3, v3
	v_fmac_f32_e32 v3, v2, v2
	v_add_f32_e32 v0, v3, v0
	s_nop 1
	v_mov_b32_dpp v2, v0 quad_perm:[1,0,3,2] row_mask:0xf bank_mask:0xf
	s_waitcnt lgkmcnt(0)
	v_add_f32_e32 v0, v0, v2
	s_nop 1
	v_mov_b32_dpp v2, v0 quad_perm:[2,3,0,1] row_mask:0xf bank_mask:0xf
	s_waitcnt lgkmcnt(0)
	v_add_f32_e32 v2, v0, v2
	s_nop 1
	v_mov_b32_dpp v3, v2 row_half_mirror row_mask:0xf bank_mask:0xf
	s_and_saveexec_b64 s[0:1], vcc
	s_cbranch_execz .LBB0_552
	v_lshlrev_b32_e32 v0, 4, v7
	v_lshl_add_u64 v[4:5], s[4:5], 0, v[0:1]
	s_waitcnt lgkmcnt(0)
	v_add_f32_e32 v0, v2, v3
	flat_atomic_add_f32 v[4:5], v0

; __device__ __forceinline__ int opaque_tid() { int t; asm volatile("v_mov_b32 %0, %1" : "=v"(t) : "v"((int)threadIdx.x)); return t; }
; #define ws (opq(P.ws))
; __device__ __forceinline__ void sg_unit(const Params& P, int l, int chunk, char* shm, float* ssb) {
;     const int tid_ = opaque_tid(), lane = tid_ & 63, wid = __builtin_amdgcn_readfirstlane(tid_ >> 6);
;     unsigned char* ws = P.ws;
;     const bf16_t* qkv = (const bf16_t*)(ws + WS_QKV); bf16_t* omix = (bf16_t*)(ws + WS_OMIX);
;     const bf16_t* Wsb = (const bf16_t*)(ws + WS_WS) + (size_t)l * 4 * 128 * 128;
;     const int R0 = chunk * 128;
;     bf16_t* vt = (bf16_t*)(shm + SG_VT);
;     const float* gs = P.g_sgu + l * 256;
;     const f32x4 g4 = *(const f32x4*)(gs + 4 * lane);
;     for (int q = wid * 16; q < wid * 16 + 16; ++q) {
;         const u32x2 vv = *(const u32x2*)(qkv + (size_t)(R0 + q) * DIN + C_V + 4 * lane);
;         f32x4 v; v[0] = __uint_as_float(vv.x << 16); v[1] = __uint_as_float(vv.x & 0xffff0000u); v[2] = __uint_as_float(vv.y << 16); v[3] = __uint_as_float(vv.y & 0xffff0000u);
; __global__ void __launch_bounds__(NTHREADS, 2) mega_fwd(Params P) {
;     ...
;                 } else if (idx < n_gqa + n_na + n_sg) {
;                     const int ch = idx - n_gqa - n_na;
;                     if (!(lastl && (ch % 66) >= 64)) { sg_unit(P, l, ch, (char*)lds, ssb); publish_cnt(cw + (ch >> 1) * 16); }
.LBB0_556:
	s_andn2_b64 vcc, exec, s[0:1]
	s_cbranch_vccnz .LBB0_579
	s_add_i32 s3, s48, 0xfffffd00
	s_add_i32 s0, s48, 0xfffffcbe
	s_cmpk_lt_u32 s3, 0x42
	s_cselect_b32 s0, s3, s0
	s_cmp_lt_u32 s0, 64
	v_readlane_b32 s4, v252, 11
	s_cselect_b64 s[0:1], -1, 0
	v_readlane_b32 s5, v252, 12
	s_or_b64 s[0:1], s[4:5], s[0:1]
	s_andn2_b64 vcc, exec, s[0:1]
	s_cbranch_vccnz .LBB0_579
	s_mov_b64 s[4:5], s[76:77]
	v_mov_b32 v12, v214
	v_readlane_b32 s0, v252, 18
	v_and_b32_e32 v13, 63, v12
	v_lshlrev_b32_e32 v0, 4, v13
	v_readlane_b32 s1, v252, 19
	v_xor_b32_e32 v6, 1, v220
	v_readfirstlane_b32 s6, v12
	s_ashr_i32 s2, s6, 6
	v_readlane_b32 s8, v254, 36
	s_mov_b32 s7, 0
	global_load_dwordx4 v[2:5], v0, s[0:1]
	v_and_b32_e32 v0, 64, v220
	v_add_u32_e32 v0, 64, v0
	v_cmp_lt_i32_e32 vcc, v6, v0
	s_lshl_b32 s1, s2, 5
	s_add_i32 s1, s1, 0
	v_cndmask_b32_e32 v6, v220, v6, vcc
	v_lshlrev_b32_e32 v17, 2, v6
	v_xor_b32_e32 v6, 2, v220
	v_cmp_lt_i32_e32 vcc, v6, v0
	s_lshl_b32 s0, s2, 4
	s_nop 0
	v_cndmask_b32_e32 v6, v220, v6, vcc
	v_lshlrev_b32_e32 v83, 2, v6
	v_xor_b32_e32 v6, 4, v220
	v_cmp_lt_i32_e32 vcc, v6, v0
	s_nop 1
	v_cndmask_b32_e32 v6, v220, v6, vcc
	v_lshlrev_b32_e32 v82, 2, v6
	v_xor_b32_e32 v6, 8, v220
	v_cmp_lt_i32_e32 vcc, v6, v0
	s_nop 1
	v_cndmask_b32_e32 v6, v220, v6, vcc
	v_lshlrev_b32_e32 v14, 2, v6
	v_xor_b32_e32 v6, 16, v220
	v_cmp_lt_i32_e32 vcc, v6, v0
	s_nop 1
	v_cndmask_b32_e32 v6, v220, v6, vcc
	v_lshlrev_b32_e32 v15, 2, v6
	v_xor_b32_e32 v6, 32, v220
	v_cmp_lt_i32_e32 vcc, v6, v0
	s_nop 1
	v_cndmask_b32_e32 v0, v220, v6, vcc
	v_lshlrev_b32_e32 v18, 2, v0
	v_mov_b32_e32 v0, s1
	s_movk_i32 s1, 0x440
	v_mad_u32_u24 v19, v13, s1, v0
	s_lshl_b32 s1, s48, 7
	s_add_i32 s0, s1, s0
	s_add_i32 s0, s0, 0xfffe8000
	s_mul_hi_i32 s1, s0, 0x1200
	s_mulk_i32 s0, 0x1200
	s_add_u32 s0, s8, s0
	v_readlane_b32 s8, v254, 37
	v_lshlrev_b32_e32 v0, 3, v13
	s_addc_u32 s1, s8, s1
	v_lshl_add_u64 v[6:7], s[0:1], 0, v[0:1]
	s_mov_b64 s[8:9], 0x1200
	global_load_dwordx2 v[96:97], v[6:7], off
	v_lshl_add_u64 v[6:7], v[6:7], 0, s[8:9]
	global_load_dwordx2 v[98:99], v[6:7], off
	v_lshl_add_u64 v[6:7], v[6:7], 0, s[8:9]
	global_load_dwordx2 v[100:101], v[6:7], off
	v_lshl_add_u64 v[6:7], v[6:7], 0, s[8:9]
	global_load_dwordx2 v[102:103], v[6:7], off
	v_lshl_add_u64 v[6:7], v[6:7], 0, s[8:9]
	global_load_dwordx2 v[104:105], v[6:7], off
	v_lshl_add_u64 v[6:7], v[6:7], 0, s[8:9]
	global_load_dwordx2 v[106:107], v[6:7], off
	v_lshl_add_u64 v[6:7], v[6:7], 0, s[8:9]
	global_load_dwordx2 v[108:109], v[6:7], off
	v_lshl_add_u64 v[6:7], v[6:7], 0, s[8:9]
	global_load_dwordx2 v[110:111], v[6:7], off
	v_lshl_add_u64 v[6:7], v[6:7], 0, s[8:9]
	global_load_dwordx2 v[112:113], v[6:7], off
	v_lshl_add_u64 v[6:7], v[6:7], 0, s[8:9]
	global_load_dwordx2 v[114:115], v[6:7], off
	v_lshl_add_u64 v[6:7], v[6:7], 0, s[8:9]
	global_load_dwordx2 v[116:117], v[6:7], off
	v_lshl_add_u64 v[6:7], v[6:7], 0, s[8:9]
	global_load_dwordx2 v[118:119], v[6:7], off
	v_lshl_add_u64 v[6:7], v[6:7], 0, s[8:9]
	global_load_dwordx2 v[120:121], v[6:7], off
	v_lshl_add_u64 v[6:7], v[6:7], 0, s[8:9]
	global_load_dwordx2 v[122:123], v[6:7], off
	v_lshl_add_u64 v[6:7], v[6:7], 0, s[8:9]
	global_load_dwordx2 v[124:125], v[6:7], off
	v_lshl_add_u64 v[6:7], v[6:7], 0, s[8:9]
	global_load_dwordx2 v[126:127], v[6:7], off
	s_waitcnt vmcnt(0)
	v_lshlrev_b32_e32 v130, 16, v97
	v_lshlrev_b32_e32 v128, 16, v96
	v_and_b32_e32 v131, 0xffff0000, v97
	v_and_b32_e32 v129, 0xffff0000, v96
	v_lshlrev_b32_e32 v134, 16, v99
	v_lshlrev_b32_e32 v132, 16, v98
	v_and_b32_e32 v135, 0xffff0000, v99
	v_and_b32_e32 v133, 0xffff0000, v98
	v_lshlrev_b32_e32 v138, 16, v101
	v_lshlrev_b32_e32 v136, 16, v100
	v_and_b32_e32 v139, 0xffff0000, v101
	v_and_b32_e32 v137, 0xffff0000, v100
	v_lshlrev_b32_e32 v142, 16, v103
	v_lshlrev_b32_e32 v140, 16, v102
	v_and_b32_e32 v143, 0xffff0000, v103
	v_and_b32_e32 v141, 0xffff0000, v102
	v_lshlrev_b32_e32 v146, 16, v105
	v_lshlrev_b32_e32 v144, 16, v104
	v_and_b32_e32 v147, 0xffff0000, v105
	v_and_b32_e32 v145, 0xffff0000, v104
	v_lshlrev_b32_e32 v150, 16, v107
	v_lshlrev_b32_e32 v148, 16, v106
	v_and_b32_e32 v151, 0xffff0000, v107
	v_and_b32_e32 v149, 0xffff0000, v106
	v_lshlrev_b32_e32 v154, 16, v109
	v_lshlrev_b32_e32 v152, 16, v108
	v_and_b32_e32 v155, 0xffff0000, v109
	v_and_b32_e32 v153, 0xffff0000, v108
	v_lshlrev_b32_e32 v158, 16, v111
	v_lshlrev_b32_e32 v156, 16, v110
	v_and_b32_e32 v159, 0xffff0000, v111
	v_and_b32_e32 v157, 0xffff0000, v110
	v_lshlrev_b32_e32 v162, 16, v113
	v_lshlrev_b32_e32 v160, 16, v112
	v_and_b32_e32 v163, 0xffff0000, v113
	v_and_b32_e32 v161, 0xffff0000, v112
	v_lshlrev_b32_e32 v166, 16, v115
	v_lshlrev_b32_e32 v164, 16, v114
	v_and_b32_e32 v167, 0xffff0000, v115
	v_and_b32_e32 v165, 0xffff0000, v114
	v_lshlrev_b32_e32 v170, 16, v117
	v_lshlrev_b32_e32 v168, 16, v116
	v_and_b32_e32 v171, 0xffff0000, v117
	v_and_b32_e32 v169, 0xffff0000, v116
	v_lshlrev_b32_e32 v174, 16, v119
	v_lshlrev_b32_e32 v172, 16, v118
	v_and_b32_e32 v175, 0xffff0000, v119
	v_and_b32_e32 v173, 0xffff0000, v118
	v_lshlrev_b32_e32 v178, 16, v121
	v_lshlrev_b32_e32 v176, 16, v120
	v_and_b32_e32 v179, 0xffff0000, v121
	v_and_b32_e32 v177, 0xffff0000, v120
	v_lshlrev_b32_e32 v182, 16, v123
	v_lshlrev_b32_e32 v180, 16, v122
	v_and_b32_e32 v183, 0xffff0000, v123
	v_and_b32_e32 v181, 0xffff0000, v122
	v_lshlrev_b32_e32 v186, 16, v125
	v_lshlrev_b32_e32 v184, 16, v124
	v_and_b32_e32 v187, 0xffff0000, v125
	v_and_b32_e32 v185, 0xffff0000, v124
	v_lshlrev_b32_e32 v190, 16, v127
	v_lshlrev_b32_e32 v188, 16, v126
	v_and_b32_e32 v191, 0xffff0000, v127
	v_and_b32_e32 v189, 0xffff0000, v126
; __device__ __forceinline__ float wave_sum(float v) {
; #pragma unroll
;     for (int o = 1; o < 64; o <<= 1) v += __shfl_xor(v, o);
;     return v;
; __device__ __forceinline__ void sg_unit(const Params& P, int l, int chunk, char* shm, float* ssb) {
;     ...
;     for (int q = wid * 16; q < wid * 16 + 16; ++q) {
;         const u32x2 vv = *(const u32x2*)(qkv + (size_t)(R0 + q) * DIN + C_V + 4 * lane);
;         f32x4 v; v[0] = __uint_as_float(vv.x << 16); v[1] = __uint_as_float(vv.x & 0xffff0000u); v[2] = __uint_as_float(vv.y << 16); v[3] = __uint_as_float(vv.y & 0xffff0000u);
;         const float mean = wave_sum((v[0] + v[1]) + (v[2] + v[3])) * (1.f / 256.f);
	v_add_f32_e32 v208, v128, v129
	v_add_f32_e32 v209, v130, v131
	v_add_f32_e32 v192, v208, v209
	v_add_f32_e32 v208, v132, v133
	v_add_f32_e32 v209, v134, v135
	v_add_f32_e32 v193, v208, v209
	v_add_f32_e32 v208, v136, v137
	v_add_f32_e32 v209, v138, v139
	v_add_f32_e32 v194, v208, v209
	v_add_f32_e32 v208, v140, v141
	v_add_f32_e32 v209, v142, v143
	v_add_f32_e32 v195, v208, v209
	v_add_f32_e32 v208, v144, v145
	v_add_f32_e32 v209, v146, v147
	v_add_f32_e32 v196, v208, v209
	v_add_f32_e32 v208, v148, v149
	v_add_f32_e32 v209, v150, v151
	v_add_f32_e32 v197, v208, v209
	v_add_f32_e32 v208, v152, v153
	v_add_f32_e32 v209, v154, v155
	v_add_f32_e32 v198, v208, v209
	v_add_f32_e32 v208, v156, v157
	v_add_f32_e32 v209, v158, v159
	v_add_f32_e32 v199, v208, v209
	v_add_f32_e32 v208, v160, v161
	v_add_f32_e32 v209, v162, v163
	v_add_f32_e32 v200, v208, v209
	v_add_f32_e32 v208, v164, v165
	v_add_f32_e32 v209, v166, v167
	v_add_f32_e32 v201, v208, v209
	v_add_f32_e32 v208, v168, v169
	v_add_f32_e32 v209, v170, v171
	v_add_f32_e32 v202, v208, v209
	v_add_f32_e32 v208, v172, v173
	v_add_f32_e32 v209, v174, v175
	v_add_f32_e32 v203, v208, v209
	v_add_f32_e32 v208, v176, v177
	v_add_f32_e32 v209, v178, v179
	v_add_f32_e32 v204, v208, v209
	v_add_f32_e32 v208, v180, v181
	v_add_f32_e32 v209, v182, v183
	v_add_f32_e32 v205, v208, v209
	v_add_f32_e32 v208, v184, v185
	v_add_f32_e32 v209, v186, v187
	v_add_f32_e32 v206, v208, v209
	v_add_f32_e32 v208, v188, v189
	v_add_f32_e32 v209, v190, v191
	v_add_f32_e32 v207, v208, v209
	v_mov_b32_dpp v96, v192 quad_perm:[1,0,3,2] row_mask:0xf bank_mask:0xf
	v_mov_b32_dpp v97, v193 quad_perm:[1,0,3,2] row_mask:0xf bank_mask:0xf
	v_mov_b32_dpp v98, v194 quad_perm:[1,0,3,2] row_mask:0xf bank_mask:0xf
	v_mov_b32_dpp v99, v195 quad_perm:[1,0,3,2] row_mask:0xf bank_mask:0xf
	v_mov_b32_dpp v100, v196 quad_perm:[1,0,3,2] row_mask:0xf bank_mask:0xf
	v_mov_b32_dpp v101, v197 quad_perm:[1,0,3,2] row_mask:0xf bank_mask:0xf
	v_mov_b32_dpp v102, v198 quad_perm:[1,0,3,2] row_mask:0xf bank_mask:0xf
	v_mov_b32_dpp v103, v199 quad_perm:[1,0,3,2] row_mask:0xf bank_mask:0xf
	v_mov_b32_dpp v104, v200 quad_perm:[1,0,3,2] row_mask:0xf bank_mask:0xf
	v_mov_b32_dpp v105, v201 quad_perm:[1,0,3,2] row_mask:0xf bank_mask:0xf
	v_mov_b32_dpp v106, v202 quad_perm:[1,0,3,2] row_mask:0xf bank_mask:0xf
	v_mov_b32_dpp v107, v203 quad_perm:[1,0,3,2] row_mask:0xf bank_mask:0xf
	v_mov_b32_dpp v108, v204 quad_perm:[1,0,3,2] row_mask:0xf bank_mask:0xf
	v_mov_b32_dpp v109, v205 quad_perm:[1,0,3,2] row_mask:0xf bank_mask:0xf
	v_mov_b32_dpp v110, v206 quad_perm:[1,0,3,2] row_mask:0xf bank_mask:0xf
	v_mov_b32_dpp v111, v207 quad_perm:[1,0,3,2] row_mask:0xf bank_mask:0xf
	v_add_f32_e32 v192, v192, v96
	v_add_f32_e32 v193, v193, v97
	v_add_f32_e32 v194, v194, v98
	v_add_f32_e32 v195, v195, v99
	v_add_f32_e32 v196, v196, v100
	v_add_f32_e32 v197, v197, v101
	v_add_f32_e32 v198, v198, v102
	v_add_f32_e32 v199, v199, v103
	v_add_f32_e32 v200, v200, v104
	v_add_f32_e32 v201, v201, v105
	v_add_f32_e32 v202, v202, v106
	v_add_f32_e32 v203, v203, v107
	v_add_f32_e32 v204, v204, v108
	v_add_f32_e32 v205, v205, v109
	v_add_f32_e32 v206, v206, v110
	v_add_f32_e32 v207, v207, v111
	v_mov_b32_dpp v96, v192 quad_perm:[2,3,0,1] row_mask:0xf bank_mask:0xf
	v_mov_b32_dpp v97, v193 quad_perm:[2,3,0,1] row_mask:0xf bank_mask:0xf
	v_mov_b32_dpp v98, v194 quad_perm:[2,3,0,1] row_mask:0xf bank_mask:0xf
	v_mov_b32_dpp v99, v195 quad_perm:[2,3,0,1] row_mask:0xf bank_mask:0xf
	v_mov_b32_dpp v100, v196 quad_perm:[2,3,0,1] row_mask:0xf bank_mask:0xf
	v_mov_b32_dpp v101, v197 quad_perm:[2,3,0,1] row_mask:0xf bank_mask:0xf
	v_mov_b32_dpp v102, v198 quad_perm:[2,3,0,1] row_mask:0xf bank_mask:0xf
	v_mov_b32_dpp v103, v199 quad_perm:[2,3,0,1] row_mask:0xf bank_mask:0xf
	v_mov_b32_dpp v104, v200 quad_perm:[2,3,0,1] row_mask:0xf bank_mask:0xf
	v_mov_b32_dpp v105, v201 quad_perm:[2,3,0,1] row_mask:0xf bank_mask:0xf
	v_mov_b32_dpp v106, v202 quad_perm:[2,3,0,1] row_mask:0xf bank_mask:0xf
	v_mov_b32_dpp v107, v203 quad_perm:[2,3,0,1] row_mask:0xf bank_mask:0xf
	v_mov_b32_dpp v108, v204 quad_perm:[2,3,0,1] row_mask:0xf bank_mask:0xf
	v_mov_b32_dpp v109, v205 quad_perm:[2,3,0,1] row_mask:0xf bank_mask:0xf
	v_mov_b32_dpp v110, v206 quad_perm:[2,3,0,1] row_mask:0xf bank_mask:0xf
	v_mov_b32_dpp v111, v207 quad_perm:[2,3,0,1] row_mask:0xf bank_mask:0xf
	v_add_f32_e32 v192, v192, v96
	v_add_f32_e32 v193, v193, v97
	v_add_f32_e32 v194, v194, v98
	v_add_f32_e32 v195, v195, v99
	v_add_f32_e32 v196, v196, v100
	v_add_f32_e32 v197, v197, v101
	v_add_f32_e32 v198, v198, v102
	v_add_f32_e32 v199, v199, v103
	v_add_f32_e32 v200, v200, v104
	v_add_f32_e32 v201, v201, v105
	v_add_f32_e32 v202, v202, v106
	v_add_f32_e32 v203, v203, v107
	v_add_f32_e32 v204, v204, v108
	v_add_f32_e32 v205, v205, v109
	v_add_f32_e32 v206, v206, v110
	v_add_f32_e32 v207, v207, v111
	v_mov_b32_dpp v96, v192 row_half_mirror row_mask:0xf bank_mask:0xf
	v_mov_b32_dpp v97, v193 row_half_mirror row_mask:0xf bank_mask:0xf
	v_mov_b32_dpp v98, v194 row_half_mirror row_mask:0xf bank_mask:0xf
	v_mov_b32_dpp v99, v195 row_half_mirror row_mask:0xf bank_mask:0xf
	v_mov_b32_dpp v100, v196 row_half_mirror row_mask:0xf bank_mask:0xf
	v_mov_b32_dpp v101, v197 row_half_mirror row_mask:0xf bank_mask:0xf
	v_mov_b32_dpp v102, v198 row_half_mirror row_mask:0xf bank_mask:0xf
	v_mov_b32_dpp v103, v199 row_half_mirror row_mask:0xf bank_mask:0xf
	v_mov_b32_dpp v104, v200 row_half_mirror row_mask:0xf bank_mask:0xf
	v_mov_b32_dpp v105, v201 row_half_mirror row_mask:0xf bank_mask:0xf
	v_mov_b32_dpp v106, v202 row_half_mirror row_mask:0xf bank_mask:0xf
; __device__ __forceinline__ float wave_sum(float v) {
; #pragma unroll
;     for (int o = 1; o < 64; o <<= 1) v += __shfl_xor(v, o);
;     return v;
; __device__ __forceinline__ void sg_unit(const Params& P, int l, int chunk, char* shm, float* ssb) {
;     ...
;         const float mean = wave_sum((v[0] + v[1]) + (v[2] + v[3])) * (1.f / 256.f);
	v_mov_b32_dpp v107, v203 row_half_mirror row_mask:0xf bank_mask:0xf
	v_mov_b32_dpp v108, v204 row_half_mirror row_mask:0xf bank_mask:0xf
	v_mov_b32_dpp v109, v205 row_half_mirror row_mask:0xf bank_mask:0xf
	v_mov_b32_dpp v110, v206 row_half_mirror row_mask:0xf bank_mask:0xf
	v_mov_b32_dpp v111, v207 row_half_mirror row_mask:0xf bank_mask:0xf
	v_add_f32_e32 v192, v192, v96
	v_add_f32_e32 v193, v193, v97
	v_add_f32_e32 v194, v194, v98
	v_add_f32_e32 v195, v195, v99
	v_add_f32_e32 v196, v196, v100
	v_add_f32_e32 v197, v197, v101
	v_add_f32_e32 v198, v198, v102
	v_add_f32_e32 v199, v199, v103
	v_add_f32_e32 v200, v200, v104
	v_add_f32_e32 v201, v201, v105
	v_add_f32_e32 v202, v202, v106
	v_add_f32_e32 v203, v203, v107
	v_add_f32_e32 v204, v204, v108
	v_add_f32_e32 v205, v205, v109
	v_add_f32_e32 v206, v206, v110
	v_add_f32_e32 v207, v207, v111
	v_mov_b32_dpp v96, v192 row_mirror row_mask:0xf bank_mask:0xf
	v_mov_b32_dpp v97, v193 row_mirror row_mask:0xf bank_mask:0xf
	v_mov_b32_dpp v98, v194 row_mirror row_mask:0xf bank_mask:0xf
	v_mov_b32_dpp v99, v195 row_mirror row_mask:0xf bank_mask:0xf
	v_mov_b32_dpp v100, v196 row_mirror row_mask:0xf bank_mask:0xf
	v_mov_b32_dpp v101, v197 row_mirror row_mask:0xf bank_mask:0xf
	v_mov_b32_dpp v102, v198 row_mirror row_mask:0xf bank_mask:0xf
	v_mov_b32_dpp v103, v199 row_mirror row_mask:0xf bank_mask:0xf
	v_mov_b32_dpp v104, v200 row_mirror row_mask:0xf bank_mask:0xf
	v_mov_b32_dpp v105, v201 row_mirror row_mask:0xf bank_mask:0xf
	v_mov_b32_dpp v106, v202 row_mirror row_mask:0xf bank_mask:0xf
	v_mov_b32_dpp v107, v203 row_mirror row_mask:0xf bank_mask:0xf
	v_mov_b32_dpp v108, v204 row_mirror row_mask:0xf bank_mask:0xf
	v_mov_b32_dpp v109, v205 row_mirror row_mask:0xf bank_mask:0xf
	v_mov_b32_dpp v110, v206 row_mirror row_mask:0xf bank_mask:0xf
	v_mov_b32_dpp v111, v207 row_mirror row_mask:0xf bank_mask:0xf
	v_add_f32_e32 v192, v192, v96
	v_add_f32_e32 v193, v193, v97
	v_add_f32_e32 v194, v194, v98
	v_add_f32_e32 v195, v195, v99
	v_add_f32_e32 v196, v196, v100
	v_add_f32_e32 v197, v197, v101
	v_add_f32_e32 v198, v198, v102
	v_add_f32_e32 v199, v199, v103
	v_add_f32_e32 v200, v200, v104
	v_add_f32_e32 v201, v201, v105
	v_add_f32_e32 v202, v202, v106
	v_add_f32_e32 v203, v203, v107
	v_add_f32_e32 v204, v204, v108
	v_add_f32_e32 v205, v205, v109
	v_add_f32_e32 v206, v206, v110
	v_add_f32_e32 v207, v207, v111
	ds_bpermute_b32 v96, v15, v192
	ds_bpermute_b32 v97, v15, v193
	ds_bpermute_b32 v98, v15, v194
	ds_bpermute_b32 v99, v15, v195
	ds_bpermute_b32 v100, v15, v196
	ds_bpermute_b32 v101, v15, v197
	ds_bpermute_b32 v102, v15, v198
	ds_bpermute_b32 v103, v15, v199
	ds_bpermute_b32 v104, v15, v200
	ds_bpermute_b32 v105, v15, v201
	ds_bpermute_b32 v106, v15, v202
	ds_bpermute_b32 v107, v15, v203
	ds_bpermute_b32 v108, v15, v204
	ds_bpermute_b32 v109, v15, v205
	ds_bpermute_b32 v110, v15, v206
	ds_bpermute_b32 v111, v15, v207
	s_waitcnt lgkmcnt(8)
	v_add_f32_e32 v192, v192, v96
	v_add_f32_e32 v193, v193, v97
	v_add_f32_e32 v194, v194, v98
	v_add_f32_e32 v195, v195, v99
	v_add_f32_e32 v196, v196, v100
	v_add_f32_e32 v197, v197, v101
	v_add_f32_e32 v198, v198, v102
	v_add_f32_e32 v199, v199, v103
	s_waitcnt lgkmcnt(0)
	v_add_f32_e32 v200, v200, v104
	v_add_f32_e32 v201, v201, v105
	v_add_f32_e32 v202, v202, v106
	v_add_f32_e32 v203, v203, v107
	v_add_f32_e32 v204, v204, v108
	v_add_f32_e32 v205, v205, v109
	v_add_f32_e32 v206, v206, v110
	v_add_f32_e32 v207, v207, v111
	ds_bpermute_b32 v96, v18, v192
	ds_bpermute_b32 v97, v18, v193
	ds_bpermute_b32 v98, v18, v194
	ds_bpermute_b32 v99, v18, v195
	ds_bpermute_b32 v100, v18, v196
	ds_bpermute_b32 v101, v18, v197
	ds_bpermute_b32 v102, v18, v198
	ds_bpermute_b32 v103, v18, v199
	ds_bpermute_b32 v104, v18, v200
	ds_bpermute_b32 v105, v18, v201
	ds_bpermute_b32 v106, v18, v202
	ds_bpermute_b32 v107, v18, v203
	ds_bpermute_b32 v108, v18, v204
	ds_bpermute_b32 v109, v18, v205
	ds_bpermute_b32 v110, v18, v206
	ds_bpermute_b32 v111, v18, v207
	s_waitcnt lgkmcnt(8)
	v_add_f32_e32 v192, v192, v96
	v_add_f32_e32 v193, v193, v97
	v_add_f32_e32 v194, v194, v98
	v_add_f32_e32 v195, v195, v99
	v_add_f32_e32 v196, v196, v100
	v_add_f32_e32 v197, v197, v101
	v_add_f32_e32 v198, v198, v102
	v_add_f32_e32 v199, v199, v103
	s_waitcnt lgkmcnt(0)
; __device__ __forceinline__ void sg_unit(const Params& P, int l, int chunk, char* shm, float* ssb) {
;     ...
;         const float mean = wave_sum((v[0] + v[1]) + (v[2] + v[3])) * (1.f / 256.f);
;         v = v - mean; const f32x4 sq = v * v;
	v_add_f32_e32 v200, v200, v104
	v_add_f32_e32 v201, v201, v105
	v_add_f32_e32 v202, v202, v106
	v_add_f32_e32 v203, v203, v107
	v_add_f32_e32 v204, v204, v108
	v_add_f32_e32 v205, v205, v109
	v_add_f32_e32 v206, v206, v110
	v_add_f32_e32 v207, v207, v111
	v_fmac_f32_e32 v129, 0xbb800000, v192
	v_fmac_f32_e32 v131, 0xbb800000, v192
	v_fmac_f32_e32 v130, 0xbb800000, v192
	v_fmac_f32_e32 v128, 0xbb800000, v192
	v_fmac_f32_e32 v133, 0xbb800000, v193
	v_fmac_f32_e32 v135, 0xbb800000, v193
	v_fmac_f32_e32 v134, 0xbb800000, v193
	v_fmac_f32_e32 v132, 0xbb800000, v193
	v_fmac_f32_e32 v137, 0xbb800000, v194
	v_fmac_f32_e32 v139, 0xbb800000, v194
	v_fmac_f32_e32 v138, 0xbb800000, v194
	v_fmac_f32_e32 v136, 0xbb800000, v194
	v_fmac_f32_e32 v141, 0xbb800000, v195
	v_fmac_f32_e32 v143, 0xbb800000, v195
	v_fmac_f32_e32 v142, 0xbb800000, v195
	v_fmac_f32_e32 v140, 0xbb800000, v195
	v_fmac_f32_e32 v145, 0xbb800000, v196
	v_fmac_f32_e32 v147, 0xbb800000, v196
	v_fmac_f32_e32 v146, 0xbb800000, v196
	v_fmac_f32_e32 v144, 0xbb800000, v196
	v_fmac_f32_e32 v149, 0xbb800000, v197
	v_fmac_f32_e32 v151, 0xbb800000, v197
	v_fmac_f32_e32 v150, 0xbb800000, v197
	v_fmac_f32_e32 v148, 0xbb800000, v197
	v_fmac_f32_e32 v153, 0xbb800000, v198
	v_fmac_f32_e32 v155, 0xbb800000, v198
	v_fmac_f32_e32 v154, 0xbb800000, v198
	v_fmac_f32_e32 v152, 0xbb800000, v198
	v_fmac_f32_e32 v157, 0xbb800000, v199
	v_fmac_f32_e32 v159, 0xbb800000, v199
	v_fmac_f32_e32 v158, 0xbb800000, v199
	v_fmac_f32_e32 v156, 0xbb800000, v199
	v_fmac_f32_e32 v161, 0xbb800000, v200
	v_fmac_f32_e32 v163, 0xbb800000, v200
	v_fmac_f32_e32 v162, 0xbb800000, v200
	v_fmac_f32_e32 v160, 0xbb800000, v200
	v_fmac_f32_e32 v165, 0xbb800000, v201
	v_fmac_f32_e32 v167, 0xbb800000, v201
	v_fmac_f32_e32 v166, 0xbb800000, v201
	v_fmac_f32_e32 v164, 0xbb800000, v201
	v_fmac_f32_e32 v169, 0xbb800000, v202
	v_fmac_f32_e32 v171, 0xbb800000, v202
	v_fmac_f32_e32 v170, 0xbb800000, v202
	v_fmac_f32_e32 v168, 0xbb800000, v202
	v_fmac_f32_e32 v173, 0xbb800000, v203
	v_fmac_f32_e32 v175, 0xbb800000, v203
	v_fmac_f32_e32 v174, 0xbb800000, v203
	v_fmac_f32_e32 v172, 0xbb800000, v203
	v_fmac_f32_e32 v177, 0xbb800000, v204
	v_fmac_f32_e32 v179, 0xbb800000, v204
	v_fmac_f32_e32 v178, 0xbb800000, v204
	v_fmac_f32_e32 v176, 0xbb800000, v204
	v_fmac_f32_e32 v181, 0xbb800000, v205
	v_fmac_f32_e32 v183, 0xbb800000, v205
	v_fmac_f32_e32 v182, 0xbb800000, v205
	v_fmac_f32_e32 v180, 0xbb800000, v205
	v_fmac_f32_e32 v185, 0xbb800000, v206
	v_fmac_f32_e32 v187, 0xbb800000, v206
	v_fmac_f32_e32 v186, 0xbb800000, v206
	v_fmac_f32_e32 v184, 0xbb800000, v206
	v_fmac_f32_e32 v189, 0xbb800000, v207
	v_fmac_f32_e32 v191, 0xbb800000, v207
	v_fmac_f32_e32 v190, 0xbb800000, v207
	v_fmac_f32_e32 v188, 0xbb800000, v207
	v_mul_f32_e32 v208, v128, v128
	v_mul_f32_e32 v209, v129, v129
	v_mul_f32_e32 v210, v130, v130
	v_mul_f32_e32 v211, v131, v131
	v_add_f32_e32 v208, v209, v208
	v_add_f32_e32 v210, v210, v211
	v_add_f32_e32 v192, v208, v210
	v_mul_f32_e32 v208, v132, v132
	v_mul_f32_e32 v209, v133, v133
	v_mul_f32_e32 v210, v134, v134
	v_mul_f32_e32 v211, v135, v135
	v_add_f32_e32 v208, v209, v208
	v_add_f32_e32 v210, v210, v211
	v_add_f32_e32 v193, v208, v210
	v_mul_f32_e32 v208, v136, v136
	v_mul_f32_e32 v209, v137, v137
	v_mul_f32_e32 v210, v138, v138
	v_mul_f32_e32 v211, v139, v139
	v_add_f32_e32 v208, v209, v208
	v_add_f32_e32 v210, v210, v211
	v_add_f32_e32 v194, v208, v210
	v_mul_f32_e32 v208, v140, v140
	v_mul_f32_e32 v209, v141, v141
	v_mul_f32_e32 v210, v142, v142
	v_mul_f32_e32 v211, v143, v143
	v_add_f32_e32 v208, v209, v208
	v_add_f32_e32 v210, v210, v211
	v_add_f32_e32 v195, v208, v210
	v_mul_f32_e32 v208, v144, v144
	v_mul_f32_e32 v209, v145, v145
	v_mul_f32_e32 v210, v146, v146
	v_mul_f32_e32 v211, v147, v147
	v_add_f32_e32 v208, v209, v208
	v_add_f32_e32 v210, v210, v211
	v_add_f32_e32 v196, v208, v210
	v_mul_f32_e32 v208, v148, v148
	v_mul_f32_e32 v209, v149, v149
	v_mul_f32_e32 v210, v150, v150
	v_mul_f32_e32 v211, v151, v151
	v_add_f32_e32 v208, v209, v208
	v_add_f32_e32 v210, v210, v211
	v_add_f32_e32 v197, v208, v210
	v_mul_f32_e32 v208, v152, v152
	v_mul_f32_e32 v209, v153, v153
	v_mul_f32_e32 v210, v154, v154
	v_mul_f32_e32 v211, v155, v155
	v_add_f32_e32 v208, v209, v208
	v_add_f32_e32 v210, v210, v211
	v_add_f32_e32 v198, v208, v210
	v_mul_f32_e32 v208, v156, v156
	v_mul_f32_e32 v209, v157, v157
	v_mul_f32_e32 v210, v158, v158
	v_mul_f32_e32 v211, v159, v159
	v_add_f32_e32 v208, v209, v208
	v_add_f32_e32 v210, v210, v211
	v_add_f32_e32 v199, v208, v210
	v_mul_f32_e32 v208, v160, v160
	v_mul_f32_e32 v209, v161, v161
	v_mul_f32_e32 v210, v162, v162
	v_mul_f32_e32 v211, v163, v163
	v_add_f32_e32 v208, v209, v208
	v_add_f32_e32 v210, v210, v211
	v_add_f32_e32 v200, v208, v210
	v_mul_f32_e32 v208, v164, v164
	v_mul_f32_e32 v209, v165, v165
	v_mul_f32_e32 v210, v166, v166
	v_mul_f32_e32 v211, v167, v167
	v_add_f32_e32 v208, v209, v208
	v_add_f32_e32 v210, v210, v211
	v_add_f32_e32 v201, v208, v210
	v_mul_f32_e32 v208, v168, v168
	v_mul_f32_e32 v209, v169, v169
	v_mul_f32_e32 v210, v170, v170
	v_mul_f32_e32 v211, v171, v171
	v_add_f32_e32 v208, v209, v208
	v_add_f32_e32 v210, v210, v211
	v_add_f32_e32 v202, v208, v210
	v_mul_f32_e32 v208, v172, v172
	v_mul_f32_e32 v209, v173, v173
	v_mul_f32_e32 v210, v174, v174
	v_mul_f32_e32 v211, v175, v175
	v_add_f32_e32 v208, v209, v208
	v_add_f32_e32 v210, v210, v211
	v_add_f32_e32 v203, v208, v210
	v_mul_f32_e32 v208, v176, v176
	v_mul_f32_e32 v209, v177, v177
	v_mul_f32_e32 v210, v178, v178
	v_mul_f32_e32 v211, v179, v179
	v_add_f32_e32 v208, v209, v208
	v_add_f32_e32 v210, v210, v211
; __device__ __forceinline__ float wave_sum(float v) {
; #pragma unroll
;     for (int o = 1; o < 64; o <<= 1) v += __shfl_xor(v, o);
;     return v;
; __device__ __forceinline__ void sg_unit(const Params& P, int l, int chunk, char* shm, float* ssb) {
;     ...
;         v = v - mean; const f32x4 sq = v * v;
;         const float rstd = 1.f / sqrtf(wave_sum((sq[0] + sq[1]) + (sq[2] + sq[3])) * (1.f / 256.f) + LN_EPS);
	v_add_f32_e32 v204, v208, v210
	v_mul_f32_e32 v208, v180, v180
	v_mul_f32_e32 v209, v181, v181
	v_mul_f32_e32 v210, v182, v182
	v_mul_f32_e32 v211, v183, v183
	v_add_f32_e32 v208, v209, v208
	v_add_f32_e32 v210, v210, v211
	v_add_f32_e32 v205, v208, v210
	v_mul_f32_e32 v208, v184, v184
	v_mul_f32_e32 v209, v185, v185
	v_mul_f32_e32 v210, v186, v186
	v_mul_f32_e32 v211, v187, v187
	v_add_f32_e32 v208, v209, v208
	v_add_f32_e32 v210, v210, v211
	v_add_f32_e32 v206, v208, v210
	v_mul_f32_e32 v208, v188, v188
	v_mul_f32_e32 v209, v189, v189
	v_mul_f32_e32 v210, v190, v190
	v_mul_f32_e32 v211, v191, v191
	v_add_f32_e32 v208, v209, v208
	v_add_f32_e32 v210, v210, v211
	v_add_f32_e32 v207, v208, v210
	v_mov_b32_dpp v96, v192 quad_perm:[1,0,3,2] row_mask:0xf bank_mask:0xf
	v_mov_b32_dpp v97, v193 quad_perm:[1,0,3,2] row_mask:0xf bank_mask:0xf
	v_mov_b32_dpp v98, v194 quad_perm:[1,0,3,2] row_mask:0xf bank_mask:0xf
	v_mov_b32_dpp v99, v195 quad_perm:[1,0,3,2] row_mask:0xf bank_mask:0xf
	v_mov_b32_dpp v100, v196 quad_perm:[1,0,3,2] row_mask:0xf bank_mask:0xf
	v_mov_b32_dpp v101, v197 quad_perm:[1,0,3,2] row_mask:0xf bank_mask:0xf
	v_mov_b32_dpp v102, v198 quad_perm:[1,0,3,2] row_mask:0xf bank_mask:0xf
	v_mov_b32_dpp v103, v199 quad_perm:[1,0,3,2] row_mask:0xf bank_mask:0xf
	v_mov_b32_dpp v104, v200 quad_perm:[1,0,3,2] row_mask:0xf bank_mask:0xf
	v_mov_b32_dpp v105, v201 quad_perm:[1,0,3,2] row_mask:0xf bank_mask:0xf
	v_mov_b32_dpp v106, v202 quad_perm:[1,0,3,2] row_mask:0xf bank_mask:0xf
	v_mov_b32_dpp v107, v203 quad_perm:[1,0,3,2] row_mask:0xf bank_mask:0xf
	v_mov_b32_dpp v108, v204 quad_perm:[1,0,3,2] row_mask:0xf bank_mask:0xf
	v_mov_b32_dpp v109, v205 quad_perm:[1,0,3,2] row_mask:0xf bank_mask:0xf
	v_mov_b32_dpp v110, v206 quad_perm:[1,0,3,2] row_mask:0xf bank_mask:0xf
	v_mov_b32_dpp v111, v207 quad_perm:[1,0,3,2] row_mask:0xf bank_mask:0xf
	v_add_f32_e32 v192, v192, v96
	v_add_f32_e32 v193, v193, v97
	v_add_f32_e32 v194, v194, v98
	v_add_f32_e32 v195, v195, v99
	v_add_f32_e32 v196, v196, v100
	v_add_f32_e32 v197, v197, v101
	v_add_f32_e32 v198, v198, v102
	v_add_f32_e32 v199, v199, v103
	v_add_f32_e32 v200, v200, v104
	v_add_f32_e32 v201, v201, v105
	v_add_f32_e32 v202, v202, v106
	v_add_f32_e32 v203, v203, v107
	v_add_f32_e32 v204, v204, v108
	v_add_f32_e32 v205, v205, v109
	v_add_f32_e32 v206, v206, v110
	v_add_f32_e32 v207, v207, v111
	v_mov_b32_dpp v96, v192 quad_perm:[2,3,0,1] row_mask:0xf bank_mask:0xf
	v_mov_b32_dpp v97, v193 quad_perm:[2,3,0,1] row_mask:0xf bank_mask:0xf
	v_mov_b32_dpp v98, v194 quad_perm:[2,3,0,1] row_mask:0xf bank_mask:0xf
	v_mov_b32_dpp v99, v195 quad_perm:[2,3,0,1] row_mask:0xf bank_mask:0xf
	v_mov_b32_dpp v100, v196 quad_perm:[2,3,0,1] row_mask:0xf bank_mask:0xf
	v_mov_b32_dpp v101, v197 quad_perm:[2,3,0,1] row_mask:0xf bank_mask:0xf
	v_mov_b32_dpp v102, v198 quad_perm:[2,3,0,1] row_mask:0xf bank_mask:0xf
	v_mov_b32_dpp v103, v199 quad_perm:[2,3,0,1] row_mask:0xf bank_mask:0xf
	v_mov_b32_dpp v104, v200 quad_perm:[2,3,0,1] row_mask:0xf bank_mask:0xf
	v_mov_b32_dpp v105, v201 quad_perm:[2,3,0,1] row_mask:0xf bank_mask:0xf
	v_mov_b32_dpp v106, v202 quad_perm:[2,3,0,1] row_mask:0xf bank_mask:0xf
	v_mov_b32_dpp v107, v203 quad_perm:[2,3,0,1] row_mask:0xf bank_mask:0xf
	v_mov_b32_dpp v108, v204 quad_perm:[2,3,0,1] row_mask:0xf bank_mask:0xf
	v_mov_b32_dpp v109, v205 quad_perm:[2,3,0,1] row_mask:0xf bank_mask:0xf
	v_mov_b32_dpp v110, v206 quad_perm:[2,3,0,1] row_mask:0xf bank_mask:0xf
	v_mov_b32_dpp v111, v207 quad_perm:[2,3,0,1] row_mask:0xf bank_mask:0xf
	v_add_f32_e32 v192, v192, v96
	v_add_f32_e32 v193, v193, v97
	v_add_f32_e32 v194, v194, v98
	v_add_f32_e32 v195, v195, v99
	v_add_f32_e32 v196, v196, v100
	v_add_f32_e32 v197, v197, v101
	v_add_f32_e32 v198, v198, v102
	v_add_f32_e32 v199, v199, v103
	v_add_f32_e32 v200, v200, v104
	v_add_f32_e32 v201, v201, v105
	v_add_f32_e32 v202, v202, v106
	v_add_f32_e32 v203, v203, v107
	v_add_f32_e32 v204, v204, v108
	v_add_f32_e32 v205, v205, v109
	v_add_f32_e32 v206, v206, v110
	v_add_f32_e32 v207, v207, v111
	v_mov_b32_dpp v96, v192 row_half_mirror row_mask:0xf bank_mask:0xf
	v_mov_b32_dpp v97, v193 row_half_mirror row_mask:0xf bank_mask:0xf
	v_mov_b32_dpp v98, v194 row_half_mirror row_mask:0xf bank_mask:0xf
	v_mov_b32_dpp v99, v195 row_half_mirror row_mask:0xf bank_mask:0xf
	v_mov_b32_dpp v100, v196 row_half_mirror row_mask:0xf bank_mask:0xf
	v_mov_b32_dpp v101, v197 row_half_mirror row_mask:0xf bank_mask:0xf
	v_mov_b32_dpp v102, v198 row_half_mirror row_mask:0xf bank_mask:0xf
	v_mov_b32_dpp v103, v199 row_half_mirror row_mask:0xf bank_mask:0xf
	v_mov_b32_dpp v104, v200 row_half_mirror row_mask:0xf bank_mask:0xf
	v_mov_b32_dpp v105, v201 row_half_mirror row_mask:0xf bank_mask:0xf
	v_mov_b32_dpp v106, v202 row_half_mirror row_mask:0xf bank_mask:0xf
	v_mov_b32_dpp v107, v203 row_half_mirror row_mask:0xf bank_mask:0xf
	v_mov_b32_dpp v108, v204 row_half_mirror row_mask:0xf bank_mask:0xf
	v_mov_b32_dpp v109, v205 row_half_mirror row_mask:0xf bank_mask:0xf
	v_mov_b32_dpp v110, v206 row_half_mirror row_mask:0xf bank_mask:0xf
	v_mov_b32_dpp v111, v207 row_half_mirror row_mask:0xf bank_mask:0xf
	v_add_f32_e32 v192, v192, v96
	v_add_f32_e32 v193, v193, v97
	v_add_f32_e32 v194, v194, v98
	v_add_f32_e32 v195, v195, v99
	v_add_f32_e32 v196, v196, v100
	v_add_f32_e32 v197, v197, v101
	v_add_f32_e32 v198, v198, v102
	v_add_f32_e32 v199, v199, v103
	v_add_f32_e32 v200, v200, v104
	v_add_f32_e32 v201, v201, v105
	v_add_f32_e32 v202, v202, v106
	v_add_f32_e32 v203, v203, v107
	v_add_f32_e32 v204, v204, v108
	v_add_f32_e32 v205, v205, v109
	v_add_f32_e32 v206, v206, v110
; __device__ __forceinline__ unsigned cvtpk_s(float lo, float hi) { typedef __bf16 bf16x2_t __attribute__((ext_vector_type(2))); f32x2 v = {lo, hi}; bf16x2_t b = __builtin_convertvector(v, bf16x2_t); return __builtin_bit_cast(unsigned, b); }
; __device__ __forceinline__ void sg_unit(const Params& P, int l, int chunk, char* shm, float* ssb) {
;     ...
;         const float mean = wave_sum((v[0] + v[1]) + (v[2] + v[3])) * (1.f / 256.f);
;         v = v - mean; const f32x4 sq = v * v;
;         const float rstd = 1.f / sqrtf(wave_sum((sq[0] + sq[1]) + (sq[2] + sq[3])) * (1.f / 256.f) + LN_EPS);
;         v = v * rstd * g4;
; #pragma unroll
;         for (int j = 0; j < 4; ++j) vt[(4 * lane + j) * SG_VT_PITCH + q] = (bf16_t)(at::cvtpk_s(v[j], 0.f) & 0xffffu);
	v_add_f32_e32 v207, v207, v111
	v_mov_b32_dpp v96, v192 row_mirror row_mask:0xf bank_mask:0xf
	v_mov_b32_dpp v97, v193 row_mirror row_mask:0xf bank_mask:0xf
	v_mov_b32_dpp v98, v194 row_mirror row_mask:0xf bank_mask:0xf
	v_mov_b32_dpp v99, v195 row_mirror row_mask:0xf bank_mask:0xf
	v_mov_b32_dpp v100, v196 row_mirror row_mask:0xf bank_mask:0xf
	v_mov_b32_dpp v101, v197 row_mirror row_mask:0xf bank_mask:0xf
	v_mov_b32_dpp v102, v198 row_mirror row_mask:0xf bank_mask:0xf
	v_mov_b32_dpp v103, v199 row_mirror row_mask:0xf bank_mask:0xf
	v_mov_b32_dpp v104, v200 row_mirror row_mask:0xf bank_mask:0xf
	v_mov_b32_dpp v105, v201 row_mirror row_mask:0xf bank_mask:0xf
	v_mov_b32_dpp v106, v202 row_mirror row_mask:0xf bank_mask:0xf
	v_mov_b32_dpp v107, v203 row_mirror row_mask:0xf bank_mask:0xf
	v_mov_b32_dpp v108, v204 row_mirror row_mask:0xf bank_mask:0xf
	v_mov_b32_dpp v109, v205 row_mirror row_mask:0xf bank_mask:0xf
	v_mov_b32_dpp v110, v206 row_mirror row_mask:0xf bank_mask:0xf
	v_mov_b32_dpp v111, v207 row_mirror row_mask:0xf bank_mask:0xf
	v_add_f32_e32 v192, v192, v96
	v_add_f32_e32 v193, v193, v97
	v_add_f32_e32 v194, v194, v98
	v_add_f32_e32 v195, v195, v99
	v_add_f32_e32 v196, v196, v100
	v_add_f32_e32 v197, v197, v101
	v_add_f32_e32 v198, v198, v102
	v_add_f32_e32 v199, v199, v103
	v_add_f32_e32 v200, v200, v104
	v_add_f32_e32 v201, v201, v105
	v_add_f32_e32 v202, v202, v106
	v_add_f32_e32 v203, v203, v107
	v_add_f32_e32 v204, v204, v108
	v_add_f32_e32 v205, v205, v109
	v_add_f32_e32 v206, v206, v110
	v_add_f32_e32 v207, v207, v111
	ds_bpermute_b32 v96, v15, v192
	ds_bpermute_b32 v97, v15, v193
	ds_bpermute_b32 v98, v15, v194
	ds_bpermute_b32 v99, v15, v195
	ds_bpermute_b32 v100, v15, v196
	ds_bpermute_b32 v101, v15, v197
	ds_bpermute_b32 v102, v15, v198
	ds_bpermute_b32 v103, v15, v199
	ds_bpermute_b32 v104, v15, v200
	ds_bpermute_b32 v105, v15, v201
	ds_bpermute_b32 v106, v15, v202
	ds_bpermute_b32 v107, v15, v203
	ds_bpermute_b32 v108, v15, v204
	ds_bpermute_b32 v109, v15, v205
	ds_bpermute_b32 v110, v15, v206
	ds_bpermute_b32 v111, v15, v207
	s_waitcnt lgkmcnt(8)
	v_add_f32_e32 v192, v192, v96
	v_add_f32_e32 v193, v193, v97
	v_add_f32_e32 v194, v194, v98
	v_add_f32_e32 v195, v195, v99
	v_add_f32_e32 v196, v196, v100
	v_add_f32_e32 v197, v197, v101
	v_add_f32_e32 v198, v198, v102
	v_add_f32_e32 v199, v199, v103
	s_waitcnt lgkmcnt(0)
	v_add_f32_e32 v200, v200, v104
	v_add_f32_e32 v201, v201, v105
	v_add_f32_e32 v202, v202, v106
	v_add_f32_e32 v203, v203, v107
	v_add_f32_e32 v204, v204, v108
	v_add_f32_e32 v205, v205, v109
	v_add_f32_e32 v206, v206, v110
	v_add_f32_e32 v207, v207, v111
	ds_bpermute_b32 v96, v18, v192
	ds_bpermute_b32 v97, v18, v193
	ds_bpermute_b32 v98, v18, v194
	ds_bpermute_b32 v99, v18, v195
	ds_bpermute_b32 v100, v18, v196
	ds_bpermute_b32 v101, v18, v197
	ds_bpermute_b32 v102, v18, v198
	ds_bpermute_b32 v103, v18, v199
	ds_bpermute_b32 v104, v18, v200
	ds_bpermute_b32 v105, v18, v201
	ds_bpermute_b32 v106, v18, v202
	ds_bpermute_b32 v107, v18, v203
	ds_bpermute_b32 v108, v18, v204
	ds_bpermute_b32 v109, v18, v205
	ds_bpermute_b32 v110, v18, v206
	ds_bpermute_b32 v111, v18, v207
	s_waitcnt lgkmcnt(8)
	v_add_f32_e32 v192, v192, v96
	v_add_f32_e32 v193, v193, v97
	v_add_f32_e32 v194, v194, v98
	v_add_f32_e32 v195, v195, v99
	v_add_f32_e32 v196, v196, v100
	v_add_f32_e32 v197, v197, v101
	v_add_f32_e32 v198, v198, v102
	v_add_f32_e32 v199, v199, v103
	s_waitcnt lgkmcnt(0)
	v_add_f32_e32 v200, v200, v104
	v_add_f32_e32 v201, v201, v105
	v_add_f32_e32 v202, v202, v106
	v_add_f32_e32 v203, v203, v107
	v_add_f32_e32 v204, v204, v108
	v_add_f32_e32 v205, v205, v109
	v_add_f32_e32 v206, v206, v110
	v_add_f32_e32 v207, v207, v111
	v_fmamk_f32 v192, v192, 0x3b800000, v216
	v_cmp_gt_f32_e32 vcc, s69, v192
	v_mul_f32_e32 v96, 0x4f800000, v192
	s_nop 0
	v_cndmask_b32_e32 v192, v192, v96, vcc
	v_sqrt_f32_e32 v96, v192
	s_nop 0
	v_add_u32_e32 v97, -1, v96
	v_fma_f32 v98, -v97, v96, v192
	v_cmp_ge_f32_e64 s[0:1], 0, v98
	v_add_u32_e32 v98, 1, v96
	s_nop 0
	v_cndmask_b32_e64 v97, v96, v97, s[0:1]
	v_fma_f32 v96, -v98, v96, v192
	v_cmp_lt_f32_e64 s[0:1], 0, v96
	s_nop 1
	v_cndmask_b32_e64 v96, v97, v98, s[0:1]
	v_mul_f32_e32 v97, 0x37800000, v96
	v_cndmask_b32_e32 v96, v96, v97, vcc
	v_cmp_class_f32_e32 vcc, v192, v217
	s_nop 1
	v_cndmask_b32_e32 v192, v96, v192, vcc
	v_div_scale_f32 v96, s[0:1], v192, v192, 1.0
	v_rcp_f32_e32 v97, v96
	s_nop 0
	v_fma_f32 v98, -v96, v97, 1.0
	v_fmac_f32_e32 v97, v98, v97
	v_div_scale_f32 v98, vcc, 1.0, v192, 1.0
	v_mul_f32_e32 v99, v98, v97
	v_fma_f32 v100, -v96, v99, v98
	v_fmac_f32_e32 v99, v100, v97
	v_fma_f32 v96, -v96, v99, v98
	v_div_fmas_f32 v96, v96, v97, v99
	v_div_fixup_f32 v192, v96, v192, 1.0
	v_mul_f32_e32 v128, v128, v192
	v_mul_f32_e32 v129, v129, v192
	v_mul_f32_e32 v130, v130, v192
	v_mul_f32_e32 v131, v131, v192
	v_mul_f32_e32 v96, v2, v128
	v_cvt_pk_bf16_f32 v96, v96, s0
	v_mul_f32_e32 v97, v3, v129
	v_cvt_pk_bf16_f32 v97, v97, s0
	v_mul_f32_e32 v98, v4, v130
	v_cvt_pk_bf16_f32 v98, v98, s0
	v_mul_f32_e32 v99, v5, v131
	v_cvt_pk_bf16_f32 v99, v99, s0
	ds_write_b16 v19, v96 offset:0
	ds_write_b16 v19, v97 offset:272
	ds_write_b16 v19, v98 offset:544
	ds_write_b16 v19, v99 offset:816
	v_fmamk_f32 v193, v193, 0x3b800000, v216
	v_cmp_gt_f32_e32 vcc, s69, v193
	v_mul_f32_e32 v96, 0x4f800000, v193
	s_nop 0
	v_cndmask_b32_e32 v193, v193, v96, vcc
	v_sqrt_f32_e32 v96, v193
	s_nop 0
	v_add_u32_e32 v97, -1, v96
	v_fma_f32 v98, -v97, v96, v193
	v_cmp_ge_f32_e64 s[0:1], 0, v98
	v_add_u32_e32 v98, 1, v96
	s_nop 0
	v_cndmask_b32_e64 v97, v96, v97, s[0:1]
	v_fma_f32 v96, -v98, v96, v193
; __device__ __forceinline__ unsigned cvtpk_s(float lo, float hi) { typedef __bf16 bf16x2_t __attribute__((ext_vector_type(2))); f32x2 v = {lo, hi}; bf16x2_t b = __builtin_convertvector(v, bf16x2_t); return __builtin_bit_cast(unsigned, b); }
; __device__ __forceinline__ void sg_unit(const Params& P, int l, int chunk, char* shm, float* ssb) {
;     ...
;         const float rstd = 1.f / sqrtf(wave_sum((sq[0] + sq[1]) + (sq[2] + sq[3])) * (1.f / 256.f) + LN_EPS);
;         v = v * rstd * g4;
; #pragma unroll
;         for (int j = 0; j < 4; ++j) vt[(4 * lane + j) * SG_VT_PITCH + q] = (bf16_t)(at::cvtpk_s(v[j], 0.f) & 0xffffu);
	v_cmp_lt_f32_e64 s[0:1], 0, v96
	s_nop 1
	v_cndmask_b32_e64 v96, v97, v98, s[0:1]
	v_mul_f32_e32 v97, 0x37800000, v96
	v_cndmask_b32_e32 v96, v96, v97, vcc
	v_cmp_class_f32_e32 vcc, v193, v217
	s_nop 1
	v_cndmask_b32_e32 v193, v96, v193, vcc
	v_div_scale_f32 v96, s[0:1], v193, v193, 1.0
	v_rcp_f32_e32 v97, v96
	s_nop 0
	v_fma_f32 v98, -v96, v97, 1.0
	v_fmac_f32_e32 v97, v98, v97
	v_div_scale_f32 v98, vcc, 1.0, v193, 1.0
	v_mul_f32_e32 v99, v98, v97
	v_fma_f32 v100, -v96, v99, v98
	v_fmac_f32_e32 v99, v100, v97
	v_fma_f32 v96, -v96, v99, v98
	v_div_fmas_f32 v96, v96, v97, v99
	v_div_fixup_f32 v193, v96, v193, 1.0
	v_mul_f32_e32 v132, v132, v193
	v_mul_f32_e32 v133, v133, v193
	v_mul_f32_e32 v134, v134, v193
	v_mul_f32_e32 v135, v135, v193
	v_mul_f32_e32 v96, v2, v132
	v_cvt_pk_bf16_f32 v96, v96, s0
	v_mul_f32_e32 v97, v3, v133
	v_cvt_pk_bf16_f32 v97, v97, s0
	v_mul_f32_e32 v98, v4, v134
	v_cvt_pk_bf16_f32 v98, v98, s0
	v_mul_f32_e32 v99, v5, v135
	v_cvt_pk_bf16_f32 v99, v99, s0
	ds_write_b16 v19, v96 offset:2
	ds_write_b16 v19, v97 offset:274
	ds_write_b16 v19, v98 offset:546
	ds_write_b16 v19, v99 offset:818
	v_fmamk_f32 v194, v194, 0x3b800000, v216
	v_cmp_gt_f32_e32 vcc, s69, v194
	v_mul_f32_e32 v96, 0x4f800000, v194
	s_nop 0
	v_cndmask_b32_e32 v194, v194, v96, vcc
	v_sqrt_f32_e32 v96, v194
	s_nop 0
	v_add_u32_e32 v97, -1, v96
	v_fma_f32 v98, -v97, v96, v194
	v_cmp_ge_f32_e64 s[0:1], 0, v98
	v_add_u32_e32 v98, 1, v96
	s_nop 0
	v_cndmask_b32_e64 v97, v96, v97, s[0:1]
	v_fma_f32 v96, -v98, v96, v194
	v_cmp_lt_f32_e64 s[0:1], 0, v96
	s_nop 1
	v_cndmask_b32_e64 v96, v97, v98, s[0:1]
	v_mul_f32_e32 v97, 0x37800000, v96
	v_cndmask_b32_e32 v96, v96, v97, vcc
	v_cmp_class_f32_e32 vcc, v194, v217
	s_nop 1
	v_cndmask_b32_e32 v194, v96, v194, vcc
	v_div_scale_f32 v96, s[0:1], v194, v194, 1.0
	v_rcp_f32_e32 v97, v96
	s_nop 0
	v_fma_f32 v98, -v96, v97, 1.0
	v_fmac_f32_e32 v97, v98, v97
	v_div_scale_f32 v98, vcc, 1.0, v194, 1.0
	v_mul_f32_e32 v99, v98, v97
	v_fma_f32 v100, -v96, v99, v98
	v_fmac_f32_e32 v99, v100, v97
	v_fma_f32 v96, -v96, v99, v98
	v_div_fmas_f32 v96, v96, v97, v99
	v_div_fixup_f32 v194, v96, v194, 1.0
	v_mul_f32_e32 v136, v136, v194
	v_mul_f32_e32 v137, v137, v194
	v_mul_f32_e32 v138, v138, v194
	v_mul_f32_e32 v139, v139, v194
	v_mul_f32_e32 v96, v2, v136
	v_cvt_pk_bf16_f32 v96, v96, s0
	v_mul_f32_e32 v97, v3, v137
	v_cvt_pk_bf16_f32 v97, v97, s0
	v_mul_f32_e32 v98, v4, v138
	v_cvt_pk_bf16_f32 v98, v98, s0
	v_mul_f32_e32 v99, v5, v139
	v_cvt_pk_bf16_f32 v99, v99, s0
	ds_write_b16 v19, v96 offset:4
	ds_write_b16 v19, v97 offset:276
	ds_write_b16 v19, v98 offset:548
	ds_write_b16 v19, v99 offset:820
	v_fmamk_f32 v195, v195, 0x3b800000, v216
	v_cmp_gt_f32_e32 vcc, s69, v195
	v_mul_f32_e32 v96, 0x4f800000, v195
	s_nop 0
	v_cndmask_b32_e32 v195, v195, v96, vcc
	v_sqrt_f32_e32 v96, v195
	s_nop 0
	v_add_u32_e32 v97, -1, v96
	v_fma_f32 v98, -v97, v96, v195
	v_cmp_ge_f32_e64 s[0:1], 0, v98
	v_add_u32_e32 v98, 1, v96
	s_nop 0
	v_cndmask_b32_e64 v97, v96, v97, s[0:1]
	v_fma_f32 v96, -v98, v96, v195
	v_cmp_lt_f32_e64 s[0:1], 0, v96
	s_nop 1
	v_cndmask_b32_e64 v96, v97, v98, s[0:1]
	v_mul_f32_e32 v97, 0x37800000, v96
	v_cndmask_b32_e32 v96, v96, v97, vcc
	v_cmp_class_f32_e32 vcc, v195, v217
	s_nop 1
	v_cndmask_b32_e32 v195, v96, v195, vcc
	v_div_scale_f32 v96, s[0:1], v195, v195, 1.0
	v_rcp_f32_e32 v97, v96
	s_nop 0
	v_fma_f32 v98, -v96, v97, 1.0
	v_fmac_f32_e32 v97, v98, v97
	v_div_scale_f32 v98, vcc, 1.0, v195, 1.0
	v_mul_f32_e32 v99, v98, v97
	v_fma_f32 v100, -v96, v99, v98
	v_fmac_f32_e32 v99, v100, v97
	v_fma_f32 v96, -v96, v99, v98
	v_div_fmas_f32 v96, v96, v97, v99
	v_div_fixup_f32 v195, v96, v195, 1.0
	v_mul_f32_e32 v140, v140, v195
	v_mul_f32_e32 v141, v141, v195
	v_mul_f32_e32 v142, v142, v195
	v_mul_f32_e32 v143, v143, v195
	v_mul_f32_e32 v96, v2, v140
	v_cvt_pk_bf16_f32 v96, v96, s0
	v_mul_f32_e32 v97, v3, v141
	v_cvt_pk_bf16_f32 v97, v97, s0
	v_mul_f32_e32 v98, v4, v142
	v_cvt_pk_bf16_f32 v98, v98, s0
	v_mul_f32_e32 v99, v5, v143
	v_cvt_pk_bf16_f32 v99, v99, s0
	ds_write_b16 v19, v96 offset:6
	ds_write_b16 v19, v97 offset:278
	ds_write_b16 v19, v98 offset:550
	ds_write_b16 v19, v99 offset:822
	v_fmamk_f32 v196, v196, 0x3b800000, v216
	v_cmp_gt_f32_e32 vcc, s69, v196
	v_mul_f32_e32 v96, 0x4f800000, v196
	s_nop 0
	v_cndmask_b32_e32 v196, v196, v96, vcc
	v_sqrt_f32_e32 v96, v196
	s_nop 0
	v_add_u32_e32 v97, -1, v96
	v_fma_f32 v98, -v97, v96, v196
	v_cmp_ge_f32_e64 s[0:1], 0, v98
	v_add_u32_e32 v98, 1, v96
	s_nop 0
	v_cndmask_b32_e64 v97, v96, v97, s[0:1]
	v_fma_f32 v96, -v98, v96, v196
	v_cmp_lt_f32_e64 s[0:1], 0, v96
	s_nop 1
	v_cndmask_b32_e64 v96, v97, v98, s[0:1]
	v_mul_f32_e32 v97, 0x37800000, v96
	v_cndmask_b32_e32 v96, v96, v97, vcc
	v_cmp_class_f32_e32 vcc, v196, v217
	s_nop 1
	v_cndmask_b32_e32 v196, v96, v196, vcc
	v_div_scale_f32 v96, s[0:1], v196, v196, 1.0
	v_rcp_f32_e32 v97, v96
	s_nop 0
	v_fma_f32 v98, -v96, v97, 1.0
	v_fmac_f32_e32 v97, v98, v97
	v_div_scale_f32 v98, vcc, 1.0, v196, 1.0
	v_mul_f32_e32 v99, v98, v97
	v_fma_f32 v100, -v96, v99, v98
	v_fmac_f32_e32 v99, v100, v97
	v_fma_f32 v96, -v96, v99, v98
	v_div_fmas_f32 v96, v96, v97, v99
	v_div_fixup_f32 v196, v96, v196, 1.0
	v_mul_f32_e32 v144, v144, v196
	v_mul_f32_e32 v145, v145, v196
	v_mul_f32_e32 v146, v146, v196
	v_mul_f32_e32 v147, v147, v196
	v_mul_f32_e32 v96, v2, v144
	v_cvt_pk_bf16_f32 v96, v96, s0
	v_mul_f32_e32 v97, v3, v145
	v_cvt_pk_bf16_f32 v97, v97, s0
	v_mul_f32_e32 v98, v4, v146
	v_cvt_pk_bf16_f32 v98, v98, s0
	v_mul_f32_e32 v99, v5, v147
	v_cvt_pk_bf16_f32 v99, v99, s0
	ds_write_b16 v19, v96 offset:8
	ds_write_b16 v19, v97 offset:280
; __device__ __forceinline__ unsigned cvtpk_s(float lo, float hi) { typedef __bf16 bf16x2_t __attribute__((ext_vector_type(2))); f32x2 v = {lo, hi}; bf16x2_t b = __builtin_convertvector(v, bf16x2_t); return __builtin_bit_cast(unsigned, b); }
; __device__ __forceinline__ void sg_unit(const Params& P, int l, int chunk, char* shm, float* ssb) {
;     ...
;         const float rstd = 1.f / sqrtf(wave_sum((sq[0] + sq[1]) + (sq[2] + sq[3])) * (1.f / 256.f) + LN_EPS);
;         v = v * rstd * g4;
; #pragma unroll
;         for (int j = 0; j < 4; ++j) vt[(4 * lane + j) * SG_VT_PITCH + q] = (bf16_t)(at::cvtpk_s(v[j], 0.f) & 0xffffu);
	ds_write_b16 v19, v98 offset:552
	ds_write_b16 v19, v99 offset:824
	v_fmamk_f32 v197, v197, 0x3b800000, v216
	v_cmp_gt_f32_e32 vcc, s69, v197
	v_mul_f32_e32 v96, 0x4f800000, v197
	s_nop 0
	v_cndmask_b32_e32 v197, v197, v96, vcc
	v_sqrt_f32_e32 v96, v197
	s_nop 0
	v_add_u32_e32 v97, -1, v96
	v_fma_f32 v98, -v97, v96, v197
	v_cmp_ge_f32_e64 s[0:1], 0, v98
	v_add_u32_e32 v98, 1, v96
	s_nop 0
	v_cndmask_b32_e64 v97, v96, v97, s[0:1]
	v_fma_f32 v96, -v98, v96, v197
	v_cmp_lt_f32_e64 s[0:1], 0, v96
	s_nop 1
	v_cndmask_b32_e64 v96, v97, v98, s[0:1]
	v_mul_f32_e32 v97, 0x37800000, v96
	v_cndmask_b32_e32 v96, v96, v97, vcc
	v_cmp_class_f32_e32 vcc, v197, v217
	s_nop 1
	v_cndmask_b32_e32 v197, v96, v197, vcc
	v_div_scale_f32 v96, s[0:1], v197, v197, 1.0
	v_rcp_f32_e32 v97, v96
	s_nop 0
	v_fma_f32 v98, -v96, v97, 1.0
	v_fmac_f32_e32 v97, v98, v97
	v_div_scale_f32 v98, vcc, 1.0, v197, 1.0
	v_mul_f32_e32 v99, v98, v97
	v_fma_f32 v100, -v96, v99, v98
	v_fmac_f32_e32 v99, v100, v97
	v_fma_f32 v96, -v96, v99, v98
	v_div_fmas_f32 v96, v96, v97, v99
	v_div_fixup_f32 v197, v96, v197, 1.0
	v_mul_f32_e32 v148, v148, v197
	v_mul_f32_e32 v149, v149, v197
	v_mul_f32_e32 v150, v150, v197
	v_mul_f32_e32 v151, v151, v197
	v_mul_f32_e32 v96, v2, v148
	v_cvt_pk_bf16_f32 v96, v96, s0
	v_mul_f32_e32 v97, v3, v149
	v_cvt_pk_bf16_f32 v97, v97, s0
	v_mul_f32_e32 v98, v4, v150
	v_cvt_pk_bf16_f32 v98, v98, s0
	v_mul_f32_e32 v99, v5, v151
	v_cvt_pk_bf16_f32 v99, v99, s0
	ds_write_b16 v19, v96 offset:10
	ds_write_b16 v19, v97 offset:282
	ds_write_b16 v19, v98 offset:554
	ds_write_b16 v19, v99 offset:826
	v_fmamk_f32 v198, v198, 0x3b800000, v216
	v_cmp_gt_f32_e32 vcc, s69, v198
	v_mul_f32_e32 v96, 0x4f800000, v198
	s_nop 0
	v_cndmask_b32_e32 v198, v198, v96, vcc
	v_sqrt_f32_e32 v96, v198
	s_nop 0
	v_add_u32_e32 v97, -1, v96
	v_fma_f32 v98, -v97, v96, v198
	v_cmp_ge_f32_e64 s[0:1], 0, v98
	v_add_u32_e32 v98, 1, v96
	s_nop 0
	v_cndmask_b32_e64 v97, v96, v97, s[0:1]
	v_fma_f32 v96, -v98, v96, v198
	v_cmp_lt_f32_e64 s[0:1], 0, v96
	s_nop 1
	v_cndmask_b32_e64 v96, v97, v98, s[0:1]
	v_mul_f32_e32 v97, 0x37800000, v96
	v_cndmask_b32_e32 v96, v96, v97, vcc
	v_cmp_class_f32_e32 vcc, v198, v217
	s_nop 1
	v_cndmask_b32_e32 v198, v96, v198, vcc
	v_div_scale_f32 v96, s[0:1], v198, v198, 1.0
	v_rcp_f32_e32 v97, v96
	s_nop 0
	v_fma_f32 v98, -v96, v97, 1.0
	v_fmac_f32_e32 v97, v98, v97
	v_div_scale_f32 v98, vcc, 1.0, v198, 1.0
	v_mul_f32_e32 v99, v98, v97
	v_fma_f32 v100, -v96, v99, v98
	v_fmac_f32_e32 v99, v100, v97
	v_fma_f32 v96, -v96, v99, v98
	v_div_fmas_f32 v96, v96, v97, v99
	v_div_fixup_f32 v198, v96, v198, 1.0
	v_mul_f32_e32 v152, v152, v198
	v_mul_f32_e32 v153, v153, v198
	v_mul_f32_e32 v154, v154, v198
	v_mul_f32_e32 v155, v155, v198
	v_mul_f32_e32 v96, v2, v152
	v_cvt_pk_bf16_f32 v96, v96, s0
	v_mul_f32_e32 v97, v3, v153
	v_cvt_pk_bf16_f32 v97, v97, s0
	v_mul_f32_e32 v98, v4, v154
	v_cvt_pk_bf16_f32 v98, v98, s0
	v_mul_f32_e32 v99, v5, v155
	v_cvt_pk_bf16_f32 v99, v99, s0
	ds_write_b16 v19, v96 offset:12
	ds_write_b16 v19, v97 offset:284
	ds_write_b16 v19, v98 offset:556
	ds_write_b16 v19, v99 offset:828
	v_fmamk_f32 v199, v199, 0x3b800000, v216
	v_cmp_gt_f32_e32 vcc, s69, v199
	v_mul_f32_e32 v96, 0x4f800000, v199
	s_nop 0
	v_cndmask_b32_e32 v199, v199, v96, vcc
	v_sqrt_f32_e32 v96, v199
	s_nop 0
	v_add_u32_e32 v97, -1, v96
	v_fma_f32 v98, -v97, v96, v199
	v_cmp_ge_f32_e64 s[0:1], 0, v98
	v_add_u32_e32 v98, 1, v96
	s_nop 0
	v_cndmask_b32_e64 v97, v96, v97, s[0:1]
	v_fma_f32 v96, -v98, v96, v199
	v_cmp_lt_f32_e64 s[0:1], 0, v96
	s_nop 1
	v_cndmask_b32_e64 v96, v97, v98, s[0:1]
	v_mul_f32_e32 v97, 0x37800000, v96
	v_cndmask_b32_e32 v96, v96, v97, vcc
	v_cmp_class_f32_e32 vcc, v199, v217
	s_nop 1
	v_cndmask_b32_e32 v199, v96, v199, vcc
	v_div_scale_f32 v96, s[0:1], v199, v199, 1.0
	v_rcp_f32_e32 v97, v96
	s_nop 0
	v_fma_f32 v98, -v96, v97, 1.0
	v_fmac_f32_e32 v97, v98, v97
	v_div_scale_f32 v98, vcc, 1.0, v199, 1.0
	v_mul_f32_e32 v99, v98, v97
	v_fma_f32 v100, -v96, v99, v98
	v_fmac_f32_e32 v99, v100, v97
	v_fma_f32 v96, -v96, v99, v98
	v_div_fmas_f32 v96, v96, v97, v99
	v_div_fixup_f32 v199, v96, v199, 1.0
	v_mul_f32_e32 v156, v156, v199
	v_mul_f32_e32 v157, v157, v199
	v_mul_f32_e32 v158, v158, v199
	v_mul_f32_e32 v159, v159, v199
	v_mul_f32_e32 v96, v2, v156
	v_cvt_pk_bf16_f32 v96, v96, s0
	v_mul_f32_e32 v97, v3, v157
	v_cvt_pk_bf16_f32 v97, v97, s0
	v_mul_f32_e32 v98, v4, v158
	v_cvt_pk_bf16_f32 v98, v98, s0
	v_mul_f32_e32 v99, v5, v159
	v_cvt_pk_bf16_f32 v99, v99, s0
	ds_write_b16 v19, v96 offset:14
	ds_write_b16 v19, v97 offset:286
	ds_write_b16 v19, v98 offset:558
	ds_write_b16 v19, v99 offset:830
	v_fmamk_f32 v200, v200, 0x3b800000, v216
	v_cmp_gt_f32_e32 vcc, s69, v200
	v_mul_f32_e32 v96, 0x4f800000, v200
	s_nop 0
	v_cndmask_b32_e32 v200, v200, v96, vcc
	v_sqrt_f32_e32 v96, v200
	s_nop 0
	v_add_u32_e32 v97, -1, v96
	v_fma_f32 v98, -v97, v96, v200
	v_cmp_ge_f32_e64 s[0:1], 0, v98
	v_add_u32_e32 v98, 1, v96
	s_nop 0
	v_cndmask_b32_e64 v97, v96, v97, s[0:1]
	v_fma_f32 v96, -v98, v96, v200
	v_cmp_lt_f32_e64 s[0:1], 0, v96
	s_nop 1
	v_cndmask_b32_e64 v96, v97, v98, s[0:1]
	v_mul_f32_e32 v97, 0x37800000, v96
	v_cndmask_b32_e32 v96, v96, v97, vcc
	v_cmp_class_f32_e32 vcc, v200, v217
	s_nop 1
	v_cndmask_b32_e32 v200, v96, v200, vcc
	v_div_scale_f32 v96, s[0:1], v200, v200, 1.0
	v_rcp_f32_e32 v97, v96
	s_nop 0
	v_fma_f32 v98, -v96, v97, 1.0
	v_fmac_f32_e32 v97, v98, v97
	v_div_scale_f32 v98, vcc, 1.0, v200, 1.0
	v_mul_f32_e32 v99, v98, v97
	v_fma_f32 v100, -v96, v99, v98
	v_fmac_f32_e32 v99, v100, v97
	v_fma_f32 v96, -v96, v99, v98
	v_div_fmas_f32 v96, v96, v97, v99
; __device__ __forceinline__ unsigned cvtpk_s(float lo, float hi) { typedef __bf16 bf16x2_t __attribute__((ext_vector_type(2))); f32x2 v = {lo, hi}; bf16x2_t b = __builtin_convertvector(v, bf16x2_t); return __builtin_bit_cast(unsigned, b); }
; __device__ __forceinline__ void sg_unit(const Params& P, int l, int chunk, char* shm, float* ssb) {
;     ...
;         const float rstd = 1.f / sqrtf(wave_sum((sq[0] + sq[1]) + (sq[2] + sq[3])) * (1.f / 256.f) + LN_EPS);
;         v = v * rstd * g4;
; #pragma unroll
;         for (int j = 0; j < 4; ++j) vt[(4 * lane + j) * SG_VT_PITCH + q] = (bf16_t)(at::cvtpk_s(v[j], 0.f) & 0xffffu);
	v_div_fixup_f32 v200, v96, v200, 1.0
	v_mul_f32_e32 v160, v160, v200
	v_mul_f32_e32 v161, v161, v200
	v_mul_f32_e32 v162, v162, v200
	v_mul_f32_e32 v163, v163, v200
	v_mul_f32_e32 v96, v2, v160
	v_cvt_pk_bf16_f32 v96, v96, s0
	v_mul_f32_e32 v97, v3, v161
	v_cvt_pk_bf16_f32 v97, v97, s0
	v_mul_f32_e32 v98, v4, v162
	v_cvt_pk_bf16_f32 v98, v98, s0
	v_mul_f32_e32 v99, v5, v163
	v_cvt_pk_bf16_f32 v99, v99, s0
	ds_write_b16 v19, v96 offset:16
	ds_write_b16 v19, v97 offset:288
	ds_write_b16 v19, v98 offset:560
	ds_write_b16 v19, v99 offset:832
	v_fmamk_f32 v201, v201, 0x3b800000, v216
	v_cmp_gt_f32_e32 vcc, s69, v201
	v_mul_f32_e32 v96, 0x4f800000, v201
	s_nop 0
	v_cndmask_b32_e32 v201, v201, v96, vcc
	v_sqrt_f32_e32 v96, v201
	s_nop 0
	v_add_u32_e32 v97, -1, v96
	v_fma_f32 v98, -v97, v96, v201
	v_cmp_ge_f32_e64 s[0:1], 0, v98
	v_add_u32_e32 v98, 1, v96
	s_nop 0
	v_cndmask_b32_e64 v97, v96, v97, s[0:1]
	v_fma_f32 v96, -v98, v96, v201
	v_cmp_lt_f32_e64 s[0:1], 0, v96
	s_nop 1
	v_cndmask_b32_e64 v96, v97, v98, s[0:1]
	v_mul_f32_e32 v97, 0x37800000, v96
	v_cndmask_b32_e32 v96, v96, v97, vcc
	v_cmp_class_f32_e32 vcc, v201, v217
	s_nop 1
	v_cndmask_b32_e32 v201, v96, v201, vcc
	v_div_scale_f32 v96, s[0:1], v201, v201, 1.0
	v_rcp_f32_e32 v97, v96
	s_nop 0
	v_fma_f32 v98, -v96, v97, 1.0
	v_fmac_f32_e32 v97, v98, v97
	v_div_scale_f32 v98, vcc, 1.0, v201, 1.0
	v_mul_f32_e32 v99, v98, v97
	v_fma_f32 v100, -v96, v99, v98
	v_fmac_f32_e32 v99, v100, v97
	v_fma_f32 v96, -v96, v99, v98
	v_div_fmas_f32 v96, v96, v97, v99
	v_div_fixup_f32 v201, v96, v201, 1.0
	v_mul_f32_e32 v164, v164, v201
	v_mul_f32_e32 v165, v165, v201
	v_mul_f32_e32 v166, v166, v201
	v_mul_f32_e32 v167, v167, v201
	v_mul_f32_e32 v96, v2, v164
	v_cvt_pk_bf16_f32 v96, v96, s0
	v_mul_f32_e32 v97, v3, v165
	v_cvt_pk_bf16_f32 v97, v97, s0
	v_mul_f32_e32 v98, v4, v166
	v_cvt_pk_bf16_f32 v98, v98, s0
	v_mul_f32_e32 v99, v5, v167
	v_cvt_pk_bf16_f32 v99, v99, s0
	ds_write_b16 v19, v96 offset:18
	ds_write_b16 v19, v97 offset:290
	ds_write_b16 v19, v98 offset:562
	ds_write_b16 v19, v99 offset:834
	v_fmamk_f32 v202, v202, 0x3b800000, v216
	v_cmp_gt_f32_e32 vcc, s69, v202
	v_mul_f32_e32 v96, 0x4f800000, v202
	s_nop 0
	v_cndmask_b32_e32 v202, v202, v96, vcc
	v_sqrt_f32_e32 v96, v202
	s_nop 0
	v_add_u32_e32 v97, -1, v96
	v_fma_f32 v98, -v97, v96, v202
	v_cmp_ge_f32_e64 s[0:1], 0, v98
	v_add_u32_e32 v98, 1, v96
	s_nop 0
	v_cndmask_b32_e64 v97, v96, v97, s[0:1]
	v_fma_f32 v96, -v98, v96, v202
	v_cmp_lt_f32_e64 s[0:1], 0, v96
	s_nop 1
	v_cndmask_b32_e64 v96, v97, v98, s[0:1]
	v_mul_f32_e32 v97, 0x37800000, v96
	v_cndmask_b32_e32 v96, v96, v97, vcc
	v_cmp_class_f32_e32 vcc, v202, v217
	s_nop 1
	v_cndmask_b32_e32 v202, v96, v202, vcc
	v_div_scale_f32 v96, s[0:1], v202, v202, 1.0
	v_rcp_f32_e32 v97, v96
	s_nop 0
	v_fma_f32 v98, -v96, v97, 1.0
	v_fmac_f32_e32 v97, v98, v97
	v_div_scale_f32 v98, vcc, 1.0, v202, 1.0
	v_mul_f32_e32 v99, v98, v97
	v_fma_f32 v100, -v96, v99, v98
	v_fmac_f32_e32 v99, v100, v97
	v_fma_f32 v96, -v96, v99, v98
	v_div_fmas_f32 v96, v96, v97, v99
	v_div_fixup_f32 v202, v96, v202, 1.0
	v_mul_f32_e32 v168, v168, v202
	v_mul_f32_e32 v169, v169, v202
	v_mul_f32_e32 v170, v170, v202
	v_mul_f32_e32 v171, v171, v202
	v_mul_f32_e32 v96, v2, v168
	v_cvt_pk_bf16_f32 v96, v96, s0
	v_mul_f32_e32 v97, v3, v169
	v_cvt_pk_bf16_f32 v97, v97, s0
	v_mul_f32_e32 v98, v4, v170
	v_cvt_pk_bf16_f32 v98, v98, s0
	v_mul_f32_e32 v99, v5, v171
	v_cvt_pk_bf16_f32 v99, v99, s0
	ds_write_b16 v19, v96 offset:20
	ds_write_b16 v19, v97 offset:292
	ds_write_b16 v19, v98 offset:564
	ds_write_b16 v19, v99 offset:836
	v_fmamk_f32 v203, v203, 0x3b800000, v216
	v_cmp_gt_f32_e32 vcc, s69, v203
	v_mul_f32_e32 v96, 0x4f800000, v203
	s_nop 0
	v_cndmask_b32_e32 v203, v203, v96, vcc
	v_sqrt_f32_e32 v96, v203
	s_nop 0
	v_add_u32_e32 v97, -1, v96
	v_fma_f32 v98, -v97, v96, v203
	v_cmp_ge_f32_e64 s[0:1], 0, v98
	v_add_u32_e32 v98, 1, v96
	s_nop 0
	v_cndmask_b32_e64 v97, v96, v97, s[0:1]
	v_fma_f32 v96, -v98, v96, v203
	v_cmp_lt_f32_e64 s[0:1], 0, v96
	s_nop 1
	v_cndmask_b32_e64 v96, v97, v98, s[0:1]
	v_mul_f32_e32 v97, 0x37800000, v96
	v_cndmask_b32_e32 v96, v96, v97, vcc
	v_cmp_class_f32_e32 vcc, v203, v217
	s_nop 1
	v_cndmask_b32_e32 v203, v96, v203, vcc
	v_div_scale_f32 v96, s[0:1], v203, v203, 1.0
	v_rcp_f32_e32 v97, v96
	s_nop 0
	v_fma_f32 v98, -v96, v97, 1.0
	v_fmac_f32_e32 v97, v98, v97
	v_div_scale_f32 v98, vcc, 1.0, v203, 1.0
	v_mul_f32_e32 v99, v98, v97
	v_fma_f32 v100, -v96, v99, v98
	v_fmac_f32_e32 v99, v100, v97
	v_fma_f32 v96, -v96, v99, v98
	v_div_fmas_f32 v96, v96, v97, v99
	v_div_fixup_f32 v203, v96, v203, 1.0
	v_mul_f32_e32 v172, v172, v203
	v_mul_f32_e32 v173, v173, v203
	v_mul_f32_e32 v174, v174, v203
	v_mul_f32_e32 v175, v175, v203
	v_mul_f32_e32 v96, v2, v172
	v_cvt_pk_bf16_f32 v96, v96, s0
	v_mul_f32_e32 v97, v3, v173
	v_cvt_pk_bf16_f32 v97, v97, s0
	v_mul_f32_e32 v98, v4, v174
	v_cvt_pk_bf16_f32 v98, v98, s0
	v_mul_f32_e32 v99, v5, v175
	v_cvt_pk_bf16_f32 v99, v99, s0
	ds_write_b16 v19, v96 offset:22
	ds_write_b16 v19, v97 offset:294
	ds_write_b16 v19, v98 offset:566
	ds_write_b16 v19, v99 offset:838
	v_fmamk_f32 v204, v204, 0x3b800000, v216
	v_cmp_gt_f32_e32 vcc, s69, v204
	v_mul_f32_e32 v96, 0x4f800000, v204
	s_nop 0
	v_cndmask_b32_e32 v204, v204, v96, vcc
	v_sqrt_f32_e32 v96, v204
	s_nop 0
	v_add_u32_e32 v97, -1, v96
	v_fma_f32 v98, -v97, v96, v204
	v_cmp_ge_f32_e64 s[0:1], 0, v98
	v_add_u32_e32 v98, 1, v96
	s_nop 0
	v_cndmask_b32_e64 v97, v96, v97, s[0:1]
	v_fma_f32 v96, -v98, v96, v204
	v_cmp_lt_f32_e64 s[0:1], 0, v96
	s_nop 1
	v_cndmask_b32_e64 v96, v97, v98, s[0:1]
	v_mul_f32_e32 v97, 0x37800000, v96
; __device__ __forceinline__ unsigned cvtpk_s(float lo, float hi) { typedef __bf16 bf16x2_t __attribute__((ext_vector_type(2))); f32x2 v = {lo, hi}; bf16x2_t b = __builtin_convertvector(v, bf16x2_t); return __builtin_bit_cast(unsigned, b); }
; __device__ __forceinline__ void sg_unit(const Params& P, int l, int chunk, char* shm, float* ssb) {
;     ...
;         const float rstd = 1.f / sqrtf(wave_sum((sq[0] + sq[1]) + (sq[2] + sq[3])) * (1.f / 256.f) + LN_EPS);
;         v = v * rstd * g4;
; #pragma unroll
;         for (int j = 0; j < 4; ++j) vt[(4 * lane + j) * SG_VT_PITCH + q] = (bf16_t)(at::cvtpk_s(v[j], 0.f) & 0xffffu);
;     }
;     asm volatile("s_waitcnt lgkmcnt(0)\n\ts_barrier" ::: "memory");
;     const int g = wid >> 1, ph = wid & 1, r32 = lane & 31, hi = lane >> 5;
;     ...
;     const bf16_t* Wg = Wsb + (size_t)g * 128 * 128;
; #pragma unroll
;     for (int k0 = 0; k0 < 128; k0 += 16) {
;         bf16x8 af[2], bfr[2];
; #pragma unroll
;         for (int pt = 0; pt < 2; ++pt) af[pt] = *(const bf16x8*)(Wg + (size_t)(64 * ph + 32 * pt + r32) * 128 + k0 + 8 * hi);
; #pragma unroll
;         for (int ct = 0; ct < 2; ++ct) bfr[ct] = *(const bf16x8*)(vt + (64 * g + 32 * ct + r32) * SG_VT_PITCH + k0 + 8 * hi);
	v_cndmask_b32_e32 v96, v96, v97, vcc
	v_cmp_class_f32_e32 vcc, v204, v217
	s_nop 1
	v_cndmask_b32_e32 v204, v96, v204, vcc
	v_div_scale_f32 v96, s[0:1], v204, v204, 1.0
	v_rcp_f32_e32 v97, v96
	s_nop 0
	v_fma_f32 v98, -v96, v97, 1.0
	v_fmac_f32_e32 v97, v98, v97
	v_div_scale_f32 v98, vcc, 1.0, v204, 1.0
	v_mul_f32_e32 v99, v98, v97
	v_fma_f32 v100, -v96, v99, v98
	v_fmac_f32_e32 v99, v100, v97
	v_fma_f32 v96, -v96, v99, v98
	v_div_fmas_f32 v96, v96, v97, v99
	v_div_fixup_f32 v204, v96, v204, 1.0
	v_mul_f32_e32 v176, v176, v204
	v_mul_f32_e32 v177, v177, v204
	v_mul_f32_e32 v178, v178, v204
	v_mul_f32_e32 v179, v179, v204
	v_mul_f32_e32 v96, v2, v176
	v_cvt_pk_bf16_f32 v96, v96, s0
	v_mul_f32_e32 v97, v3, v177
	v_cvt_pk_bf16_f32 v97, v97, s0
	v_mul_f32_e32 v98, v4, v178
	v_cvt_pk_bf16_f32 v98, v98, s0
	v_mul_f32_e32 v99, v5, v179
	v_cvt_pk_bf16_f32 v99, v99, s0
	ds_write_b16 v19, v96 offset:24
	ds_write_b16 v19, v97 offset:296
	ds_write_b16 v19, v98 offset:568
	ds_write_b16 v19, v99 offset:840
	v_fmamk_f32 v205, v205, 0x3b800000, v216
	v_cmp_gt_f32_e32 vcc, s69, v205
	v_mul_f32_e32 v96, 0x4f800000, v205
	s_nop 0
	v_cndmask_b32_e32 v205, v205, v96, vcc
	v_sqrt_f32_e32 v96, v205
	s_nop 0
	v_add_u32_e32 v97, -1, v96
	v_fma_f32 v98, -v97, v96, v205
	v_cmp_ge_f32_e64 s[0:1], 0, v98
	v_add_u32_e32 v98, 1, v96
	s_nop 0
	v_cndmask_b32_e64 v97, v96, v97, s[0:1]
	v_fma_f32 v96, -v98, v96, v205
	v_cmp_lt_f32_e64 s[0:1], 0, v96
	s_nop 1
	v_cndmask_b32_e64 v96, v97, v98, s[0:1]
	v_mul_f32_e32 v97, 0x37800000, v96
	v_cndmask_b32_e32 v96, v96, v97, vcc
	v_cmp_class_f32_e32 vcc, v205, v217
	s_nop 1
	v_cndmask_b32_e32 v205, v96, v205, vcc
	v_div_scale_f32 v96, s[0:1], v205, v205, 1.0
	v_rcp_f32_e32 v97, v96
	s_nop 0
	v_fma_f32 v98, -v96, v97, 1.0
	v_fmac_f32_e32 v97, v98, v97
	v_div_scale_f32 v98, vcc, 1.0, v205, 1.0
	v_mul_f32_e32 v99, v98, v97
	v_fma_f32 v100, -v96, v99, v98
	v_fmac_f32_e32 v99, v100, v97
	v_fma_f32 v96, -v96, v99, v98
	v_div_fmas_f32 v96, v96, v97, v99
	v_div_fixup_f32 v205, v96, v205, 1.0
	v_mul_f32_e32 v180, v180, v205
	v_mul_f32_e32 v181, v181, v205
	v_mul_f32_e32 v182, v182, v205
	v_mul_f32_e32 v183, v183, v205
	v_mul_f32_e32 v96, v2, v180
	v_cvt_pk_bf16_f32 v96, v96, s0
	v_mul_f32_e32 v97, v3, v181
	v_cvt_pk_bf16_f32 v97, v97, s0
	v_mul_f32_e32 v98, v4, v182
	v_cvt_pk_bf16_f32 v98, v98, s0
	v_mul_f32_e32 v99, v5, v183
	v_cvt_pk_bf16_f32 v99, v99, s0
	ds_write_b16 v19, v96 offset:26
	ds_write_b16 v19, v97 offset:298
	ds_write_b16 v19, v98 offset:570
	ds_write_b16 v19, v99 offset:842
	v_fmamk_f32 v206, v206, 0x3b800000, v216
	v_cmp_gt_f32_e32 vcc, s69, v206
	v_mul_f32_e32 v96, 0x4f800000, v206
	s_nop 0
	v_cndmask_b32_e32 v206, v206, v96, vcc
	v_sqrt_f32_e32 v96, v206
	s_nop 0
	v_add_u32_e32 v97, -1, v96
	v_fma_f32 v98, -v97, v96, v206
	v_cmp_ge_f32_e64 s[0:1], 0, v98
	v_add_u32_e32 v98, 1, v96
	s_nop 0
	v_cndmask_b32_e64 v97, v96, v97, s[0:1]
	v_fma_f32 v96, -v98, v96, v206
	v_cmp_lt_f32_e64 s[0:1], 0, v96
	s_nop 1
	v_cndmask_b32_e64 v96, v97, v98, s[0:1]
	v_mul_f32_e32 v97, 0x37800000, v96
	v_cndmask_b32_e32 v96, v96, v97, vcc
	v_cmp_class_f32_e32 vcc, v206, v217
	s_nop 1
	v_cndmask_b32_e32 v206, v96, v206, vcc
	v_div_scale_f32 v96, s[0:1], v206, v206, 1.0
	v_rcp_f32_e32 v97, v96
	s_nop 0
	v_fma_f32 v98, -v96, v97, 1.0
	v_fmac_f32_e32 v97, v98, v97
	v_div_scale_f32 v98, vcc, 1.0, v206, 1.0
	v_mul_f32_e32 v99, v98, v97
	v_fma_f32 v100, -v96, v99, v98
	v_fmac_f32_e32 v99, v100, v97
	v_fma_f32 v96, -v96, v99, v98
	v_div_fmas_f32 v96, v96, v97, v99
	v_div_fixup_f32 v206, v96, v206, 1.0
	v_mul_f32_e32 v184, v184, v206
	v_mul_f32_e32 v185, v185, v206
	v_mul_f32_e32 v186, v186, v206
	v_mul_f32_e32 v187, v187, v206
	v_mul_f32_e32 v96, v2, v184
	v_cvt_pk_bf16_f32 v96, v96, s0
	v_mul_f32_e32 v97, v3, v185
	v_cvt_pk_bf16_f32 v97, v97, s0
	v_mul_f32_e32 v98, v4, v186
	v_cvt_pk_bf16_f32 v98, v98, s0
	v_mul_f32_e32 v99, v5, v187
	v_cvt_pk_bf16_f32 v99, v99, s0
	ds_write_b16 v19, v96 offset:28
	ds_write_b16 v19, v97 offset:300
	ds_write_b16 v19, v98 offset:572
	ds_write_b16 v19, v99 offset:844
	v_fmamk_f32 v207, v207, 0x3b800000, v216
	v_cmp_gt_f32_e32 vcc, s69, v207
	v_mul_f32_e32 v96, 0x4f800000, v207
	s_nop 0
	v_cndmask_b32_e32 v207, v207, v96, vcc
	v_sqrt_f32_e32 v96, v207
	s_nop 0
	v_add_u32_e32 v97, -1, v96
	v_fma_f32 v98, -v97, v96, v207
	v_cmp_ge_f32_e64 s[0:1], 0, v98
	v_add_u32_e32 v98, 1, v96
	s_nop 0
	v_cndmask_b32_e64 v97, v96, v97, s[0:1]
	v_fma_f32 v96, -v98, v96, v207
	v_cmp_lt_f32_e64 s[0:1], 0, v96
	s_nop 1
	v_cndmask_b32_e64 v96, v97, v98, s[0:1]
	v_mul_f32_e32 v97, 0x37800000, v96
	v_cndmask_b32_e32 v96, v96, v97, vcc
	v_cmp_class_f32_e32 vcc, v207, v217
	s_nop 1
	v_cndmask_b32_e32 v207, v96, v207, vcc
	v_div_scale_f32 v96, s[0:1], v207, v207, 1.0
	v_rcp_f32_e32 v97, v96
	s_nop 0
	v_fma_f32 v98, -v96, v97, 1.0
	v_fmac_f32_e32 v97, v98, v97
	v_div_scale_f32 v98, vcc, 1.0, v207, 1.0
	v_mul_f32_e32 v99, v98, v97
	v_fma_f32 v100, -v96, v99, v98
	v_fmac_f32_e32 v99, v100, v97
	v_fma_f32 v96, -v96, v99, v98
	v_div_fmas_f32 v96, v96, v97, v99
	v_div_fixup_f32 v207, v96, v207, 1.0
	v_mul_f32_e32 v188, v188, v207
	v_mul_f32_e32 v189, v189, v207
	v_mul_f32_e32 v190, v190, v207
	v_mul_f32_e32 v191, v191, v207
	v_mul_f32_e32 v96, v2, v188
	v_cvt_pk_bf16_f32 v96, v96, s0
	v_mul_f32_e32 v97, v3, v189
	v_cvt_pk_bf16_f32 v97, v97, s0
	v_mul_f32_e32 v98, v4, v190
	v_cvt_pk_bf16_f32 v98, v98, s0
	v_mul_f32_e32 v99, v5, v191
	v_cvt_pk_bf16_f32 v99, v99, s0
	ds_write_b16 v19, v96 offset:30
	ds_write_b16 v19, v97 offset:302
	ds_write_b16 v19, v98 offset:574
	ds_write_b16 v19, v99 offset:846
	s_lshl_b32 s7, s3, 7
	s_add_u32 s10, s4, 0x200000
	s_addc_u32 s11, s5, 0
	s_ashr_i32 s4, s6, 7
	s_ashr_i32 s5, s4, 31
	s_bfe_u32 s1, s6, 0x10006
	s_lshl_b64 s[8:9], s[4:5], 15
	v_readlane_b32 s0, v252, 20
	v_and_b32_e32 v14, 31, v12
	v_lshrrev_b32_e32 v15, 5, v13
	s_add_u32 s8, s0, s8
	v_readlane_b32 s0, v252, 21
	s_addc_u32 s9, s0, s9
	v_lshlrev_b32_e32 v0, 4, v15
	v_lshlrev_b32_e32 v2, 8, v14
	v_lshl_add_u64 v[4:5], s[8:9], 0, v[0:1]
	v_lshl_or_b32 v10, s1, 14, v2
	v_mov_b32_e32 v11, v1
	s_waitcnt lgkmcnt(0)
	s_barrier
; __device__ __forceinline__ void sg_unit(const Params& P, int l, int chunk, char* shm, float* ssb) {
;     ...
;     const bf16_t* Wg = Wsb + (size_t)g * 128 * 128;
; #pragma unroll
;     for (int k0 = 0; k0 < 128; k0 += 16) {
;         bf16x8 af[2], bfr[2];
; #pragma unroll
;         for (int pt = 0; pt < 2; ++pt) af[pt] = *(const bf16x8*)(Wg + (size_t)(64 * ph + 32 * pt + r32) * 128 + k0 + 8 * hi);
; #pragma unroll
;         for (int ct = 0; ct < 2; ++ct) bfr[ct] = *(const bf16x8*)(vt + (64 * g + 32 * ct + r32) * SG_VT_PITCH + k0 + 8 * hi);
; #pragma unroll
;         for (int pt = 0; pt < 2; ++pt)
; #pragma unroll
;             for (int ct = 0; ct < 2; ++ct) acc[pt][ct] = __builtin_amdgcn_mfma_f32_32x32x16_bf16(af[pt], bfr[ct], acc[pt][ct], 0, 0, 0);
;     }
	v_lshl_add_u64 v[2:3], v[4:5], 0, v[10:11]
	v_or_b32_e32 v10, 0x2000, v10
	v_lshl_add_u64 v[4:5], v[4:5], 0, v[10:11]
	global_load_dwordx4 v[96:99], v[2:3], off
	global_load_dwordx4 v[100:103], v[4:5], off
	global_load_dwordx4 v[104:107], v[2:3], off offset:32
	global_load_dwordx4 v[108:111], v[4:5], off offset:32
	global_load_dwordx4 v[112:115], v[2:3], off offset:64
	global_load_dwordx4 v[116:119], v[4:5], off offset:64
	global_load_dwordx4 v[120:123], v[2:3], off offset:96
	global_load_dwordx4 v[124:127], v[4:5], off offset:96
	global_load_dwordx4 v[128:131], v[2:3], off offset:128
	global_load_dwordx4 v[132:135], v[4:5], off offset:128
	global_load_dwordx4 v[136:139], v[2:3], off offset:160
	global_load_dwordx4 v[140:143], v[4:5], off offset:160
	global_load_dwordx4 v[144:147], v[2:3], off offset:192
	global_load_dwordx4 v[148:151], v[4:5], off offset:192
	global_load_dwordx4 v[152:155], v[2:3], off offset:224
	global_load_dwordx4 v[156:159], v[4:5], off offset:224
	s_lshl_b32 s0, s4, 6
	v_or_b32_e32 v22, s0, v14
	s_movk_i32 s4, 0x110
	v_mul_lo_u32 v10, v22, s4
	v_add3_u32 v0, 0, v0, v10
	ds_read_b128 v[22:25], v0 offset:8704
	ds_read_b128 v[26:29], v0
	ds_read_b128 v[84:87], v0 offset:32
	s_and_b32 s4, s6, 0xffffff80
	s_ashr_i32 s5, s4, 31
	s_lshl_b64 s[4:5], s[4:5], 2
	v_readlane_b32 s6, v252, 22
	s_add_u32 s4, s6, s4
	v_readlane_b32 s6, v252, 23
	s_addc_u32 s5, s6, s5
	s_lshl_b32 s6, s1, 6
	s_or_b32 s86, s6, s7
	s_ashr_i32 s1, s0, 31
	s_lshl_b32 s2, s2, 12
	s_add_i32 s2, s2, 0
	s_lshl_b64 s[0:1], s[0:1], 1
	s_add_i32 s2, s2, 0x12000
	v_lshlrev_b32_e32 v10, 1, v14
	s_waitcnt lgkmcnt(1)
	s_waitcnt vmcnt(0)
	v_mfma_f32_32x32x16_bf16 v[66:81], v[96:99], v[26:29], 0
	v_mfma_f32_32x32x16_bf16 v[50:65], v[96:99], v[22:25], 0
	ds_read_b128 v[92:95], v0 offset:8736
	v_mfma_f32_32x32x16_bf16 v[34:49], v[100:103], v[26:29], 0
	v_mfma_f32_32x32x16_bf16 v[18:33], v[100:103], v[22:25], 0
	s_waitcnt lgkmcnt(1)
	v_mfma_f32_32x32x16_bf16 v[66:81], v[104:107], v[84:87], v[66:81]
	s_waitcnt lgkmcnt(0)
	v_mfma_f32_32x32x16_bf16 v[50:65], v[104:107], v[92:95], v[50:65]
	v_mfma_f32_32x32x16_bf16 v[34:49], v[108:111], v[84:87], v[34:49]
	v_mfma_f32_32x32x16_bf16 v[18:33], v[108:111], v[92:95], v[18:33]
	ds_read_b128 v[88:91], v0 offset:64
	ds_read_b128 v[92:95], v0 offset:8768
	s_waitcnt lgkmcnt(1)
	v_mfma_f32_32x32x16_bf16 v[66:81], v[112:115], v[88:91], v[66:81]
	s_waitcnt lgkmcnt(0)
	v_mfma_f32_32x32x16_bf16 v[50:65], v[112:115], v[92:95], v[50:65]
	v_mfma_f32_32x32x16_bf16 v[34:49], v[116:119], v[88:91], v[34:49]
	v_mfma_f32_32x32x16_bf16 v[18:33], v[116:119], v[92:95], v[18:33]
	ds_read_b128 v[88:91], v0 offset:96
	ds_read_b128 v[92:95], v0 offset:8800
	s_waitcnt lgkmcnt(1)
	v_mfma_f32_32x32x16_bf16 v[66:81], v[120:123], v[88:91], v[66:81]
	s_waitcnt lgkmcnt(0)
	v_mfma_f32_32x32x16_bf16 v[50:65], v[120:123], v[92:95], v[50:65]
	v_mfma_f32_32x32x16_bf16 v[34:49], v[124:127], v[88:91], v[34:49]
	v_mfma_f32_32x32x16_bf16 v[18:33], v[124:127], v[92:95], v[18:33]
	ds_read_b128 v[88:91], v0 offset:128
	ds_read_b128 v[92:95], v0 offset:8832
	s_waitcnt lgkmcnt(1)
	v_mfma_f32_32x32x16_bf16 v[66:81], v[128:131], v[88:91], v[66:81]
	s_waitcnt lgkmcnt(0)
	v_mfma_f32_32x32x16_bf16 v[50:65], v[128:131], v[92:95], v[50:65]
	v_mfma_f32_32x32x16_bf16 v[34:49], v[132:135], v[88:91], v[34:49]
	v_mfma_f32_32x32x16_bf16 v[18:33], v[132:135], v[92:95], v[18:33]
	ds_read_b128 v[88:91], v0 offset:160
	ds_read_b128 v[92:95], v0 offset:8864
	s_waitcnt lgkmcnt(1)
	v_mfma_f32_32x32x16_bf16 v[66:81], v[136:139], v[88:91], v[66:81]
	s_waitcnt lgkmcnt(0)
	v_mfma_f32_32x32x16_bf16 v[50:65], v[136:139], v[92:95], v[50:65]
	v_mfma_f32_32x32x16_bf16 v[34:49], v[140:143], v[88:91], v[34:49]
	v_mfma_f32_32x32x16_bf16 v[18:33], v[140:143], v[92:95], v[18:33]
	ds_read_b128 v[88:91], v0 offset:192
	ds_read_b128 v[92:95], v0 offset:8896
	s_waitcnt lgkmcnt(1)
	v_mfma_f32_32x32x16_bf16 v[66:81], v[144:147], v[88:91], v[66:81]
	s_waitcnt lgkmcnt(0)
	v_mfma_f32_32x32x16_bf16 v[50:65], v[144:147], v[92:95], v[50:65]
	s_nop 0
	v_mfma_f32_32x32x16_bf16 v[34:49], v[148:151], v[88:91], v[34:49]
	v_mfma_f32_32x32x16_bf16 v[18:33], v[148:151], v[92:95], v[18:33]
	ds_read_b128 v[84:87], v0 offset:224
	ds_read_b128 v[88:91], v0 offset:8928
	v_lshl_or_b32 v0, v15, 2, s6
	s_waitcnt lgkmcnt(1)
	v_mfma_f32_32x32x16_bf16 v[66:81], v[152:155], v[84:87], v[66:81]
	v_mfma_f32_32x32x16_bf16 v[34:49], v[156:159], v[84:87], v[34:49]
	v_or_b32_e32 v86, s7, v0
	v_readlane_b32 s6, v254, 8
	v_and_b32_e32 v87, 7, v12
	v_lshlrev_b32_e32 v12, 2, v0
	v_mul_lo_u32 v0, v86, s80
	v_readlane_b32 s7, v254, 9
	v_lshlrev_b32_e32 v14, 4, v87
	s_waitcnt lgkmcnt(0)
; __device__ __forceinline__ float bf2f(unsigned short h) { return __uint_as_float(((unsigned)h) << 16); }
; __device__ __forceinline__ int crow(int r, int hi) { return (r & 3) + 8 * (r >> 2) + 4 * hi; }
; __device__ __forceinline__ void sg_unit(const Params& P, int l, int chunk, char* shm, float* ssb) {
;     ...
;     const float* bs = P.b_s + (size_t)l * 512 + g * 128;
;     float ones[16];
; #pragma unroll
;     for (int r = 0; r < 16; ++r) ones[r] = 1.0f;
; #pragma unroll
;     for (int pt = 0; pt < 2; ++pt) {
;         f32x16 o[2];
; #pragma unroll
;         for (int r = 0; r < 16; ++r) { const int p = 64 * ph + 32 * pt + at::crow(r, hi); const float bp = bs[p];
; #pragma unroll
;             for (int ct = 0; ct < 2; ++ct) { const float uu = bf2f(qkv[(size_t)(R0 + p) * DIN + C_U + 64 * g + 32 * ct + r32]); o[ct][r] = uu * (acc[pt][ct][r] + bp); } }
	v_mfma_f32_32x32x16_bf16 v[50:65], v[152:155], v[88:91], v[50:65]
	v_mov_b32_e32 v9, v1
	v_cmp_eq_u32_e32 vcc, 0, v87
	v_mov_b32_e32 v7, v1
	v_mfma_f32_32x32x16_bf16 v[18:33], v[156:159], v[88:91], v[18:33]
	v_lshl_add_u64 v[90:91], s[6:7], 0, v[0:1]
	v_lshlrev_b32_e32 v2, 9, v15
	v_lshrrev_b32_e32 v89, 3, v13
	v_lshl_add_u64 v[90:91], v[90:91], 0, s[0:1]
	v_add3_u32 v85, s2, v2, v10
	v_add_u32_e32 v88, s2, v14
	v_lshlrev_b32_e32 v2, 7, v89
	v_lshl_add_u64 v[90:91], v[90:91], 0, v[10:11]
	v_add_u32_e32 v84, v88, v2
	v_mov_b32_e32 v192, v10
	v_mov_b32_e32 v193, v1
	global_load_dwordx4 v[160:163], v12, s[4:5]
	global_load_dwordx4 v[164:167], v12, s[4:5] offset:32
	global_load_dwordx4 v[168:171], v12, s[4:5] offset:64
	global_load_dwordx4 v[172:175], v12, s[4:5] offset:96
	global_load_dwordx4 v[176:179], v12, s[4:5] offset:128
	global_load_dwordx4 v[180:183], v12, s[4:5] offset:160
	global_load_dwordx4 v[184:187], v12, s[4:5] offset:192
	global_load_dwordx4 v[188:191], v12, s[4:5] offset:224
	v_or_b32_e32 v194, 0, v86
	v_mul_lo_u32 v194, v194, s80
	v_mov_b32_e32 v195, v1
	v_lshl_add_u64 v[194:195], s[6:7], 0, v[194:195]
	v_lshl_add_u64 v[194:195], v[194:195], 0, s[0:1]
	v_lshl_add_u64 v[194:195], v[194:195], 0, v[192:193]
	global_load_ushort v96, v[194:195], off offset:1024
	global_load_ushort v97, v[194:195], off offset:1088
	v_or_b32_e32 v196, 1, v86
	v_mul_lo_u32 v196, v196, s80
	v_mov_b32_e32 v197, v1
	v_lshl_add_u64 v[196:197], s[6:7], 0, v[196:197]
	v_lshl_add_u64 v[196:197], v[196:197], 0, s[0:1]
	v_lshl_add_u64 v[196:197], v[196:197], 0, v[192:193]
	global_load_ushort v98, v[196:197], off offset:1024
	global_load_ushort v99, v[196:197], off offset:1088
	v_or_b32_e32 v194, 2, v86
	v_mul_lo_u32 v194, v194, s80
	v_mov_b32_e32 v195, v1
	v_lshl_add_u64 v[194:195], s[6:7], 0, v[194:195]
	v_lshl_add_u64 v[194:195], v[194:195], 0, s[0:1]
	v_lshl_add_u64 v[194:195], v[194:195], 0, v[192:193]
	global_load_ushort v100, v[194:195], off offset:1024
	global_load_ushort v101, v[194:195], off offset:1088
	v_or_b32_e32 v196, 3, v86
	v_mul_lo_u32 v196, v196, s80
	v_mov_b32_e32 v197, v1
	v_lshl_add_u64 v[196:197], s[6:7], 0, v[196:197]
	v_lshl_add_u64 v[196:197], v[196:197], 0, s[0:1]
	v_lshl_add_u64 v[196:197], v[196:197], 0, v[192:193]
	global_load_ushort v102, v[196:197], off offset:1024
	global_load_ushort v103, v[196:197], off offset:1088
	v_or_b32_e32 v194, 8, v86
	v_mul_lo_u32 v194, v194, s80
	v_mov_b32_e32 v195, v1
	v_lshl_add_u64 v[194:195], s[6:7], 0, v[194:195]
	v_lshl_add_u64 v[194:195], v[194:195], 0, s[0:1]
	v_lshl_add_u64 v[194:195], v[194:195], 0, v[192:193]
	global_load_ushort v104, v[194:195], off offset:1024
	global_load_ushort v105, v[194:195], off offset:1088
	v_or_b32_e32 v196, 9, v86
	v_mul_lo_u32 v196, v196, s80
	v_mov_b32_e32 v197, v1
	v_lshl_add_u64 v[196:197], s[6:7], 0, v[196:197]
	v_lshl_add_u64 v[196:197], v[196:197], 0, s[0:1]
	v_lshl_add_u64 v[196:197], v[196:197], 0, v[192:193]
	global_load_ushort v106, v[196:197], off offset:1024
	global_load_ushort v107, v[196:197], off offset:1088
	v_or_b32_e32 v194, 10, v86
	v_mul_lo_u32 v194, v194, s80
	v_mov_b32_e32 v195, v1
	v_lshl_add_u64 v[194:195], s[6:7], 0, v[194:195]
	v_lshl_add_u64 v[194:195], v[194:195], 0, s[0:1]
	v_lshl_add_u64 v[194:195], v[194:195], 0, v[192:193]
	global_load_ushort v108, v[194:195], off offset:1024
	global_load_ushort v109, v[194:195], off offset:1088
	v_or_b32_e32 v196, 11, v86
	v_mul_lo_u32 v196, v196, s80
	v_mov_b32_e32 v197, v1
	v_lshl_add_u64 v[196:197], s[6:7], 0, v[196:197]
	v_lshl_add_u64 v[196:197], v[196:197], 0, s[0:1]
	v_lshl_add_u64 v[196:197], v[196:197], 0, v[192:193]
	global_load_ushort v110, v[196:197], off offset:1024
	global_load_ushort v111, v[196:197], off offset:1088
	v_or_b32_e32 v194, 16, v86
	v_mul_lo_u32 v194, v194, s80
	v_mov_b32_e32 v195, v1
	v_lshl_add_u64 v[194:195], s[6:7], 0, v[194:195]
	v_lshl_add_u64 v[194:195], v[194:195], 0, s[0:1]
	v_lshl_add_u64 v[194:195], v[194:195], 0, v[192:193]
	global_load_ushort v112, v[194:195], off offset:1024
	global_load_ushort v113, v[194:195], off offset:1088
	v_or_b32_e32 v196, 17, v86
	v_mul_lo_u32 v196, v196, s80
	v_mov_b32_e32 v197, v1
	v_lshl_add_u64 v[196:197], s[6:7], 0, v[196:197]
	v_lshl_add_u64 v[196:197], v[196:197], 0, s[0:1]
	v_lshl_add_u64 v[196:197], v[196:197], 0, v[192:193]
	global_load_ushort v114, v[196:197], off offset:1024
	global_load_ushort v115, v[196:197], off offset:1088
	v_or_b32_e32 v194, 18, v86
	v_mul_lo_u32 v194, v194, s80
	v_mov_b32_e32 v195, v1
	v_lshl_add_u64 v[194:195], s[6:7], 0, v[194:195]
	v_lshl_add_u64 v[194:195], v[194:195], 0, s[0:1]
	v_lshl_add_u64 v[194:195], v[194:195], 0, v[192:193]
	global_load_ushort v116, v[194:195], off offset:1024
	global_load_ushort v117, v[194:195], off offset:1088
	v_or_b32_e32 v196, 19, v86
	v_mul_lo_u32 v196, v196, s80
	v_mov_b32_e32 v197, v1
	v_lshl_add_u64 v[196:197], s[6:7], 0, v[196:197]
	v_lshl_add_u64 v[196:197], v[196:197], 0, s[0:1]
	v_lshl_add_u64 v[196:197], v[196:197], 0, v[192:193]
	global_load_ushort v118, v[196:197], off offset:1024
	global_load_ushort v119, v[196:197], off offset:1088
	v_or_b32_e32 v194, 24, v86
	v_mul_lo_u32 v194, v194, s80
	v_mov_b32_e32 v195, v1
	v_lshl_add_u64 v[194:195], s[6:7], 0, v[194:195]
	v_lshl_add_u64 v[194:195], v[194:195], 0, s[0:1]
	v_lshl_add_u64 v[194:195], v[194:195], 0, v[192:193]
	global_load_ushort v120, v[194:195], off offset:1024
	global_load_ushort v121, v[194:195], off offset:1088
	v_or_b32_e32 v196, 25, v86
	v_mul_lo_u32 v196, v196, s80
	v_mov_b32_e32 v197, v1
	v_lshl_add_u64 v[196:197], s[6:7], 0, v[196:197]
	v_lshl_add_u64 v[196:197], v[196:197], 0, s[0:1]
; __device__ __forceinline__ float bf2f(unsigned short h) { return __uint_as_float(((unsigned)h) << 16); }
; __device__ __forceinline__ int crow(int r, int hi) { return (r & 3) + 8 * (r >> 2) + 4 * hi; }
; __device__ __forceinline__ void sg_unit(const Params& P, int l, int chunk, char* shm, float* ssb) {
;     ...
;         for (int r = 0; r < 16; ++r) { const int p = 64 * ph + 32 * pt + at::crow(r, hi); const float bp = bs[p];
; #pragma unroll
;             for (int ct = 0; ct < 2; ++ct) { const float uu = bf2f(qkv[(size_t)(R0 + p) * DIN + C_U + 64 * g + 32 * ct + r32]); o[ct][r] = uu * (acc[pt][ct][r] + bp); } }
	v_lshl_add_u64 v[196:197], v[196:197], 0, v[192:193]
	global_load_ushort v122, v[196:197], off offset:1024
	global_load_ushort v123, v[196:197], off offset:1088
	v_or_b32_e32 v194, 26, v86
	v_mul_lo_u32 v194, v194, s80
	v_mov_b32_e32 v195, v1
	v_lshl_add_u64 v[194:195], s[6:7], 0, v[194:195]
	v_lshl_add_u64 v[194:195], v[194:195], 0, s[0:1]
	v_lshl_add_u64 v[194:195], v[194:195], 0, v[192:193]
	global_load_ushort v124, v[194:195], off offset:1024
	global_load_ushort v125, v[194:195], off offset:1088
	v_or_b32_e32 v196, 27, v86
	v_mul_lo_u32 v196, v196, s80
	v_mov_b32_e32 v197, v1
	v_lshl_add_u64 v[196:197], s[6:7], 0, v[196:197]
	v_lshl_add_u64 v[196:197], v[196:197], 0, s[0:1]
	v_lshl_add_u64 v[196:197], v[196:197], 0, v[192:193]
	global_load_ushort v126, v[196:197], off offset:1024
	global_load_ushort v127, v[196:197], off offset:1088
	v_or_b32_e32 v194, 32, v86
	v_mul_lo_u32 v194, v194, s80
	v_mov_b32_e32 v195, v1
	v_lshl_add_u64 v[194:195], s[6:7], 0, v[194:195]
	v_lshl_add_u64 v[194:195], v[194:195], 0, s[0:1]
	v_lshl_add_u64 v[194:195], v[194:195], 0, v[192:193]
	global_load_ushort v128, v[194:195], off offset:1024
	global_load_ushort v129, v[194:195], off offset:1088
	v_or_b32_e32 v196, 33, v86
	v_mul_lo_u32 v196, v196, s80
	v_mov_b32_e32 v197, v1
	v_lshl_add_u64 v[196:197], s[6:7], 0, v[196:197]
	v_lshl_add_u64 v[196:197], v[196:197], 0, s[0:1]
	v_lshl_add_u64 v[196:197], v[196:197], 0, v[192:193]
	global_load_ushort v130, v[196:197], off offset:1024
	global_load_ushort v131, v[196:197], off offset:1088
	v_or_b32_e32 v194, 34, v86
	v_mul_lo_u32 v194, v194, s80
	v_mov_b32_e32 v195, v1
	v_lshl_add_u64 v[194:195], s[6:7], 0, v[194:195]
	v_lshl_add_u64 v[194:195], v[194:195], 0, s[0:1]
	v_lshl_add_u64 v[194:195], v[194:195], 0, v[192:193]
	global_load_ushort v132, v[194:195], off offset:1024
	global_load_ushort v133, v[194:195], off offset:1088
	v_or_b32_e32 v196, 35, v86
	v_mul_lo_u32 v196, v196, s80
	v_mov_b32_e32 v197, v1
	v_lshl_add_u64 v[196:197], s[6:7], 0, v[196:197]
	v_lshl_add_u64 v[196:197], v[196:197], 0, s[0:1]
	v_lshl_add_u64 v[196:197], v[196:197], 0, v[192:193]
	global_load_ushort v134, v[196:197], off offset:1024
	global_load_ushort v135, v[196:197], off offset:1088
	v_or_b32_e32 v194, 40, v86
	v_mul_lo_u32 v194, v194, s80
	v_mov_b32_e32 v195, v1
	v_lshl_add_u64 v[194:195], s[6:7], 0, v[194:195]
	v_lshl_add_u64 v[194:195], v[194:195], 0, s[0:1]
	v_lshl_add_u64 v[194:195], v[194:195], 0, v[192:193]
	global_load_ushort v136, v[194:195], off offset:1024
	global_load_ushort v137, v[194:195], off offset:1088
	v_or_b32_e32 v196, 41, v86
	v_mul_lo_u32 v196, v196, s80
	v_mov_b32_e32 v197, v1
	v_lshl_add_u64 v[196:197], s[6:7], 0, v[196:197]
	v_lshl_add_u64 v[196:197], v[196:197], 0, s[0:1]
	v_lshl_add_u64 v[196:197], v[196:197], 0, v[192:193]
	global_load_ushort v138, v[196:197], off offset:1024
	global_load_ushort v139, v[196:197], off offset:1088
	v_or_b32_e32 v194, 42, v86
	v_mul_lo_u32 v194, v194, s80
	v_mov_b32_e32 v195, v1
	v_lshl_add_u64 v[194:195], s[6:7], 0, v[194:195]
	v_lshl_add_u64 v[194:195], v[194:195], 0, s[0:1]
	v_lshl_add_u64 v[194:195], v[194:195], 0, v[192:193]
	global_load_ushort v140, v[194:195], off offset:1024
	global_load_ushort v141, v[194:195], off offset:1088
	v_or_b32_e32 v196, 43, v86
	v_mul_lo_u32 v196, v196, s80
	v_mov_b32_e32 v197, v1
	v_lshl_add_u64 v[196:197], s[6:7], 0, v[196:197]
	v_lshl_add_u64 v[196:197], v[196:197], 0, s[0:1]
	v_lshl_add_u64 v[196:197], v[196:197], 0, v[192:193]
	global_load_ushort v142, v[196:197], off offset:1024
	global_load_ushort v143, v[196:197], off offset:1088
	v_or_b32_e32 v194, 48, v86
	v_mul_lo_u32 v194, v194, s80
	v_mov_b32_e32 v195, v1
	v_lshl_add_u64 v[194:195], s[6:7], 0, v[194:195]
	v_lshl_add_u64 v[194:195], v[194:195], 0, s[0:1]
	v_lshl_add_u64 v[194:195], v[194:195], 0, v[192:193]
	global_load_ushort v144, v[194:195], off offset:1024
	global_load_ushort v145, v[194:195], off offset:1088
	v_or_b32_e32 v196, 49, v86
	v_mul_lo_u32 v196, v196, s80
	v_mov_b32_e32 v197, v1
	v_lshl_add_u64 v[196:197], s[6:7], 0, v[196:197]
	v_lshl_add_u64 v[196:197], v[196:197], 0, s[0:1]
	v_lshl_add_u64 v[196:197], v[196:197], 0, v[192:193]
	global_load_ushort v146, v[196:197], off offset:1024
	global_load_ushort v147, v[196:197], off offset:1088
	v_or_b32_e32 v194, 50, v86
	v_mul_lo_u32 v194, v194, s80
	v_mov_b32_e32 v195, v1
	v_lshl_add_u64 v[194:195], s[6:7], 0, v[194:195]
	v_lshl_add_u64 v[194:195], v[194:195], 0, s[0:1]
	v_lshl_add_u64 v[194:195], v[194:195], 0, v[192:193]
	global_load_ushort v148, v[194:195], off offset:1024
	global_load_ushort v149, v[194:195], off offset:1088
	v_or_b32_e32 v196, 51, v86
	v_mul_lo_u32 v196, v196, s80
	v_mov_b32_e32 v197, v1
	v_lshl_add_u64 v[196:197], s[6:7], 0, v[196:197]
	v_lshl_add_u64 v[196:197], v[196:197], 0, s[0:1]
	v_lshl_add_u64 v[196:197], v[196:197], 0, v[192:193]
	global_load_ushort v150, v[196:197], off offset:1024
	global_load_ushort v151, v[196:197], off offset:1088
	v_or_b32_e32 v194, 56, v86
	v_mul_lo_u32 v194, v194, s80
	v_mov_b32_e32 v195, v1
	v_lshl_add_u64 v[194:195], s[6:7], 0, v[194:195]
	v_lshl_add_u64 v[194:195], v[194:195], 0, s[0:1]
	v_lshl_add_u64 v[194:195], v[194:195], 0, v[192:193]
	global_load_ushort v152, v[194:195], off offset:1024
	global_load_ushort v153, v[194:195], off offset:1088
	v_or_b32_e32 v196, 57, v86
	v_mul_lo_u32 v196, v196, s80
	v_mov_b32_e32 v197, v1
	v_lshl_add_u64 v[196:197], s[6:7], 0, v[196:197]
	v_lshl_add_u64 v[196:197], v[196:197], 0, s[0:1]
	v_lshl_add_u64 v[196:197], v[196:197], 0, v[192:193]
	global_load_ushort v154, v[196:197], off offset:1024
	global_load_ushort v155, v[196:197], off offset:1088
	v_or_b32_e32 v194, 58, v86
	v_mul_lo_u32 v194, v194, s80
	v_mov_b32_e32 v195, v1
	v_lshl_add_u64 v[194:195], s[6:7], 0, v[194:195]
	v_lshl_add_u64 v[194:195], v[194:195], 0, s[0:1]
	v_lshl_add_u64 v[194:195], v[194:195], 0, v[192:193]
	global_load_ushort v156, v[194:195], off offset:1024
	global_load_ushort v157, v[194:195], off offset:1088
	v_or_b32_e32 v196, 59, v86
	v_mul_lo_u32 v196, v196, s80
	v_mov_b32_e32 v197, v1
	v_lshl_add_u64 v[196:197], s[6:7], 0, v[196:197]
	v_lshl_add_u64 v[196:197], v[196:197], 0, s[0:1]
	v_lshl_add_u64 v[196:197], v[196:197], 0, v[192:193]
	global_load_ushort v158, v[196:197], off offset:1024
	global_load_ushort v159, v[196:197], off offset:1088
	s_waitcnt vmcnt(0)
; __device__ __forceinline__ float bf2f(unsigned short h) { return __uint_as_float(((unsigned)h) << 16); }
; __device__ __forceinline__ int crow(int r, int hi) { return (r & 3) + 8 * (r >> 2) + 4 * hi; }
; __device__ __forceinline__ void sg_unit(const Params& P, int l, int chunk, char* shm, float* ssb) {
;     ...
;     for (int pt = 0; pt < 2; ++pt) {
;         f32x16 o[2];
; #pragma unroll
;         for (int r = 0; r < 16; ++r) { const int p = 64 * ph + 32 * pt + at::crow(r, hi); const float bp = bs[p];
; #pragma unroll
;             for (int ct = 0; ct < 2; ++ct) { const float uu = bf2f(qkv[(size_t)(R0 + p) * DIN + C_U + 64 * g + 32 * ct + r32]); o[ct][r] = uu * (acc[pt][ct][r] + bp); } }
	v_mov_b64_e32 v[2:3], v[160:161]
	v_mov_b64_e32 v[4:5], v[162:163]
	v_mov_b32_e32 v0, v96
	v_lshlrev_b32_e32 v8, 11, v89
	v_lshlrev_b32_e32 v6, 4, v89
	v_add_f32_e32 v13, v66, v2
	v_lshlrev_b32_e32 v0, 16, v0
	v_mul_f32_e32 v13, v13, v0
	v_mov_b32_e32 v0, v97
	v_add_f32_e32 v2, v50, v2
	v_add_f32_e32 v66, v68, v4
	v_lshlrev_b32_e32 v0, 16, v0
	v_mul_f32_e32 v15, v2, v0
	v_or_b32_e32 v0, 1, v86
	v_mul_lo_u32 v0, v0, s80
	v_lshl_add_u64 v[90:91], s[6:7], 0, v[0:1]
	v_lshl_add_u64 v[90:91], v[90:91], 0, s[0:1]
	v_lshl_add_u64 v[90:91], v[90:91], 0, v[10:11]
	v_mov_b32_e32 v0, v98
	v_add_f32_e32 v2, v67, v3
	v_lshlrev_b32_e32 v0, 16, v0
	v_mul_f32_e32 v50, v2, v0
	v_mov_b32_e32 v0, v99
	v_add_f32_e32 v2, v51, v3
	v_lshlrev_b32_e32 v0, 16, v0
	v_mul_f32_e32 v51, v2, v0
	v_or_b32_e32 v0, 2, v86
	v_mul_lo_u32 v0, v0, s80
	v_lshl_add_u64 v[2:3], s[6:7], 0, v[0:1]
	v_lshl_add_u64 v[2:3], v[2:3], 0, s[0:1]
	v_lshl_add_u64 v[2:3], v[2:3], 0, v[10:11]
	v_mov_b32_e32 v0, v100
	v_lshlrev_b32_e32 v0, 16, v0
	v_mul_f32_e32 v66, v66, v0
	v_mov_b32_e32 v0, v101
	v_add_f32_e32 v2, v52, v4
	v_add_f32_e32 v4, v69, v5
	v_lshlrev_b32_e32 v0, 16, v0
	v_mul_f32_e32 v52, v2, v0
	v_or_b32_e32 v0, 3, v86
	v_mul_lo_u32 v0, v0, s80
	v_lshl_add_u64 v[2:3], s[6:7], 0, v[0:1]
	v_lshl_add_u64 v[2:3], v[2:3], 0, s[0:1]
	v_lshl_add_u64 v[2:3], v[2:3], 0, v[10:11]
	v_mov_b32_e32 v0, v102
	v_lshlrev_b32_e32 v0, 16, v0
	v_mul_f32_e32 v67, v4, v0
	v_mov_b32_e32 v0, v103
	v_add_f32_e32 v2, v53, v5
	v_lshlrev_b32_e32 v0, 16, v0
	v_mul_f32_e32 v53, v2, v0
	v_or_b32_e32 v0, 8, v86
	v_mul_lo_u32 v0, v0, s80
	v_lshl_add_u64 v[68:69], s[6:7], 0, v[0:1]
	v_lshl_add_u64 v[68:69], v[68:69], 0, s[0:1]
	v_lshl_add_u64 v[90:91], v[68:69], 0, v[10:11]
	v_mov_b64_e32 v[2:3], v[164:165]
	v_mov_b64_e32 v[4:5], v[166:167]
	v_mov_b32_e32 v0, v104
	v_add_f32_e32 v68, v70, v2
	v_lshlrev_b32_e32 v0, 16, v0
	v_mul_f32_e32 v68, v68, v0
	v_mov_b32_e32 v0, v105
	v_add_f32_e32 v2, v54, v2
	v_add_f32_e32 v70, v72, v4
	v_lshlrev_b32_e32 v0, 16, v0
	v_mul_f32_e32 v54, v2, v0
	v_or_b32_e32 v0, 9, v86
	v_mul_lo_u32 v0, v0, s80
	v_lshl_add_u64 v[90:91], s[6:7], 0, v[0:1]
	v_lshl_add_u64 v[90:91], v[90:91], 0, s[0:1]
	v_lshl_add_u64 v[90:91], v[90:91], 0, v[10:11]
	v_mov_b32_e32 v0, v106
	v_add_f32_e32 v2, v71, v3
	v_lshlrev_b32_e32 v0, 16, v0
	v_mul_f32_e32 v69, v2, v0
	v_mov_b32_e32 v0, v107
	v_add_f32_e32 v2, v55, v3
	v_lshlrev_b32_e32 v0, 16, v0
	v_mul_f32_e32 v55, v2, v0
	v_or_b32_e32 v0, 10, v86
	v_mul_lo_u32 v0, v0, s80
	v_lshl_add_u64 v[2:3], s[6:7], 0, v[0:1]
	v_lshl_add_u64 v[2:3], v[2:3], 0, s[0:1]
	v_lshl_add_u64 v[2:3], v[2:3], 0, v[10:11]
	v_mov_b32_e32 v0, v108
	v_lshlrev_b32_e32 v0, 16, v0
	v_mul_f32_e32 v70, v70, v0
	v_mov_b32_e32 v0, v109
	v_add_f32_e32 v2, v56, v4
	v_add_f32_e32 v4, v73, v5
	v_lshlrev_b32_e32 v0, 16, v0
	v_mul_f32_e32 v56, v2, v0
	v_or_b32_e32 v0, 11, v86
	v_mul_lo_u32 v0, v0, s80
	v_lshl_add_u64 v[2:3], s[6:7], 0, v[0:1]
	v_lshl_add_u64 v[2:3], v[2:3], 0, s[0:1]
	v_lshl_add_u64 v[2:3], v[2:3], 0, v[10:11]
	v_mov_b32_e32 v0, v110
	v_lshlrev_b32_e32 v0, 16, v0
	v_mul_f32_e32 v71, v4, v0
	v_mov_b32_e32 v0, v111
	v_add_f32_e32 v2, v57, v5
	v_lshlrev_b32_e32 v0, 16, v0
	v_mul_f32_e32 v57, v2, v0
	v_or_b32_e32 v0, 16, v86
	v_mul_lo_u32 v0, v0, s80
	v_lshl_add_u64 v[72:73], s[6:7], 0, v[0:1]
	v_lshl_add_u64 v[72:73], v[72:73], 0, s[0:1]
	v_lshl_add_u64 v[90:91], v[72:73], 0, v[10:11]
	v_mov_b64_e32 v[2:3], v[168:169]
	v_mov_b64_e32 v[4:5], v[170:171]
	v_mov_b32_e32 v0, v112
	v_add_f32_e32 v72, v74, v2
	v_lshlrev_b32_e32 v0, 16, v0
	v_mul_f32_e32 v72, v72, v0
	v_mov_b32_e32 v0, v113
	v_add_f32_e32 v2, v58, v2
	v_add_f32_e32 v74, v76, v4
	v_lshlrev_b32_e32 v0, 16, v0
	v_mul_f32_e32 v58, v2, v0
	v_or_b32_e32 v0, 17, v86
	v_mul_lo_u32 v0, v0, s80
	v_lshl_add_u64 v[90:91], s[6:7], 0, v[0:1]
	v_lshl_add_u64 v[90:91], v[90:91], 0, s[0:1]
	v_lshl_add_u64 v[90:91], v[90:91], 0, v[10:11]
	v_mov_b32_e32 v0, v114
	v_add_f32_e32 v2, v75, v3
	v_lshlrev_b32_e32 v0, 16, v0
	v_mul_f32_e32 v73, v2, v0
	v_mov_b32_e32 v0, v115
	v_add_f32_e32 v2, v59, v3
	v_lshlrev_b32_e32 v0, 16, v0
	v_mul_f32_e32 v59, v2, v0
	v_or_b32_e32 v0, 18, v86
	v_mul_lo_u32 v0, v0, s80
	v_lshl_add_u64 v[2:3], s[6:7], 0, v[0:1]
	v_lshl_add_u64 v[2:3], v[2:3], 0, s[0:1]
	v_lshl_add_u64 v[2:3], v[2:3], 0, v[10:11]
	v_mov_b32_e32 v0, v116
	v_lshlrev_b32_e32 v0, 16, v0
	v_mul_f32_e32 v74, v74, v0
	v_mov_b32_e32 v0, v117
	v_add_f32_e32 v2, v60, v4
	v_add_f32_e32 v4, v77, v5
	v_lshlrev_b32_e32 v0, 16, v0
	v_mul_f32_e32 v60, v2, v0
	v_or_b32_e32 v0, 19, v86
	v_mul_lo_u32 v0, v0, s80
	v_lshl_add_u64 v[2:3], s[6:7], 0, v[0:1]
	v_lshl_add_u64 v[2:3], v[2:3], 0, s[0:1]
	v_lshl_add_u64 v[2:3], v[2:3], 0, v[10:11]
	v_mov_b32_e32 v0, v118
	v_lshlrev_b32_e32 v0, 16, v0
	v_mul_f32_e32 v75, v4, v0
	v_mov_b32_e32 v0, v119
	v_add_f32_e32 v2, v61, v5
	v_lshlrev_b32_e32 v0, 16, v0
	v_mul_f32_e32 v61, v2, v0
	v_or_b32_e32 v0, 24, v86
	v_mul_lo_u32 v0, v0, s80
	v_lshl_add_u64 v[76:77], s[6:7], 0, v[0:1]
	v_lshl_add_u64 v[76:77], v[76:77], 0, s[0:1]
	v_lshl_add_u64 v[90:91], v[76:77], 0, v[10:11]
	v_mov_b64_e32 v[2:3], v[172:173]
	v_mov_b64_e32 v[4:5], v[174:175]
	v_mov_b32_e32 v0, v120
	v_add_f32_e32 v76, v78, v2
	v_lshlrev_b32_e32 v0, 16, v0
	v_mul_f32_e32 v76, v76, v0
	v_mov_b32_e32 v0, v121
	v_add_f32_e32 v2, v62, v2
	v_add_f32_e32 v62, v79, v3
	v_add_f32_e32 v3, v63, v3
	v_add_f32_e32 v63, v80, v4
	v_add_f32_e32 v4, v64, v4
	v_lshlrev_b32_e32 v0, 16, v0
	v_mul_f32_e32 v2, v2, v0
	v_or_b32_e32 v0, 25, v86
	v_mul_lo_u32 v0, v0, s80
	v_lshl_add_u64 v[90:91], s[6:7], 0, v[0:1]
	v_lshl_add_u64 v[90:91], v[90:91], 0, s[0:1]
; __device__ __forceinline__ int crow(int r, int hi) { return (r & 3) + 8 * (r >> 2) + 4 * hi; }
; __device__ __forceinline__ unsigned cvtpk_s(float lo, float hi) { typedef __bf16 bf16x2_t __attribute__((ext_vector_type(2))); f32x2 v = {lo, hi}; bf16x2_t b = __builtin_convertvector(v, bf16x2_t); return __builtin_bit_cast(unsigned, b); }
; __device__ __forceinline__ void store_tile(const f32x16* o, const float* rli, bf16_t* stg, bf16_t* Ow, int pitch, float* ss, int lane, int r32, int hi) {
; #pragma unroll
;     for (int r = 0; r < 16; ++r) { const int orow = crow(r, hi);
; #pragma unroll
;         for (int d0 = 0; d0 < 2; ++d0) stg[orow * 64 + d0 * 32 + r32] = (bf16_t)(cvtpk_s(o[d0][r] * rli[r], 0.f) & 0xffffu); }
;     asm volatile("s_waitcnt lgkmcnt(0)" ::: "memory");
; #pragma unroll
;     for (int i = 0; i < 4; ++i) { const int row = i * 8 + (lane >> 3), ch = lane & 7; const u32x4 v = *(const u32x4*)(stg + row * 64 + ch * 8);
;         { const bf16_t* gp_ = Ow + (long)row * pitch + ch * 8; asm volatile("global_store_dwordx4 %0, %1, off sc0 sc1\n\ts_nop 1" :: "v"(gp_), "v"(v) : "memory"); }
;         float s = 0.f;
; #pragma unroll
;         for (int j = 0; j < 4; ++j) { const float a = __uint_as_float(v[j] << 16), b = __uint_as_float(v[j] & 0xffff0000u); s += a * a + b * b; }
;         s += __shfl_xor(s, 1); s += __shfl_xor(s, 2); s += __shfl_xor(s, 4);
;         if (ch == 0) atomicAdd(ss + (long)row * 4, s); }
;     asm volatile("s_waitcnt lgkmcnt(0)" ::: "memory");
	v_lshl_add_u64 v[90:91], v[90:91], 0, v[10:11]
	v_mov_b32_e32 v0, v122
	v_cvt_pk_bf16_f32 v2, v2, s0
	ds_write_b16 v85, v2 offset:3136
	v_lshlrev_b32_e32 v0, 16, v0
	v_mul_f32_e32 v62, v62, v0
	v_mov_b32_e32 v0, v123
	v_cvt_pk_bf16_f32 v2, v62, s0
	ds_write_b16 v85, v2 offset:3200
	v_lshlrev_b32_e32 v0, 16, v0
	v_mul_f32_e32 v3, v3, v0
	v_or_b32_e32 v0, 26, v86
	v_mul_lo_u32 v0, v0, s80
	v_lshl_add_u64 v[78:79], s[6:7], 0, v[0:1]
	v_lshl_add_u64 v[78:79], v[78:79], 0, s[0:1]
	v_lshl_add_u64 v[78:79], v[78:79], 0, v[10:11]
	v_mov_b32_e32 v0, v124
	v_cvt_pk_bf16_f32 v2, v3, s0
	ds_write_b16 v85, v2 offset:3264
	v_lshlrev_b32_e32 v0, 16, v0
	v_mul_f32_e32 v63, v63, v0
	v_mov_b32_e32 v0, v125
	v_cvt_pk_bf16_f32 v2, v63, s0
	ds_write_b16 v85, v2 offset:3328
	v_lshlrev_b32_e32 v0, 16, v0
	v_mul_f32_e32 v4, v4, v0
	v_or_b32_e32 v0, 27, v86
	v_mul_lo_u32 v0, v0, s80
	v_lshl_add_u64 v[78:79], s[6:7], 0, v[0:1]
	v_lshl_add_u64 v[78:79], v[78:79], 0, s[0:1]
	v_lshl_add_u64 v[78:79], v[78:79], 0, v[10:11]
	v_mov_b32_e32 v0, v126
	v_add_f32_e32 v11, v81, v5
	v_add_f32_e32 v5, v65, v5
	s_lshl_b64 s[6:7], s[86:87], 11
	v_cvt_pk_bf16_f32 v2, v4, s0
	s_add_u32 s2, s76, s6
	ds_write_b16 v85, v2 offset:3392
	s_addc_u32 s6, s77, s7
	s_add_u32 s8, s2, s0
	s_addc_u32 s9, s6, s1
	s_lshl_b64 s[6:7], s[86:87], 4
	s_add_u32 s6, s10, s6
	s_addc_u32 s7, s11, s7
	v_lshlrev_b32_e32 v0, 16, v0
	v_mul_f32_e32 v0, v11, v0
	v_mov_b32_e32 v11, v127
	v_cvt_pk_bf16_f32 v0, v0, s0
	ds_write_b16 v85, v0 offset:3456
	v_lshlrev_b32_e32 v11, 16, v11
	v_mul_f32_e32 v5, v5, v11
	v_cvt_pk_bf16_f32 v11, v13, s0
	ds_write_b16 v85, v11
	v_cvt_pk_bf16_f32 v11, v15, s0
	ds_write_b16 v85, v11 offset:64
	v_cvt_pk_bf16_f32 v11, v50, s0
	ds_write_b16 v85, v11 offset:128
	v_cvt_pk_bf16_f32 v11, v51, s0
	ds_write_b16 v85, v11 offset:192
	v_cvt_pk_bf16_f32 v11, v66, s0
	ds_write_b16 v85, v11 offset:256
	v_cvt_pk_bf16_f32 v11, v52, s0
	ds_write_b16 v85, v11 offset:320
	v_cvt_pk_bf16_f32 v11, v67, s0
	ds_write_b16 v85, v11 offset:384
	v_cvt_pk_bf16_f32 v11, v53, s0
	ds_write_b16 v85, v11 offset:448
	v_cvt_pk_bf16_f32 v11, v68, s0
	ds_write_b16 v85, v11 offset:1024
	v_cvt_pk_bf16_f32 v11, v54, s0
	ds_write_b16 v85, v11 offset:1088
	v_cvt_pk_bf16_f32 v11, v69, s0
	ds_write_b16 v85, v11 offset:1152
	v_cvt_pk_bf16_f32 v11, v55, s0
	ds_write_b16 v85, v11 offset:1216
	v_cvt_pk_bf16_f32 v11, v70, s0
	ds_write_b16 v85, v11 offset:1280
	v_cvt_pk_bf16_f32 v11, v56, s0
	ds_write_b16 v85, v11 offset:1344
	v_cvt_pk_bf16_f32 v11, v71, s0
	ds_write_b16 v85, v11 offset:1408
	v_cvt_pk_bf16_f32 v11, v57, s0
	ds_write_b16 v85, v11 offset:1472
	v_cvt_pk_bf16_f32 v11, v72, s0
	ds_write_b16 v85, v11 offset:2048
	v_cvt_pk_bf16_f32 v11, v58, s0
	ds_write_b16 v85, v11 offset:2112
	v_cvt_pk_bf16_f32 v11, v73, s0
	ds_write_b16 v85, v11 offset:2176
	v_cvt_pk_bf16_f32 v11, v59, s0
	ds_write_b16 v85, v11 offset:2240
	v_cvt_pk_bf16_f32 v11, v74, s0
	ds_write_b16 v85, v11 offset:2304
	v_cvt_pk_bf16_f32 v11, v60, s0
	ds_write_b16 v85, v11 offset:2368
	v_cvt_pk_bf16_f32 v11, v75, s0
	ds_write_b16 v85, v11 offset:2432
	v_cvt_pk_bf16_f32 v11, v61, s0
	ds_write_b16 v85, v11 offset:2496
	v_cvt_pk_bf16_f32 v11, v76, s0
	v_cvt_pk_bf16_f32 v0, v5, s0
	ds_write_b16 v85, v11 offset:3072
	ds_write_b16 v85, v0 offset:3520
	s_waitcnt lgkmcnt(0)
	ds_read_b128 v[50:53], v84
	v_mov_b32_e32 v15, v1
	v_lshl_add_u64 v[2:3], s[8:9], 0, v[14:15]
	s_mov_b64 s[8:9], 0x12e40300
	v_lshl_add_u64 v[2:3], v[2:3], 0, s[8:9]
	v_lshl_add_u64 v[4:5], v[2:3], 0, v[8:9]
	s_waitcnt lgkmcnt(0)
	global_store_dwordx4 v[4:5], v[50:53], off sc0 sc1
	s_nop 1
	v_and_b32_e32 v4, 0xffff0000, v50
	v_lshlrev_b32_e32 v0, 16, v50
	v_mul_f32_e32 v4, v4, v4
	v_and_b32_e32 v5, 0xffff0000, v51
	v_fmac_f32_e32 v4, v0, v0
	v_lshlrev_b32_e32 v0, 16, v51
	v_mul_f32_e32 v5, v5, v5
	v_fmac_f32_e32 v5, v0, v0
	v_add_f32_e32 v0, v4, v5
	v_and_b32_e32 v5, 0xffff0000, v52
	v_lshlrev_b32_e32 v4, 16, v52
	v_mul_f32_e32 v5, v5, v5
	v_fmac_f32_e32 v5, v4, v4
	v_add_f32_e32 v0, v5, v0
	v_and_b32_e32 v5, 0xffff0000, v53
	v_lshlrev_b32_e32 v4, 16, v53
	v_mul_f32_e32 v5, v5, v5
	v_fmac_f32_e32 v5, v4, v4
	v_add_f32_e32 v0, v5, v0
	s_nop 1
	v_mov_b32_dpp v4, v0 quad_perm:[1,0,3,2] row_mask:0xf bank_mask:0xf
	s_waitcnt lgkmcnt(0)
	v_add_f32_e32 v0, v0, v4
	s_nop 1
	v_mov_b32_dpp v4, v0 quad_perm:[2,3,0,1] row_mask:0xf bank_mask:0xf
	s_waitcnt lgkmcnt(0)
	v_add_f32_e32 v0, v0, v4
	s_nop 1
	v_mov_b32_dpp v4, v0 row_half_mirror row_mask:0xf bank_mask:0xf
	s_and_saveexec_b64 s[8:9], vcc
	s_cbranch_execz .LBB0_562
	v_lshl_add_u64 v[14:15], s[6:7], 0, v[6:7]
	s_waitcnt lgkmcnt(0)
	v_add_f32_e32 v0, v0, v4
	flat_atomic_add_f32 v[14:15], v0 offset:4
.LBB0_562:
	s_or_b64 exec, exec, s[8:9]
	s_waitcnt lgkmcnt(0)
	v_or_b32_e32 v4, 8, v89
	v_lshlrev_b32_e32 v5, 7, v4
	v_add_u32_e32 v58, v88, v5
	ds_read_b128 v[50:53], v58
	v_lshlrev_b32_e32 v0, 11, v4
	v_lshlrev_b32_e32 v14, 4, v4
	v_lshl_add_u64 v[4:5], v[2:3], 0, v[0:1]
	s_waitcnt lgkmcnt(0)
	global_store_dwordx4 v[4:5], v[50:53], off sc0 sc1
	s_nop 1
	v_and_b32_e32 v5, 0xffff0000, v50
	v_lshlrev_b32_e32 v4, 16, v50
	v_mul_f32_e32 v5, v5, v5
	v_and_b32_e32 v11, 0xffff0000, v51
	v_fmac_f32_e32 v5, v4, v4
	v_lshlrev_b32_e32 v4, 16, v51
	v_mul_f32_e32 v11, v11, v11
	v_fmac_f32_e32 v11, v4, v4
	v_add_f32_e32 v4, v5, v11
	v_and_b32_e32 v11, 0xffff0000, v52
	v_lshlrev_b32_e32 v5, 16, v52
	v_mul_f32_e32 v11, v11, v11
	v_fmac_f32_e32 v11, v5, v5
	v_add_f32_e32 v4, v11, v4
	v_and_b32_e32 v11, 0xffff0000, v53
	v_lshlrev_b32_e32 v5, 16, v53
	v_mul_f32_e32 v11, v11, v11
	v_fmac_f32_e32 v11, v5, v5
	v_add_f32_e32 v4, v11, v4
	s_nop 1
	v_mov_b32_dpp v5, v4 quad_perm:[1,0,3,2] row_mask:0xf bank_mask:0xf
	v_mov_b32_e32 v15, v1
	s_waitcnt lgkmcnt(0)
	v_add_f32_e32 v4, v4, v5
	s_nop 1
	v_mov_b32_dpp v5, v4 quad_perm:[2,3,0,1] row_mask:0xf bank_mask:0xf
	s_waitcnt lgkmcnt(0)
	v_add_f32_e32 v4, v4, v5
	s_nop 1
	v_mov_b32_dpp v5, v4 row_half_mirror row_mask:0xf bank_mask:0xf
	s_and_saveexec_b64 s[8:9], vcc
	s_cbranch_execz .LBB0_564
	v_lshl_add_u64 v[50:51], s[6:7], 0, v[14:15]
	s_waitcnt lgkmcnt(0)
	v_add_f32_e32 v4, v4, v5
	flat_atomic_add_f32 v[50:51], v4 offset:4
; __device__ __forceinline__ float bf2f(unsigned short h) { return __uint_as_float(((unsigned)h) << 16); }
; __device__ __forceinline__ int crow(int r, int hi) { return (r & 3) + 8 * (r >> 2) + 4 * hi; }
; __device__ __forceinline__ void store_tile(const f32x16* o, const float* rli, bf16_t* stg, bf16_t* Ow, int pitch, float* ss, int lane, int r32, int hi) {
;     ...
;     for (int i = 0; i < 4; ++i) { const int row = i * 8 + (lane >> 3), ch = lane & 7; const u32x4 v = *(const u32x4*)(stg + row * 64 + ch * 8);
;         { const bf16_t* gp_ = Ow + (long)row * pitch + ch * 8; asm volatile("global_store_dwordx4 %0, %1, off sc0 sc1\n\ts_nop 1" :: "v"(gp_), "v"(v) : "memory"); }
;         float s = 0.f;
; #pragma unroll
;         for (int j = 0; j < 4; ++j) { const float a = __uint_as_float(v[j] << 16), b = __uint_as_float(v[j] & 0xffff0000u); s += a * a + b * b; }
;         s += __shfl_xor(s, 1); s += __shfl_xor(s, 2); s += __shfl_xor(s, 4);
;         if (ch == 0) atomicAdd(ss + (long)row * 4, s); }
; __device__ __forceinline__ void sg_unit(const Params& P, int l, int chunk, char* shm, float* ssb) {
;     ...
;         for (int r = 0; r < 16; ++r) { const int p = 64 * ph + 32 * pt + at::crow(r, hi); const float bp = bs[p];
; #pragma unroll
;             for (int ct = 0; ct < 2; ++ct) { const float uu = bf2f(qkv[(size_t)(R0 + p) * DIN + C_U + 64 * g + 32 * ct + r32]); o[ct][r] = uu * (acc[pt][ct][r] + bp); } }
.LBB0_564:
	s_or_b64 exec, exec, s[8:9]
	v_or_b32_e32 v4, 16, v89
	s_waitcnt lgkmcnt(0)
	v_lshlrev_b32_e32 v5, 7, v4
	v_add_u32_e32 v59, v88, v5
	ds_read_b128 v[54:57], v59
	v_lshlrev_b32_e32 v52, 11, v4
	v_mov_b32_e32 v53, v1
	v_lshlrev_b32_e32 v50, 4, v4
	v_lshl_add_u64 v[4:5], v[2:3], 0, v[52:53]
	s_waitcnt lgkmcnt(0)
	global_store_dwordx4 v[4:5], v[54:57], off sc0 sc1
	s_nop 1
	v_and_b32_e32 v5, 0xffff0000, v54
	v_lshlrev_b32_e32 v4, 16, v54
	v_mul_f32_e32 v5, v5, v5
	v_and_b32_e32 v11, 0xffff0000, v55
	v_fmac_f32_e32 v5, v4, v4
	v_lshlrev_b32_e32 v4, 16, v55
	v_mul_f32_e32 v11, v11, v11
	v_fmac_f32_e32 v11, v4, v4
	v_add_f32_e32 v4, v5, v11
	v_and_b32_e32 v11, 0xffff0000, v56
	v_lshlrev_b32_e32 v5, 16, v56
	v_mul_f32_e32 v11, v11, v11
	v_fmac_f32_e32 v11, v5, v5
	v_add_f32_e32 v4, v11, v4
	v_and_b32_e32 v11, 0xffff0000, v57
	v_lshlrev_b32_e32 v5, 16, v57
	v_mul_f32_e32 v11, v11, v11
	v_fmac_f32_e32 v11, v5, v5
	v_add_f32_e32 v4, v11, v4
	s_nop 1
	v_mov_b32_dpp v5, v4 quad_perm:[1,0,3,2] row_mask:0xf bank_mask:0xf
	v_mov_b32_e32 v51, v1
	s_waitcnt lgkmcnt(0)
	v_add_f32_e32 v4, v4, v5
	s_nop 1
	v_mov_b32_dpp v5, v4 quad_perm:[2,3,0,1] row_mask:0xf bank_mask:0xf
	s_waitcnt lgkmcnt(0)
	v_add_f32_e32 v4, v4, v5
	s_nop 1
	v_mov_b32_dpp v5, v4 row_half_mirror row_mask:0xf bank_mask:0xf
	s_and_saveexec_b64 s[8:9], vcc
	s_cbranch_execz .LBB0_566
	v_lshl_add_u64 v[54:55], s[6:7], 0, v[50:51]
	s_waitcnt lgkmcnt(0)
	v_add_f32_e32 v4, v4, v5
	flat_atomic_add_f32 v[54:55], v4 offset:4
.LBB0_566:
	s_or_b64 exec, exec, s[8:9]
	v_or_b32_e32 v4, 24, v89
	s_waitcnt lgkmcnt(0)
	v_lshlrev_b32_e32 v5, 7, v4
	v_add_u32_e32 v60, v88, v5
	ds_read_b128 v[62:65], v60
	v_lshlrev_b32_e32 v54, 11, v4
	v_mov_b32_e32 v55, v1
	v_lshl_add_u64 v[2:3], v[2:3], 0, v[54:55]
	v_mov_b32_e32 v13, v1
	s_waitcnt lgkmcnt(0)
	global_store_dwordx4 v[2:3], v[62:65], off sc0 sc1
	s_nop 1
	v_and_b32_e32 v3, 0xffff0000, v62
	v_lshl_add_u64 v[56:57], s[4:5], 0, v[12:13]
	v_lshlrev_b32_e32 v12, 4, v4
	v_lshlrev_b32_e32 v2, 16, v62
	v_mul_f32_e32 v3, v3, v3
	v_and_b32_e32 v4, 0xffff0000, v63
	v_fmac_f32_e32 v3, v2, v2
	v_lshlrev_b32_e32 v2, 16, v63
	v_mul_f32_e32 v4, v4, v4
	v_fmac_f32_e32 v4, v2, v2
	v_add_f32_e32 v2, v3, v4
	v_and_b32_e32 v4, 0xffff0000, v64
	v_lshlrev_b32_e32 v3, 16, v64
	v_mul_f32_e32 v4, v4, v4
	v_fmac_f32_e32 v4, v3, v3
	v_add_f32_e32 v2, v4, v2
	v_and_b32_e32 v4, 0xffff0000, v65
	v_lshlrev_b32_e32 v3, 16, v65
	v_mul_f32_e32 v4, v4, v4
	v_fmac_f32_e32 v4, v3, v3
	v_add_f32_e32 v2, v4, v2
	s_nop 1
	v_mov_b32_dpp v3, v2 quad_perm:[1,0,3,2] row_mask:0xf bank_mask:0xf
	s_waitcnt lgkmcnt(0)
	v_add_f32_e32 v2, v2, v3
	s_nop 1
	v_mov_b32_dpp v3, v2 quad_perm:[2,3,0,1] row_mask:0xf bank_mask:0xf
	s_waitcnt lgkmcnt(0)
	v_add_f32_e32 v2, v2, v3
	s_nop 1
	v_mov_b32_dpp v3, v2 row_half_mirror row_mask:0xf bank_mask:0xf
	s_and_saveexec_b64 s[4:5], vcc
	s_cbranch_execz .LBB0_568
	v_lshl_add_u64 v[4:5], s[6:7], 0, v[12:13]
	s_waitcnt lgkmcnt(0)
	v_add_f32_e32 v2, v2, v3
	flat_atomic_add_f32 v[4:5], v2 offset:4
.LBB0_568:
	s_or_b64 exec, exec, s[4:5]
	v_or_b32_e32 v11, 32, v86
	v_readlane_b32 s4, v254, 8
	v_mul_lo_u32 v62, v11, s80
	v_mov_b32_e32 v63, v1
	v_readlane_b32 s5, v254, 9
	v_mov_b32_e32 v11, v1
	s_waitcnt lgkmcnt(0)
	s_waitcnt lgkmcnt(0)
	v_mov_b64_e32 v[2:3], v[176:177]
	v_mov_b64_e32 v[4:5], v[178:179]
	v_lshl_add_u64 v[62:63], s[4:5], 0, v[62:63]
	v_lshl_add_u64 v[62:63], v[62:63], 0, s[0:1]
	v_lshl_add_u64 v[62:63], v[62:63], 0, v[10:11]
	v_mov_b32_e32 v64, v128
	s_or_b32 s86, s86, 32
	v_mov_b32_e32 v62, v129
	v_mov_b32_e32 v63, v1
	v_lshlrev_b32_e32 v61, 3, v87
	v_add_f32_e32 v34, v34, v2
	v_add_f32_e32 v2, v18, v2
	v_add_f32_e32 v35, v35, v3
	v_add_f32_e32 v3, v19, v3
	v_add_f32_e32 v36, v36, v4
	v_lshlrev_b32_e32 v64, 16, v64
	v_lshlrev_b32_e32 v62, 16, v62
	v_mul_f32_e32 v18, v2, v62
	v_or_b32_e32 v2, 33, v86
	v_mul_lo_u32 v62, v2, s80
	v_lshl_add_u64 v[62:63], s[4:5], 0, v[62:63]
	v_lshl_add_u64 v[62:63], v[62:63], 0, s[0:1]
	v_lshl_add_u64 v[62:63], v[62:63], 0, v[10:11]
	v_mov_b32_e32 v2, v130
	v_mul_f32_e32 v34, v34, v64
	v_add_f32_e32 v37, v37, v5
	v_lshlrev_b32_e32 v2, 16, v2
	v_mul_f32_e32 v35, v35, v2
	v_mov_b32_e32 v2, v131
	v_mov_b32_e32 v63, v1
	v_lshlrev_b32_e32 v2, 16, v2
	v_mul_f32_e32 v19, v3, v2
	v_or_b32_e32 v2, 34, v86
	v_mul_lo_u32 v2, v2, s80
	v_mov_b32_e32 v3, v1
	v_lshl_add_u64 v[2:3], s[4:5], 0, v[2:3]
	v_lshl_add_u64 v[2:3], v[2:3], 0, s[0:1]
	v_lshl_add_u64 v[2:3], v[2:3], 0, v[10:11]
	v_mov_b32_e32 v62, v132
	v_lshlrev_b32_e32 v62, 16, v62
	v_mov_b32_e32 v2, v133
	v_add_f32_e32 v3, v20, v4
	v_mul_f32_e32 v36, v36, v62
	v_or_b32_e32 v62, 40, v86
	v_mul_lo_u32 v62, v62, s80
	v_lshl_add_u64 v[62:63], s[4:5], 0, v[62:63]
	v_lshl_add_u64 v[62:63], v[62:63], 0, s[0:1]
	v_lshl_add_u64 v[62:63], v[62:63], 0, v[10:11]
	v_mov_b32_e32 v64, v136
	v_lshlrev_b32_e32 v2, 16, v2
	v_mul_f32_e32 v20, v3, v2
	v_or_b32_e32 v2, 35, v86
	v_mul_lo_u32 v2, v2, s80
	v_mov_b32_e32 v3, v1
	v_lshl_add_u64 v[2:3], s[4:5], 0, v[2:3]
	v_lshl_add_u64 v[2:3], v[2:3], 0, s[0:1]
	v_lshl_add_u64 v[2:3], v[2:3], 0, v[10:11]
	v_mov_b32_e32 v4, v134
	v_lshlrev_b32_e32 v64, 16, v64
	v_mov_b32_e32 v2, v135
	v_lshlrev_b32_e32 v4, 16, v4
	v_mov_b32_e32 v62, v137
	v_lshlrev_b32_e32 v2, 16, v2
	v_add_f32_e32 v3, v21, v5
	v_mul_f32_e32 v37, v37, v4
	v_mul_f32_e32 v21, v3, v2
	v_mov_b64_e32 v[2:3], v[180:181]
	v_mov_b64_e32 v[4:5], v[182:183]
	v_mov_b32_e32 v63, v1
	v_lshlrev_b32_e32 v62, 16, v62
	v_add_f32_e32 v38, v38, v2
	v_add_f32_e32 v2, v22, v2
	v_mul_f32_e32 v22, v2, v62
	v_or_b32_e32 v2, 41, v86
	v_mul_lo_u32 v62, v2, s80
	v_lshl_add_u64 v[62:63], s[4:5], 0, v[62:63]
; __device__ __forceinline__ float bf2f(unsigned short h) { return __uint_as_float(((unsigned)h) << 16); }
; __device__ __forceinline__ int crow(int r, int hi) { return (r & 3) + 8 * (r >> 2) + 4 * hi; }
; __device__ __forceinline__ unsigned cvtpk_s(float lo, float hi) { typedef __bf16 bf16x2_t __attribute__((ext_vector_type(2))); f32x2 v = {lo, hi}; bf16x2_t b = __builtin_convertvector(v, bf16x2_t); return __builtin_bit_cast(unsigned, b); }
; __device__ __forceinline__ void store_tile(const f32x16* o, const float* rli, bf16_t* stg, bf16_t* Ow, int pitch, float* ss, int lane, int r32, int hi) {
;     ...
;     for (int r = 0; r < 16; ++r) { const int orow = crow(r, hi);
; #pragma unroll
;         for (int d0 = 0; d0 < 2; ++d0) stg[orow * 64 + d0 * 32 + r32] = (bf16_t)(cvtpk_s(o[d0][r] * rli[r], 0.f) & 0xffffu); }
; __device__ __forceinline__ void sg_unit(const Params& P, int l, int chunk, char* shm, float* ssb) {
;     ...
;         for (int r = 0; r < 16; ++r) { const int p = 64 * ph + 32 * pt + at::crow(r, hi); const float bp = bs[p];
; #pragma unroll
;             for (int ct = 0; ct < 2; ++ct) { const float uu = bf2f(qkv[(size_t)(R0 + p) * DIN + C_U + 64 * g + 32 * ct + r32]); o[ct][r] = uu * (acc[pt][ct][r] + bp); } }
;         const int prow = R0 + 64 * ph + 32 * pt;
;         at::store_tile(o, ones, (bf16_t*)(shm + SG_STAGE) + wid * 2048, omix + (size_t)prow * DM + 384 + 64 * g, DM, ssb + (size_t)prow * 4 + 1, lane, r32, hi);
	v_lshl_add_u64 v[62:63], v[62:63], 0, s[0:1]
	v_lshl_add_u64 v[62:63], v[62:63], 0, v[10:11]
	v_mov_b32_e32 v2, v138
	v_add_f32_e32 v39, v39, v3
	v_add_f32_e32 v3, v23, v3
	v_add_f32_e32 v40, v40, v4
	v_mul_f32_e32 v38, v38, v64
	v_add_f32_e32 v41, v41, v5
	v_lshlrev_b32_e32 v2, 16, v2
	v_mul_f32_e32 v39, v39, v2
	v_mov_b32_e32 v2, v139
	v_mov_b32_e32 v63, v1
	v_lshlrev_b32_e32 v2, 16, v2
	v_mul_f32_e32 v23, v3, v2
	v_or_b32_e32 v2, 42, v86
	v_mul_lo_u32 v2, v2, s80
	v_mov_b32_e32 v3, v1
	v_lshl_add_u64 v[2:3], s[4:5], 0, v[2:3]
	v_lshl_add_u64 v[2:3], v[2:3], 0, s[0:1]
	v_lshl_add_u64 v[2:3], v[2:3], 0, v[10:11]
	v_mov_b32_e32 v62, v140
	v_lshlrev_b32_e32 v62, 16, v62
	v_mov_b32_e32 v2, v141
	v_add_f32_e32 v3, v24, v4
	v_mul_f32_e32 v40, v40, v62
	v_or_b32_e32 v62, 48, v86
	v_mul_lo_u32 v62, v62, s80
	v_lshl_add_u64 v[62:63], s[4:5], 0, v[62:63]
	v_lshl_add_u64 v[62:63], v[62:63], 0, s[0:1]
	v_lshl_add_u64 v[62:63], v[62:63], 0, v[10:11]
	v_mov_b32_e32 v64, v144
	v_lshlrev_b32_e32 v2, 16, v2
	v_mul_f32_e32 v24, v3, v2
	v_or_b32_e32 v2, 43, v86
	v_mul_lo_u32 v2, v2, s80
	v_mov_b32_e32 v3, v1
	v_lshl_add_u64 v[2:3], s[4:5], 0, v[2:3]
	v_lshl_add_u64 v[2:3], v[2:3], 0, s[0:1]
	v_lshl_add_u64 v[2:3], v[2:3], 0, v[10:11]
	v_mov_b32_e32 v4, v142
	v_lshlrev_b32_e32 v64, 16, v64
	v_mov_b32_e32 v2, v143
	v_lshlrev_b32_e32 v4, 16, v4
	v_mov_b32_e32 v62, v145
	v_lshlrev_b32_e32 v2, 16, v2
	v_add_f32_e32 v3, v25, v5
	v_mul_f32_e32 v41, v41, v4
	v_mul_f32_e32 v25, v3, v2
	v_mov_b64_e32 v[2:3], v[184:185]
	v_mov_b64_e32 v[4:5], v[186:187]
	v_mov_b32_e32 v63, v1
	v_lshlrev_b32_e32 v62, 16, v62
	v_add_f32_e32 v42, v42, v2
	v_add_f32_e32 v2, v26, v2
	v_mul_f32_e32 v26, v2, v62
	v_or_b32_e32 v2, 49, v86
	v_mul_lo_u32 v62, v2, s80
	v_lshl_add_u64 v[62:63], s[4:5], 0, v[62:63]
	v_lshl_add_u64 v[62:63], v[62:63], 0, s[0:1]
	v_lshl_add_u64 v[62:63], v[62:63], 0, v[10:11]
	v_mov_b32_e32 v2, v146
	v_add_f32_e32 v43, v43, v3
	v_add_f32_e32 v3, v27, v3
	v_add_f32_e32 v44, v44, v4
	v_add_f32_e32 v45, v45, v5
	v_mul_f32_e32 v42, v42, v64
	v_lshlrev_b32_e32 v2, 16, v2
	v_mul_f32_e32 v43, v43, v2
	v_mov_b32_e32 v2, v147
	v_lshlrev_b32_e32 v2, 16, v2
	v_mul_f32_e32 v27, v3, v2
	v_or_b32_e32 v2, 50, v86
	v_mul_lo_u32 v2, v2, s80
	v_mov_b32_e32 v3, v1
	v_lshl_add_u64 v[2:3], s[4:5], 0, v[2:3]
	v_lshl_add_u64 v[2:3], v[2:3], 0, s[0:1]
	v_lshl_add_u64 v[2:3], v[2:3], 0, v[10:11]
	v_mov_b32_e32 v62, v148
	v_lshlrev_b32_e32 v62, 16, v62
	v_mov_b32_e32 v2, v149
	v_add_f32_e32 v3, v28, v4
	v_mul_f32_e32 v44, v44, v62
	v_lshlrev_b32_e32 v2, 16, v2
	v_mul_f32_e32 v28, v3, v2
	v_or_b32_e32 v2, 51, v86
	v_mul_lo_u32 v2, v2, s80
	v_mov_b32_e32 v3, v1
	v_lshl_add_u64 v[2:3], s[4:5], 0, v[2:3]
	v_lshl_add_u64 v[2:3], v[2:3], 0, s[0:1]
	v_lshl_add_u64 v[2:3], v[2:3], 0, v[10:11]
	v_mov_b32_e32 v4, v150
	v_lshlrev_b32_e32 v4, 16, v4
	v_mov_b32_e32 v2, v151
	v_add_f32_e32 v3, v29, v5
	v_mul_f32_e32 v45, v45, v4
	v_lshlrev_b32_e32 v2, 16, v2
	v_mul_f32_e32 v29, v3, v2
	v_mov_b64_e32 v[2:3], v[188:189]
	v_mov_b64_e32 v[4:5], v[190:191]
	v_or_b32_e32 v56, 56, v86
	v_mul_lo_u32 v56, v56, s80
	v_mov_b32_e32 v57, v1
	v_lshl_add_u64 v[56:57], s[4:5], 0, v[56:57]
	v_lshl_add_u64 v[56:57], v[56:57], 0, s[0:1]
	v_lshl_add_u64 v[56:57], v[56:57], 0, v[10:11]
	v_mov_b32_e32 v62, v152
	v_add_f32_e32 v46, v46, v2
	v_mov_b32_e32 v56, v153
	v_add_f32_e32 v2, v30, v2
	v_or_b32_e32 v30, 57, v86
	v_mov_b32_e32 v57, v1
	v_add_f32_e32 v47, v47, v3
	v_add_f32_e32 v3, v31, v3
	v_or_b32_e32 v31, 58, v86
	v_lshlrev_b32_e32 v62, 16, v62
	v_mul_f32_e32 v46, v46, v62
	v_lshlrev_b32_e32 v56, 16, v56
	v_mul_f32_e32 v2, v2, v56
	v_mul_lo_u32 v56, v30, s80
	v_lshl_add_u64 v[56:57], s[4:5], 0, v[56:57]
	v_lshl_add_u64 v[56:57], v[56:57], 0, s[0:1]
	v_lshl_add_u64 v[56:57], v[56:57], 0, v[10:11]
	v_mov_b32_e32 v30, v154
	v_lshlrev_b32_e32 v30, 16, v30
	v_mul_f32_e32 v30, v47, v30
	v_mov_b32_e32 v47, v155
	v_mul_lo_u32 v56, v31, s80
	v_mov_b32_e32 v57, v1
	v_lshl_add_u64 v[56:57], s[4:5], 0, v[56:57]
	v_lshl_add_u64 v[56:57], v[56:57], 0, s[0:1]
	v_lshl_add_u64 v[56:57], v[56:57], 0, v[10:11]
	v_mov_b32_e32 v31, v156
	v_lshlrev_b32_e32 v47, 16, v47
	v_mul_f32_e32 v3, v3, v47
	v_add_f32_e32 v47, v48, v4
	v_add_f32_e32 v4, v32, v4
	v_or_b32_e32 v32, 59, v86
	v_lshlrev_b32_e32 v31, 16, v31
	v_mul_f32_e32 v31, v47, v31
	v_mov_b32_e32 v47, v157
	v_mul_lo_u32 v56, v32, s80
	v_mov_b32_e32 v57, v1
	v_lshl_add_u64 v[56:57], s[4:5], 0, v[56:57]
	v_lshl_add_u64 v[56:57], v[56:57], 0, s[0:1]
	v_lshl_add_u64 v[10:11], v[56:57], 0, v[10:11]
	v_mov_b32_e32 v32, v158
	s_lshl_b64 s[4:5], s[86:87], 11
	v_mov_b32_e32 v10, v159
	s_add_u32 s2, s76, s4
	s_addc_u32 s5, s77, s5
	s_add_u32 s4, s2, s0
	s_addc_u32 s5, s5, s1
	s_lshl_b64 s[0:1], s[86:87], 4
	s_add_u32 s0, s10, s0
	v_cvt_pk_bf16_f32 v2, v2, s0
	ds_write_b16 v85, v2 offset:3136
	v_cvt_pk_bf16_f32 v2, v30, s0
	ds_write_b16 v85, v2 offset:3200
	v_cvt_pk_bf16_f32 v2, v3, s0
	ds_write_b16 v85, v2 offset:3264
	v_cvt_pk_bf16_f32 v2, v31, s0
	ds_write_b16 v85, v2 offset:3328
	v_mov_b32_e32 v3, v1
	s_addc_u32 s1, s11, s1
	v_lshlrev_b32_e32 v47, 16, v47
	v_mul_f32_e32 v4, v4, v47
	v_add_f32_e32 v47, v49, v5
	v_add_f32_e32 v5, v33, v5
	v_cvt_pk_bf16_f32 v2, v4, s0
	ds_write_b16 v85, v2 offset:3392
	v_lshlrev_b32_e32 v32, 16, v32
	v_mul_f32_e32 v32, v47, v32
	v_lshlrev_b32_e32 v10, 16, v10
	v_mul_f32_e32 v5, v5, v10
	v_cvt_pk_bf16_f32 v10, v34, s0
	ds_write_b16 v85, v10
	v_cvt_pk_bf16_f32 v10, v18, s0
	ds_write_b16 v85, v10 offset:64
	v_cvt_pk_bf16_f32 v10, v35, s0
	ds_write_b16 v85, v10 offset:128
	v_cvt_pk_bf16_f32 v10, v19, s0
	ds_write_b16 v85, v10 offset:192
	v_cvt_pk_bf16_f32 v10, v36, s0
; __device__ __forceinline__ int crow(int r, int hi) { return (r & 3) + 8 * (r >> 2) + 4 * hi; }
; __device__ __forceinline__ unsigned cvtpk_s(float lo, float hi) { typedef __bf16 bf16x2_t __attribute__((ext_vector_type(2))); f32x2 v = {lo, hi}; bf16x2_t b = __builtin_convertvector(v, bf16x2_t); return __builtin_bit_cast(unsigned, b); }
; __device__ __forceinline__ void store_tile(const f32x16* o, const float* rli, bf16_t* stg, bf16_t* Ow, int pitch, float* ss, int lane, int r32, int hi) {
;     ...
;     for (int r = 0; r < 16; ++r) { const int orow = crow(r, hi);
; #pragma unroll
;         for (int d0 = 0; d0 < 2; ++d0) stg[orow * 64 + d0 * 32 + r32] = (bf16_t)(cvtpk_s(o[d0][r] * rli[r], 0.f) & 0xffffu); }
;     asm volatile("s_waitcnt lgkmcnt(0)" ::: "memory");
; #pragma unroll
;     for (int i = 0; i < 4; ++i) { const int row = i * 8 + (lane >> 3), ch = lane & 7; const u32x4 v = *(const u32x4*)(stg + row * 64 + ch * 8);
;         { const bf16_t* gp_ = Ow + (long)row * pitch + ch * 8; asm volatile("global_store_dwordx4 %0, %1, off sc0 sc1\n\ts_nop 1" :: "v"(gp_), "v"(v) : "memory"); }
;         float s = 0.f;
; #pragma unroll
;         for (int j = 0; j < 4; ++j) { const float a = __uint_as_float(v[j] << 16), b = __uint_as_float(v[j] & 0xffff0000u); s += a * a + b * b; }
;         s += __shfl_xor(s, 1); s += __shfl_xor(s, 2); s += __shfl_xor(s, 4);
;         if (ch == 0) atomicAdd(ss + (long)row * 4, s); }
;     asm volatile("s_waitcnt lgkmcnt(0)" ::: "memory");
	ds_write_b16 v85, v10 offset:256
	v_cvt_pk_bf16_f32 v10, v20, s0
	ds_write_b16 v85, v10 offset:320
	v_cvt_pk_bf16_f32 v10, v37, s0
	ds_write_b16 v85, v10 offset:384
	v_cvt_pk_bf16_f32 v10, v21, s0
	ds_write_b16 v85, v10 offset:448
	v_cvt_pk_bf16_f32 v10, v38, s0
	ds_write_b16 v85, v10 offset:1024
	v_cvt_pk_bf16_f32 v10, v22, s0
	ds_write_b16 v85, v10 offset:1088
	v_cvt_pk_bf16_f32 v10, v39, s0
	ds_write_b16 v85, v10 offset:1152
	v_cvt_pk_bf16_f32 v10, v23, s0
	ds_write_b16 v85, v10 offset:1216
	v_cvt_pk_bf16_f32 v10, v40, s0
	ds_write_b16 v85, v10 offset:1280
	v_cvt_pk_bf16_f32 v10, v24, s0
	ds_write_b16 v85, v10 offset:1344
	v_cvt_pk_bf16_f32 v10, v41, s0
	ds_write_b16 v85, v10 offset:1408
	v_cvt_pk_bf16_f32 v10, v25, s0
	ds_write_b16 v85, v10 offset:1472
	v_cvt_pk_bf16_f32 v10, v42, s0
	ds_write_b16 v85, v10 offset:2048
	v_cvt_pk_bf16_f32 v10, v26, s0
	ds_write_b16 v85, v10 offset:2112
	v_cvt_pk_bf16_f32 v10, v43, s0
	ds_write_b16 v85, v10 offset:2176
	v_cvt_pk_bf16_f32 v10, v27, s0
	ds_write_b16 v85, v10 offset:2240
	v_cvt_pk_bf16_f32 v10, v44, s0
	ds_write_b16 v85, v10 offset:2304
	v_cvt_pk_bf16_f32 v10, v28, s0
	ds_write_b16 v85, v10 offset:2368
	v_cvt_pk_bf16_f32 v10, v45, s0
	ds_write_b16 v85, v10 offset:2432
	v_cvt_pk_bf16_f32 v10, v29, s0
	v_cvt_pk_bf16_f32 v2, v32, s0
	ds_write_b16 v85, v10 offset:2496
	v_cvt_pk_bf16_f32 v10, v46, s0
	ds_write_b16 v85, v2 offset:3456
	v_cvt_pk_bf16_f32 v2, v5, s0
	ds_write_b16 v85, v10 offset:3072
	ds_write_b16 v85, v2 offset:3520
	s_waitcnt lgkmcnt(0)
	ds_read_b128 v[18:21], v84
	v_lshlrev_b32_e32 v2, 1, v61
	v_lshl_add_u64 v[2:3], s[4:5], 0, v[2:3]
	s_mov_b64 s[4:5], 0x12e40300
	v_lshl_add_u64 v[2:3], v[2:3], 0, s[4:5]
	v_lshl_add_u64 v[4:5], v[2:3], 0, v[8:9]
	s_waitcnt lgkmcnt(0)
	global_store_dwordx4 v[4:5], v[18:21], off sc0 sc1
	s_nop 1
	v_and_b32_e32 v5, 0xffff0000, v18
	v_lshlrev_b32_e32 v4, 16, v18
	v_mul_f32_e32 v5, v5, v5
	v_and_b32_e32 v8, 0xffff0000, v19
	v_fmac_f32_e32 v5, v4, v4
	v_lshlrev_b32_e32 v4, 16, v19
	v_mul_f32_e32 v8, v8, v8
	v_fmac_f32_e32 v8, v4, v4
	v_add_f32_e32 v4, v5, v8
	v_and_b32_e32 v8, 0xffff0000, v20
	v_lshlrev_b32_e32 v5, 16, v20
	v_mul_f32_e32 v8, v8, v8
	v_fmac_f32_e32 v8, v5, v5
	v_add_f32_e32 v4, v8, v4
	v_and_b32_e32 v8, 0xffff0000, v21
	v_lshlrev_b32_e32 v5, 16, v21
	v_mul_f32_e32 v8, v8, v8
	v_fmac_f32_e32 v8, v5, v5
	v_add_f32_e32 v4, v8, v4
	s_nop 1
	v_mov_b32_dpp v5, v4 quad_perm:[1,0,3,2] row_mask:0xf bank_mask:0xf
	s_waitcnt lgkmcnt(0)
	v_add_f32_e32 v4, v4, v5
	s_nop 1
	v_mov_b32_dpp v5, v4 quad_perm:[2,3,0,1] row_mask:0xf bank_mask:0xf
	s_waitcnt lgkmcnt(0)
	v_add_f32_e32 v4, v4, v5
	s_nop 1
	v_mov_b32_dpp v5, v4 row_half_mirror row_mask:0xf bank_mask:0xf
	s_and_saveexec_b64 s[4:5], vcc
	s_cbranch_execz .LBB0_570
	v_lshl_add_u64 v[6:7], s[0:1], 0, v[6:7]
	s_waitcnt lgkmcnt(0)
	v_add_f32_e32 v4, v4, v5
	flat_atomic_add_f32 v[6:7], v4 offset:4
.LBB0_570:
	s_or_b64 exec, exec, s[4:5]
	s_waitcnt lgkmcnt(0)
	ds_read_b128 v[4:7], v58
	v_lshl_add_u64 v[8:9], v[2:3], 0, v[0:1]
	s_waitcnt lgkmcnt(0)
	global_store_dwordx4 v[8:9], v[4:7], off sc0 sc1
	s_nop 1
	v_lshlrev_b32_e32 v0, 16, v4
	v_and_b32_e32 v4, 0xffff0000, v4
	v_mul_f32_e32 v4, v4, v4
	v_fmac_f32_e32 v4, v0, v0
	v_lshlrev_b32_e32 v0, 16, v5
	v_and_b32_e32 v5, 0xffff0000, v5
	v_mul_f32_e32 v5, v5, v5
	v_fmac_f32_e32 v5, v0, v0
	v_add_f32_e32 v0, v4, v5
	v_and_b32_e32 v5, 0xffff0000, v6
	v_lshlrev_b32_e32 v4, 16, v6
	v_mul_f32_e32 v5, v5, v5
	v_fmac_f32_e32 v5, v4, v4
	v_add_f32_e32 v0, v5, v0
	v_and_b32_e32 v5, 0xffff0000, v7
	v_lshlrev_b32_e32 v4, 16, v7
	v_mul_f32_e32 v5, v5, v5
	v_fmac_f32_e32 v5, v4, v4
	v_add_f32_e32 v0, v5, v0
	s_nop 1
	v_mov_b32_dpp v4, v0 quad_perm:[1,0,3,2] row_mask:0xf bank_mask:0xf
	s_waitcnt lgkmcnt(0)
	v_add_f32_e32 v0, v0, v4
	s_nop 1
	v_mov_b32_dpp v4, v0 quad_perm:[2,3,0,1] row_mask:0xf bank_mask:0xf
	s_waitcnt lgkmcnt(0)
	v_add_f32_e32 v0, v0, v4
	s_nop 1
	v_mov_b32_dpp v4, v0 row_half_mirror row_mask:0xf bank_mask:0xf
	s_and_saveexec_b64 s[4:5], vcc
	s_cbranch_execz .LBB0_572
	v_lshl_add_u64 v[6:7], s[0:1], 0, v[14:15]
	s_waitcnt lgkmcnt(0)
	v_add_f32_e32 v0, v0, v4
	flat_atomic_add_f32 v[6:7], v0 offset:4
.LBB0_572:
	s_or_b64 exec, exec, s[4:5]
	s_waitcnt lgkmcnt(0)
	ds_read_b128 v[4:7], v59
	v_lshl_add_u64 v[8:9], v[2:3], 0, v[52:53]
	s_waitcnt lgkmcnt(0)
	global_store_dwordx4 v[8:9], v[4:7], off sc0 sc1
	s_nop 1
	v_lshlrev_b32_e32 v0, 16, v4
	v_and_b32_e32 v4, 0xffff0000, v4
	v_mul_f32_e32 v4, v4, v4
	v_fmac_f32_e32 v4, v0, v0
	v_lshlrev_b32_e32 v0, 16, v5
	v_and_b32_e32 v5, 0xffff0000, v5
	v_mul_f32_e32 v5, v5, v5
	v_fmac_f32_e32 v5, v0, v0
	v_add_f32_e32 v0, v4, v5
	v_and_b32_e32 v5, 0xffff0000, v6
	v_lshlrev_b32_e32 v4, 16, v6
	v_mul_f32_e32 v5, v5, v5
	v_fmac_f32_e32 v5, v4, v4
	v_add_f32_e32 v0, v5, v0
	v_and_b32_e32 v5, 0xffff0000, v7
	v_lshlrev_b32_e32 v4, 16, v7
	v_mul_f32_e32 v5, v5, v5
	v_fmac_f32_e32 v5, v4, v4
	v_add_f32_e32 v0, v5, v0
	s_nop 1
	v_mov_b32_dpp v4, v0 quad_perm:[1,0,3,2] row_mask:0xf bank_mask:0xf
	s_waitcnt lgkmcnt(0)
	v_add_f32_e32 v0, v0, v4
	s_nop 1
	v_mov_b32_dpp v4, v0 quad_perm:[2,3,0,1] row_mask:0xf bank_mask:0xf
	s_waitcnt lgkmcnt(0)
	v_add_f32_e32 v0, v0, v4
	s_nop 1
	v_mov_b32_dpp v4, v0 row_half_mirror row_mask:0xf bank_mask:0xf
	s_and_saveexec_b64 s[4:5], vcc
	s_cbranch_execz .LBB0_574
	v_lshl_add_u64 v[6:7], s[0:1], 0, v[50:51]
	s_waitcnt lgkmcnt(0)
	v_add_f32_e32 v0, v0, v4
	flat_atomic_add_f32 v[6:7], v0 offset:4
.LBB0_574:
	s_or_b64 exec, exec, s[4:5]
	s_waitcnt lgkmcnt(0)
	ds_read_b128 v[4:7], v60
	v_lshl_add_u64 v[2:3], v[2:3], 0, v[54:55]
	s_waitcnt lgkmcnt(0)
	global_store_dwordx4 v[2:3], v[4:7], off sc0 sc1
	s_nop 1
	v_and_b32_e32 v2, 0xffff0000, v4
	v_lshlrev_b32_e32 v0, 16, v4
	v_mul_f32_e32 v2, v2, v2
	v_and_b32_e32 v3, 0xffff0000, v5
	v_fmac_f32_e32 v2, v0, v0
	v_lshlrev_b32_e32 v0, 16, v5
	v_mul_f32_e32 v3, v3, v3
	v_fmac_f32_e32 v3, v0, v0
	v_add_f32_e32 v0, v2, v3
	v_and_b32_e32 v3, 0xffff0000, v6
	v_lshlrev_b32_e32 v2, 16, v6
	v_mul_f32_e32 v3, v3, v3
	v_fmac_f32_e32 v3, v2, v2
	v_add_f32_e32 v0, v3, v0
	v_and_b32_e32 v3, 0xffff0000, v7
	v_lshlrev_b32_e32 v2, 16, v7
	v_mul_f32_e32 v3, v3, v3
	v_fmac_f32_e32 v3, v2, v2
	v_add_f32_e32 v0, v3, v0
	s_nop 1
	v_mov_b32_dpp v2, v0 quad_perm:[1,0,3,2] row_mask:0xf bank_mask:0xf
	s_waitcnt lgkmcnt(0)
	v_add_f32_e32 v0, v0, v2
	s_nop 1
	v_mov_b32_dpp v2, v0 quad_perm:[2,3,0,1] row_mask:0xf bank_mask:0xf
	s_waitcnt lgkmcnt(0)
	v_add_f32_e32 v0, v0, v2
	s_nop 1
	v_mov_b32_dpp v2, v0 row_half_mirror row_mask:0xf bank_mask:0xf
	s_and_saveexec_b64 s[4:5], vcc
	s_cbranch_execz .LBB0_576
	v_lshl_add_u64 v[4:5], s[0:1], 0, v[12:13]
	s_waitcnt lgkmcnt(0)
	v_add_f32_e32 v0, v0, v2
	flat_atomic_add_f32 v[4:5], v0 offset:4

; __device__ __forceinline__ int crow(int r, int hi) { return (r & 3) + 8 * (r >> 2) + 4 * hi; }
; #define SBAR() __builtin_amdgcn_sched_barrier(0)
; #define PKW(P, B) cvtpk_s(P[B], P[B + 1])
;     ...
;     { float sacc = pB0[0] + pB0[1]; _Pragma("unroll") for (int r = 2; r < 16; ++r) sacc += pB0[r]; _Pragma("unroll") for (int r = 0; r < 16; ++r) sacc += pB1[r]; l_reg += sacc;
;       pw0 = (u32x4){PKW(pB0, 0), PKW(pB0, 2), PKW(pB0, 4), PKW(pB0, 6)}; pw1 = (u32x4){PKW(pB0, 8), PKW(pB0, 10), PKW(pB0, 12), PKW(pB0, 14)}; pw2 = (u32x4){PKW(pB1, 0), PKW(pB1, 2), PKW(pB1, 4), PKW(pB1, 6)}; pw3 = (u32x4){PKW(pB1, 8), PKW(pB1, 10), PKW(pB1, 12), PKW(pB1, 14)};
;       SBAR(); const int vb0 = (int)(lds0 + LDS_V) + ((lane >> 4) & 1) * 32 + (lane & 3) * 8 + (4 * hi + ((lane & 15) >> 2)) * 64;
;       at::pv(o, vb0 + sl_cur, PAF(0), PAF(1), PAF(2), PAF(3)); }
;     ...
;     { auto rr = __builtin_amdgcn_permlane32_swap(__float_as_uint(l_reg), __float_as_uint(l_reg), false, false); l_reg = __uint_as_float(rr[0]) + __uint_as_float(rr[1]); }
;     if (hi == 0) wsf[32 + r32] = l_reg; asm volatile("s_waitcnt lgkmcnt(0)" ::: "memory");
;     float rli[16];
; #pragma unroll
;     for (int r = 0; r < 16; ++r) rli[r] = __builtin_amdgcn_rcpf(wsf[32 + crow(r, hi)]);
;     at::store_tile(o, rli, (bf16_t*)(shm + LDS_OST) + wid * 2048, O + (long)(wid * QBLK) * OPITCH, OPITCH, ss + (long)(wid * QBLK) * 4, lane, r32, hi);
.LBB0_860:
	v_add_f32_e32 v3, v64, v65
	v_add_f32_e32 v3, v66, v3
	v_add_f32_e32 v3, v67, v3
	v_add_f32_e32 v3, v68, v3
	v_add_f32_e32 v3, v69, v3
	v_add_f32_e32 v3, v70, v3
	v_add_f32_e32 v3, v71, v3
	v_add_f32_e32 v3, v72, v3
	v_add_f32_e32 v3, v73, v3
	v_add_f32_e32 v3, v74, v3
	v_add_f32_e32 v3, v75, v3
	v_add_f32_e32 v3, v76, v3
	v_add_f32_e32 v3, v77, v3
	v_add_f32_e32 v3, v78, v3
	v_add_f32_e32 v3, v79, v3
	v_add_f32_e32 v3, v80, v3
	v_add_f32_e32 v3, v81, v3
	v_add_f32_e32 v3, v82, v3
	v_add_f32_e32 v3, v83, v3
	v_add_f32_e32 v3, v84, v3
	v_add_f32_e32 v3, v85, v3
	v_add_f32_e32 v3, v86, v3
	v_add_f32_e32 v3, v87, v3
	v_add_f32_e32 v3, v88, v3
	v_add_f32_e32 v3, v89, v3
	v_add_f32_e32 v3, v90, v3
	v_add_f32_e32 v3, v91, v3
	v_add_f32_e32 v3, v92, v3
	v_add_f32_e32 v3, v93, v3
	v_add_f32_e32 v3, v94, v3
	v_add_f32_e32 v3, v95, v3
	v_add_f32_e32 v0, v0, v3
	v_cvt_pk_bf16_f32 v4, v64, v65
	v_cvt_pk_bf16_f32 v5, v66, v67
	v_cvt_pk_bf16_f32 v6, v68, v69
	v_cvt_pk_bf16_f32 v7, v70, v71
	v_cvt_pk_bf16_f32 v8, v72, v73
	v_cvt_pk_bf16_f32 v9, v74, v75
	v_cvt_pk_bf16_f32 v10, v76, v77
	v_cvt_pk_bf16_f32 v11, v78, v79
	v_cvt_pk_bf16_f32 v12, v80, v81
	v_cvt_pk_bf16_f32 v13, v82, v83
	v_cvt_pk_bf16_f32 v14, v84, v85
	v_cvt_pk_bf16_f32 v15, v86, v87
	v_cvt_pk_bf16_f32 v18, v88, v89
	v_cvt_pk_bf16_f32 v19, v90, v91
	v_cvt_pk_bf16_f32 v20, v92, v93
	v_cvt_pk_bf16_f32 v21, v94, v95
	s_cmp_lg_u32 0, -1
	s_cselect_b32 s0, 0, 0
	s_addk_i32 s0, 0x6000
	v_add3_u32 v3, v228, s0, v227
	v_add3_u32 v3, v3, v229, s88
	ds_read_b64_tr_b16 v[22:23],v3 offset:0
	ds_read_b64_tr_b16 v[24:25],v3 offset:512
	ds_read_b64_tr_b16 v[26:27],v3 offset:1024
	ds_read_b64_tr_b16 v[28:29],v3 offset:1536
	ds_read_b64_tr_b16 v[64:65],v3 offset:2048
	ds_read_b64_tr_b16 v[66:67],v3 offset:2560
	ds_read_b64_tr_b16 v[68:69],v3 offset:3072
	ds_read_b64_tr_b16 v[70:71],v3 offset:3584
	s_waitcnt lgkmcnt(0)
	s_nop 0
	v_mfma_f32_32x32x16_bf16 v[48:63], v[4:7], v[22:25], v[48:63]
	ds_read_b64_tr_b16 v[22:23],v3 offset:4096
	ds_read_b64_tr_b16 v[24:25],v3 offset:4608
	v_mfma_f32_32x32x16_bf16 v[48:63], v[8:11], v[26:29], v[48:63]
	ds_read_b64_tr_b16 v[26:27],v3 offset:5120
	ds_read_b64_tr_b16 v[28:29],v3 offset:5632
	v_mfma_f32_32x32x16_bf16 v[48:63], v[12:15], v[64:67], v[48:63]
	ds_read_b64_tr_b16 v[64:65],v3 offset:6144
	ds_read_b64_tr_b16 v[66:67],v3 offset:6656
	v_mfma_f32_32x32x16_bf16 v[48:63], v[18:21], v[68:71], v[48:63]
	ds_read_b64_tr_b16 v[68:69],v3 offset:7168
	ds_read_b64_tr_b16 v[70:71],v3 offset:7680
	s_waitcnt lgkmcnt(0)
	v_mfma_f32_32x32x16_bf16 v[32:47], v[4:7], v[22:25], v[32:47]
	v_mov_b32_e32 v3, v0
	s_nop 1
	v_permlane32_swap_b32_e32 v0, v3
	v_cmp_gt_u32_e32 vcc, 32, v224
	v_mfma_f32_32x32x16_bf16 v[32:47], v[8:11], v[26:29], v[32:47]
	v_mfma_f32_32x32x16_bf16 v[32:47], v[12:15], v[64:67], v[32:47]
	v_mfma_f32_32x32x16_bf16 v[32:47], v[18:21], v[68:71], v[32:47]
	s_and_saveexec_b64 s[0:1], vcc
	v_add_f32_e32 v0, v0, v3
	v_lshl_add_u32 v3, v225, 2, s3
	ds_write_b32 v3, v0 offset:49280
	s_or_b64 exec, exec, s[0:1]
	s_waitcnt lgkmcnt(0)
	ds_read_b128 v[4:7], v2 offset:49280
	ds_read_b128 v[8:11], v2 offset:49312
	s_lshl_b64 s[0:1], s[86:87], 11
	v_readlane_b32 s2, v252, 32
	v_readlane_b32 s3, v252, 33
	s_add_u32 s0, s2, s0
	s_addc_u32 s1, s3, s1
	s_lshl_b32 s2, s82, 1
	s_waitcnt lgkmcnt(1)
	v_rcp_f32_e32 v0, v4
	v_rcp_f32_e32 v3, v5
	v_rcp_f32_e32 v12, v6
	v_rcp_f32_e32 v13, v7
	s_waitcnt lgkmcnt(0)
	v_rcp_f32_e32 v14, v8
	ds_read_b128 v[4:7], v2 offset:49344
	v_rcp_f32_e32 v15, v9
	v_rcp_f32_e32 v17, v10
	v_rcp_f32_e32 v18, v11
	ds_read_b128 v[8:11], v2 offset:49376
	s_add_u32 s2, s0, s2
	s_addc_u32 s3, s1, 0
	s_lshl_b32 s0, s86, 4
	v_readlane_b32 s4, v252, 34
	v_readlane_b32 s5, v252, 35
	s_add_u32 s4, s4, s0
	v_readlane_b32 s0, v252, 36
	v_readlane_b32 s8, v252, 38
	s_addc_u32 s5, s5, 0
	s_lshl_b32 s0, s0, 12
	v_readlane_b32 s9, v252, 39
	s_waitcnt lgkmcnt(1)
	v_rcp_f32_e32 v2, v4
	v_rcp_f32_e32 v4, v5
	v_rcp_f32_e32 v5, v6
	v_rcp_f32_e32 v6, v7
	s_waitcnt lgkmcnt(0)
	v_rcp_f32_e32 v7, v8
	v_rcp_f32_e32 v8, v9
	v_rcp_f32_e32 v9, v10
	v_rcp_f32_e32 v10, v11
	s_add_i32 s6, s0, 0
	s_lshl_b64 s[0:1], s[8:9], 11
	v_mul_f32_e32 v11, v48, v0
	v_lshlrev_b32_e32 v19, 1, v226
	v_lshlrev_b32_e32 v20, 1, v225
	v_mul_f32_e32 v0, v32, v0
	v_add3_u32 v19, s6, v19, v20
	v_cvt_pk_bf16_f32 v0, v0, s0
	ds_write_b16 v19, v0 offset:51264
	v_mul_f32_e32 v0, v49, v3
	v_cvt_pk_bf16_f32 v0, v0, s0
	ds_write_b16 v19, v0 offset:51328
	v_mul_f32_e32 v0, v33, v3
	v_cvt_pk_bf16_f32 v0, v0, s0
	ds_write_b16 v19, v0 offset:51392
	v_mul_f32_e32 v0, v50, v12
	v_cvt_pk_bf16_f32 v0, v0, s0
	ds_write_b16 v19, v0 offset:51456
	v_mul_f32_e32 v0, v34, v12
	v_cvt_pk_bf16_f32 v0, v0, s0
	ds_write_b16 v19, v0 offset:51520
	v_mul_f32_e32 v0, v51, v13
	v_cvt_pk_bf16_f32 v0, v0, s0
	ds_write_b16 v19, v0 offset:51584
	v_mul_f32_e32 v0, v35, v13
	v_cvt_pk_bf16_f32 v0, v0, s0
	ds_write_b16 v19, v0 offset:51648
	v_mul_f32_e32 v0, v52, v14
	v_cvt_pk_bf16_f32 v0, v0, s0
	ds_write_b16 v19, v0 offset:52224
	v_mul_f32_e32 v0, v36, v14
	v_cvt_pk_bf16_f32 v0, v0, s0
	ds_write_b16 v19, v0 offset:52288
	v_mul_f32_e32 v0, v53, v15
	v_cvt_pk_bf16_f32 v0, v0, s0
	ds_write_b16 v19, v0 offset:52352
	v_mul_f32_e32 v0, v37, v15
	v_cvt_pk_bf16_f32 v0, v0, s0
	ds_write_b16 v19, v0 offset:52416
	v_mul_f32_e32 v0, v54, v17
	v_cvt_pk_bf16_f32 v0, v0, s0
	ds_write_b16 v19, v0 offset:52480
	v_mul_f32_e32 v0, v38, v17
	v_cvt_pk_bf16_f32 v0, v0, s0
	ds_write_b16 v19, v0 offset:52544
	v_mul_f32_e32 v0, v55, v18
	v_cvt_pk_bf16_f32 v0, v0, s0
	ds_write_b16 v19, v0 offset:52608
	v_mul_f32_e32 v0, v39, v18
	v_cvt_pk_bf16_f32 v0, v0, s0
; __device__ __forceinline__ int crow(int r, int hi) { return (r & 3) + 8 * (r >> 2) + 4 * hi; }
; __device__ __forceinline__ unsigned cvtpk_s(float lo, float hi) { typedef __bf16 bf16x2_t __attribute__((ext_vector_type(2))); f32x2 v = {lo, hi}; bf16x2_t b = __builtin_convertvector(v, bf16x2_t); return __builtin_bit_cast(unsigned, b); }
; __device__ __forceinline__ void store_tile(const f32x16* o, const float* rli, bf16_t* stg, bf16_t* Ow, int pitch, float* ss, int lane, int r32, int hi) {
;     ...
;     for (int r = 0; r < 16; ++r) { const int orow = crow(r, hi);
; #pragma unroll
;         for (int d0 = 0; d0 < 2; ++d0) stg[orow * 64 + d0 * 32 + r32] = (bf16_t)(cvtpk_s(o[d0][r] * rli[r], 0.f) & 0xffffu); }
;     asm volatile("s_waitcnt lgkmcnt(0)" ::: "memory");
; #pragma unroll
;     for (int i = 0; i < 4; ++i) { const int row = i * 8 + (lane >> 3), ch = lane & 7; const u32x4 v = *(const u32x4*)(stg + row * 64 + ch * 8);
;         { const bf16_t* gp_ = Ow + (long)row * pitch + ch * 8; asm volatile("global_store_dwordx4 %0, %1, off sc0 sc1\n\ts_nop 1" :: "v"(gp_), "v"(v) : "memory"); }
;         float s = 0.f;
; #pragma unroll
;         for (int j = 0; j < 4; ++j) { const float a = __uint_as_float(v[j] << 16), b = __uint_as_float(v[j] & 0xffff0000u); s += a * a + b * b; }
;         s += __shfl_xor(s, 1); s += __shfl_xor(s, 2); s += __shfl_xor(s, 4);
;         if (ch == 0) atomicAdd(ss + (long)row * 4, s); }
	ds_write_b16 v19, v0 offset:52672
	v_mul_f32_e32 v0, v56, v2
	v_cvt_pk_bf16_f32 v0, v0, s0
	ds_write_b16 v19, v0 offset:53248
	v_mul_f32_e32 v0, v40, v2
	v_cvt_pk_bf16_f32 v0, v0, s0
	ds_write_b16 v19, v0 offset:53312
	v_mul_f32_e32 v0, v57, v4
	v_cvt_pk_bf16_f32 v0, v0, s0
	ds_write_b16 v19, v0 offset:53376
	v_mul_f32_e32 v0, v41, v4
	v_cvt_pk_bf16_f32 v0, v0, s0
	ds_write_b16 v19, v0 offset:53440
	v_mul_f32_e32 v0, v58, v5
	v_cvt_pk_bf16_f32 v0, v0, s0
	ds_write_b16 v19, v0 offset:53504
	v_mul_f32_e32 v0, v42, v5
	v_cvt_pk_bf16_f32 v0, v0, s0
	ds_write_b16 v19, v0 offset:53568
	v_mul_f32_e32 v0, v59, v6
	v_cvt_pk_bf16_f32 v0, v0, s0
	ds_write_b16 v19, v0 offset:53632
	v_mul_f32_e32 v0, v43, v6
	v_cvt_pk_bf16_f32 v0, v0, s0
	ds_write_b16 v19, v0 offset:53696
	v_mul_f32_e32 v0, v60, v7
	v_cvt_pk_bf16_f32 v0, v0, s0
	ds_write_b16 v19, v0 offset:54272
	v_mul_f32_e32 v0, v44, v7
	v_cvt_pk_bf16_f32 v0, v0, s0
	ds_write_b16 v19, v0 offset:54336
	v_mul_f32_e32 v0, v61, v8
	v_cvt_pk_bf16_f32 v0, v0, s0
	ds_write_b16 v19, v0 offset:54400
	v_mul_f32_e32 v0, v45, v8
	v_cvt_pk_bf16_f32 v0, v0, s0
	ds_write_b16 v19, v0 offset:54464
	v_mul_f32_e32 v0, v62, v9
	v_cvt_pk_bf16_f32 v0, v0, s0
	ds_write_b16 v19, v0 offset:54528
	v_mul_f32_e32 v0, v46, v9
	v_cvt_pk_bf16_f32 v0, v0, s0
	ds_write_b16 v19, v0 offset:54592
	v_mul_f32_e32 v0, v63, v10
	v_cvt_pk_bf16_f32 v0, v0, s0
	ds_write_b16 v19, v0 offset:54656
	v_mul_f32_e32 v0, v47, v10
	v_cvt_pk_bf16_f32 v0, v0, s0
	v_and_b32_e32 v6, 7, v223
	v_cvt_pk_bf16_f32 v11, v11, s0
	ds_write_b16 v19, v0 offset:54720
	v_lshlrev_b32_e32 v0, 4, v6
	ds_write_b16 v19, v11 offset:51200
	v_lshrrev_b32_e32 v7, 3, v224
	v_add_u32_e32 v8, s6, v0
	s_waitcnt lgkmcnt(0)
	v_lshl_add_u32 v2, v7, 7, v8
	ds_read_b128 v[12:15], v2 offset:51200
	s_add_u32 s0, s2, s0
	s_addc_u32 s1, s3, s1
	s_lshl_b64 s[2:3], s[8:9], 4
	s_add_u32 s2, s4, s2
	s_waitcnt lgkmcnt(0)
	v_and_b32_e32 v3, 0xffff0000, v12
	v_lshlrev_b32_e32 v2, 16, v12
	v_mul_f32_e32 v3, v3, v3
	v_and_b32_e32 v4, 0xffff0000, v13
	v_fmac_f32_e32 v3, v2, v2
	v_lshlrev_b32_e32 v2, 16, v13
	v_mul_f32_e32 v4, v4, v4
	v_fmac_f32_e32 v4, v2, v2
	v_add_f32_e32 v2, v3, v4
	v_and_b32_e32 v4, 0xffff0000, v14
	v_lshlrev_b32_e32 v3, 16, v14
	v_mul_f32_e32 v4, v4, v4
	v_fmac_f32_e32 v4, v3, v3
	v_add_f32_e32 v2, v4, v2
	v_and_b32_e32 v4, 0xffff0000, v15
	v_lshlrev_b32_e32 v3, 16, v15
	v_mul_f32_e32 v4, v4, v4
	v_fmac_f32_e32 v4, v3, v3
	v_and_b32_e32 v3, 64, v220
	v_add_f32_e32 v5, v4, v2
	v_xor_b32_e32 v2, 1, v220
	v_add_u32_e32 v10, 64, v3
	v_cmp_lt_i32_e32 vcc, v2, v10
	s_addc_u32 s3, s5, s3
	s_add_u32 s4, s2, 0x200000
	v_cndmask_b32_e32 v2, v220, v2, vcc
	v_lshlrev_b32_e32 v4, 2, v2
	s_nop 1
	v_mov_b32_dpp v9, v5 quad_perm:[1,0,3,2] row_mask:0xf bank_mask:0xf
	v_lshl_add_u64 v[2:3], s[0:1], 0, v[0:1]
	v_xor_b32_e32 v0, 2, v220
	v_cmp_lt_i32_e32 vcc, v0, v10
	s_mov_b64 s[0:1], 0x12e40000
	s_waitcnt lgkmcnt(0)
	v_add_f32_e32 v9, v5, v9
	v_cndmask_b32_e32 v0, v220, v0, vcc
	v_lshlrev_b32_e32 v5, 2, v0
	s_nop 1
	v_mov_b32_dpp v11, v9 quad_perm:[2,3,0,1] row_mask:0xf bank_mask:0xf
	v_lshl_add_u64 v[2:3], v[2:3], 0, s[0:1]
	v_lshlrev_b32_e32 v0, 11, v7
	v_lshl_add_u64 v[18:19], v[2:3], 0, v[0:1]
	v_xor_b32_e32 v0, 4, v220
	v_cmp_lt_i32_e64 s[0:1], v0, v10
	v_cmp_eq_u32_e32 vcc, 0, v6
	s_waitcnt lgkmcnt(0)
	v_add_f32_e32 v9, v9, v11
	v_cndmask_b32_e64 v0, v220, v0, s[0:1]
	v_lshlrev_b32_e32 v6, 2, v0
	s_nop 1
	v_mov_b32_dpp v10, v9 row_half_mirror row_mask:0xf bank_mask:0xf
	global_store_dwordx4 v[18:19], v[12:15], off sc0 sc1
	s_nop 1
	s_addc_u32 s5, s3, 0
	s_and_saveexec_b64 s[0:1], vcc
	s_movk_i32 s80, 0x1200
	s_movk_i32 s81, 0x900
	s_mov_b32 s82, 0xe400000
	s_cbranch_execz .LBB0_864
	v_lshlrev_b32_e32 v0, 4, v7
	v_lshl_add_u64 v[12:13], s[4:5], 0, v[0:1]
	s_waitcnt lgkmcnt(0)
	v_add_f32_e32 v0, v9, v10
	flat_atomic_add_f32 v[12:13], v0
; __device__ __forceinline__ void store_tile(const f32x16* o, const float* rli, bf16_t* stg, bf16_t* Ow, int pitch, float* ss, int lane, int r32, int hi) {
;     ...
;     for (int i = 0; i < 4; ++i) { const int row = i * 8 + (lane >> 3), ch = lane & 7; const u32x4 v = *(const u32x4*)(stg + row * 64 + ch * 8);
;         { const bf16_t* gp_ = Ow + (long)row * pitch + ch * 8; asm volatile("global_store_dwordx4 %0, %1, off sc0 sc1\n\ts_nop 1" :: "v"(gp_), "v"(v) : "memory"); }
;         float s = 0.f;
; #pragma unroll
;         for (int j = 0; j < 4; ++j) { const float a = __uint_as_float(v[j] << 16), b = __uint_as_float(v[j] & 0xffff0000u); s += a * a + b * b; }
;         s += __shfl_xor(s, 1); s += __shfl_xor(s, 2); s += __shfl_xor(s, 4);
;         if (ch == 0) atomicAdd(ss + (long)row * 4, s); }
.LBB0_864:
	s_or_b64 exec, exec, s[0:1]
	v_or_b32_e32 v9, 8, v7
	v_lshl_add_u32 v0, v9, 7, v8
	s_waitcnt lgkmcnt(0)
	ds_read_b128 v[10:13], v0 offset:51200
	v_lshlrev_b32_e32 v0, 11, v9
	v_lshl_add_u64 v[14:15], v[2:3], 0, v[0:1]
	s_waitcnt lgkmcnt(0)
	global_store_dwordx4 v[14:15], v[10:13], off sc0 sc1
	s_nop 1
	v_lshlrev_b32_e32 v0, 16, v10
	v_and_b32_e32 v10, 0xffff0000, v10
	v_mul_f32_e32 v10, v10, v10
	v_fmac_f32_e32 v10, v0, v0
	v_lshlrev_b32_e32 v0, 16, v11
	v_and_b32_e32 v11, 0xffff0000, v11
	v_mul_f32_e32 v11, v11, v11
	v_fmac_f32_e32 v11, v0, v0
	v_add_f32_e32 v0, v10, v11
	v_and_b32_e32 v11, 0xffff0000, v12
	v_lshlrev_b32_e32 v10, 16, v12
	v_mul_f32_e32 v11, v11, v11
	v_fmac_f32_e32 v11, v10, v10
	v_add_f32_e32 v0, v11, v0
	v_and_b32_e32 v11, 0xffff0000, v13
	v_lshlrev_b32_e32 v10, 16, v13
	v_mul_f32_e32 v11, v11, v11
	v_fmac_f32_e32 v11, v10, v10
	v_add_f32_e32 v0, v11, v0
	s_nop 1
	v_mov_b32_dpp v10, v0 quad_perm:[1,0,3,2] row_mask:0xf bank_mask:0xf
	s_waitcnt lgkmcnt(0)
	v_add_f32_e32 v0, v0, v10
	s_nop 1
	v_mov_b32_dpp v10, v0 quad_perm:[2,3,0,1] row_mask:0xf bank_mask:0xf
	s_waitcnt lgkmcnt(0)
	v_add_f32_e32 v10, v0, v10
	s_nop 1
	v_mov_b32_dpp v11, v10 row_half_mirror row_mask:0xf bank_mask:0xf
	s_and_saveexec_b64 s[0:1], vcc
	s_cbranch_execz .LBB0_866
	v_lshlrev_b32_e32 v0, 4, v9
	v_lshl_add_u64 v[12:13], s[4:5], 0, v[0:1]
	s_waitcnt lgkmcnt(0)
	v_add_f32_e32 v0, v10, v11
	flat_atomic_add_f32 v[12:13], v0
.LBB0_866:
	s_or_b64 exec, exec, s[0:1]
	v_or_b32_e32 v9, 16, v7
	v_lshl_add_u32 v0, v9, 7, v8
	s_waitcnt lgkmcnt(0)
	ds_read_b128 v[10:13], v0 offset:51200
	v_lshlrev_b32_e32 v0, 11, v9
	v_lshl_add_u64 v[14:15], v[2:3], 0, v[0:1]
	s_waitcnt lgkmcnt(0)
	global_store_dwordx4 v[14:15], v[10:13], off sc0 sc1
	s_nop 1
	v_lshlrev_b32_e32 v0, 16, v10
	v_and_b32_e32 v10, 0xffff0000, v10
	v_mul_f32_e32 v10, v10, v10
	v_fmac_f32_e32 v10, v0, v0
	v_lshlrev_b32_e32 v0, 16, v11
	v_and_b32_e32 v11, 0xffff0000, v11
	v_mul_f32_e32 v11, v11, v11
	v_fmac_f32_e32 v11, v0, v0
	v_add_f32_e32 v0, v10, v11
	v_and_b32_e32 v11, 0xffff0000, v12
	v_lshlrev_b32_e32 v10, 16, v12
	v_mul_f32_e32 v11, v11, v11
	v_fmac_f32_e32 v11, v10, v10
	v_add_f32_e32 v0, v11, v0
	v_and_b32_e32 v11, 0xffff0000, v13
	v_lshlrev_b32_e32 v10, 16, v13
	v_mul_f32_e32 v11, v11, v11
	v_fmac_f32_e32 v11, v10, v10
	v_add_f32_e32 v0, v11, v0
	s_nop 1
	v_mov_b32_dpp v10, v0 quad_perm:[1,0,3,2] row_mask:0xf bank_mask:0xf
	s_waitcnt lgkmcnt(0)
	v_add_f32_e32 v0, v0, v10
	s_nop 1
	v_mov_b32_dpp v10, v0 quad_perm:[2,3,0,1] row_mask:0xf bank_mask:0xf
	s_waitcnt lgkmcnt(0)
	v_add_f32_e32 v10, v0, v10
	s_nop 1
	v_mov_b32_dpp v11, v10 row_half_mirror row_mask:0xf bank_mask:0xf
	s_and_saveexec_b64 s[0:1], vcc
	s_cbranch_execz .LBB0_868
	v_lshlrev_b32_e32 v0, 4, v9
	v_lshl_add_u64 v[12:13], s[4:5], 0, v[0:1]
	s_waitcnt lgkmcnt(0)
	v_add_f32_e32 v0, v10, v11
	flat_atomic_add_f32 v[12:13], v0
.LBB0_868:
	s_or_b64 exec, exec, s[0:1]
	v_or_b32_e32 v7, 24, v7
	v_lshl_add_u32 v0, v7, 7, v8
	s_waitcnt lgkmcnt(0)
	ds_read_b128 v[8:11], v0 offset:51200
	v_lshlrev_b32_e32 v0, 11, v7
	v_lshl_add_u64 v[2:3], v[2:3], 0, v[0:1]
	s_waitcnt lgkmcnt(0)
	global_store_dwordx4 v[2:3], v[8:11], off sc0 sc1
	s_nop 1
	v_and_b32_e32 v2, 0xffff0000, v8
	v_lshlrev_b32_e32 v0, 16, v8
	v_mul_f32_e32 v2, v2, v2
	v_and_b32_e32 v3, 0xffff0000, v9
	v_fmac_f32_e32 v2, v0, v0
	v_lshlrev_b32_e32 v0, 16, v9
	v_mul_f32_e32 v3, v3, v3
	v_fmac_f32_e32 v3, v0, v0
	v_add_f32_e32 v0, v2, v3
	v_and_b32_e32 v3, 0xffff0000, v10
	v_lshlrev_b32_e32 v2, 16, v10
	v_mul_f32_e32 v3, v3, v3
	v_fmac_f32_e32 v3, v2, v2
	v_add_f32_e32 v0, v3, v0
	v_and_b32_e32 v3, 0xffff0000, v11
	v_lshlrev_b32_e32 v2, 16, v11
	v_mul_f32_e32 v3, v3, v3
	v_fmac_f32_e32 v3, v2, v2
	v_add_f32_e32 v0, v3, v0
	s_nop 1
	v_mov_b32_dpp v2, v0 quad_perm:[1,0,3,2] row_mask:0xf bank_mask:0xf
	s_waitcnt lgkmcnt(0)
	v_add_f32_e32 v0, v0, v2
	s_nop 1
	v_mov_b32_dpp v2, v0 quad_perm:[2,3,0,1] row_mask:0xf bank_mask:0xf
	s_waitcnt lgkmcnt(0)
	v_add_f32_e32 v2, v0, v2
	s_nop 1
	v_mov_b32_dpp v3, v2 row_half_mirror row_mask:0xf bank_mask:0xf
	s_and_saveexec_b64 s[0:1], vcc
	s_cbranch_execz .LBB0_870
	v_lshlrev_b32_e32 v0, 4, v7
	v_lshl_add_u64 v[4:5], s[4:5], 0, v[0:1]
	s_waitcnt lgkmcnt(0)
	v_add_f32_e32 v0, v2, v3
	flat_atomic_add_f32 v[4:5], v0

; #define WAIT_BAR(N) asm volatile("s_waitcnt vmcnt(" #N ") lgkmcnt(0)\n\ts_barrier" ::: "memory")
; #define RESC() do { if (resc) { asm volatile("s_waitcnt lgkmcnt(0)" ::: "memory"); \
;       _Pragma("unroll") for (int d_ = 0; d_ < 2; ++d_) _Pragma("unroll") for (int r = 0; r < 16; ++r) o[d_][r] *= wsf[crow(r, hi)]; } } while (0)
; #define ROT() do { sl_prev = sl_cur; sl_cur = sl_next; sl_next = (sl_next == (NSLOT - 1) * SLOTB) ? 0 : sl_next + SLOTB; } while (0)
;     ...
;     int t = 1;
;     for (; t + 5 < NT; t += 2) {
;         STEP(pB0, pB1, pA0, pA1, t, true, true, true);     WAIT_BAR(2); RESC(); ROT();
.LBB0_876:
	v_add_u32_e32 v195, s31, v190
	ds_read_b64_tr_b16 v[182:183], v195 offset:24576
	ds_read_b64_tr_b16 v[184:185], v195 offset:25088
	v_add_f32_e32 v2, v82, v83
	v_add_f32_e32 v2, v84, v2
	v_add_f32_e32 v2, v85, v2
	v_add_f32_e32 v2, v86, v2
	v_add_f32_e32 v2, v87, v2
	v_cvt_pk_bf16_f32 v146, v82, v83
	v_cvt_pk_bf16_f32 v147, v84, v85
	s_waitcnt lgkmcnt(9)
	v_mfma_f32_32x32x16_bf16 v[114:129], v[98:101], v[162:165], v[50:65]
	ds_read_b64_tr_b16 v[178:179], v195 offset:28672
	ds_read_b64_tr_b16 v[180:181], v195 offset:29184
	s_waitcnt lgkmcnt(10)
	v_mfma_f32_32x32x16_bf16 v[98:113], v[170:173], v[162:165], v[50:65]
	v_add_f32_e32 v2, v88, v2
	v_add_f32_e32 v2, v89, v2
	v_add_f32_e32 v2, v90, v2
	v_add_f32_e32 v2, v91, v2
	v_cvt_pk_bf16_f32 v148, v86, v87
	v_cvt_pk_bf16_f32 v149, v88, v89
	ds_read_b64_tr_b16 v[82:83], v195 offset:25600
	ds_read_b64_tr_b16 v[84:85], v195 offset:26112
	v_add_f32_e32 v2, v92, v2
	v_add_f32_e32 v2, v93, v2
	v_add_f32_e32 v2, v94, v2
	v_add_f32_e32 v2, v95, v2
	v_cvt_pk_bf16_f32 v10, v90, v91
	v_cvt_pk_bf16_f32 v11, v92, v93
	s_waitcnt lgkmcnt(11)
	v_mfma_f32_32x32x16_bf16 v[114:129], v[174:177], v[158:161], v[114:129]
	ds_read_b64_tr_b16 v[86:87], v195 offset:29696
	ds_read_b64_tr_b16 v[88:89], v195 offset:30208
	s_waitcnt lgkmcnt(12)
	v_mfma_f32_32x32x16_bf16 v[98:113], v[166:169], v[158:161], v[98:113]
	v_add_f32_e32 v2, v96, v2
	v_add_f32_e32 v2, v97, v2
	v_add_f32_e32 v2, v66, v2
	v_add_f32_e32 v2, v67, v2
	v_cvt_pk_bf16_f32 v12, v94, v95
	v_cvt_pk_bf16_f32 v13, v96, v97
	ds_read_b64_tr_b16 v[90:91], v195 offset:26624
	ds_read_b64_tr_b16 v[92:93], v195 offset:27136
	v_add_f32_e32 v2, v68, v2
	v_add_f32_e32 v2, v69, v2
	v_add_f32_e32 v2, v70, v2
	v_add_f32_e32 v2, v71, v2
	v_cvt_pk_bf16_f32 v6, v66, v67
	v_cvt_pk_bf16_f32 v7, v68, v69
	s_waitcnt lgkmcnt(13)
	v_mfma_f32_32x32x16_bf16 v[114:129], v[142:145], v[154:157], v[114:129]
	ds_read_b64_tr_b16 v[66:67], v195 offset:30720
	ds_read_b64_tr_b16 v[68:69], v195 offset:31232
	s_waitcnt lgkmcnt(14)
	v_mfma_f32_32x32x16_bf16 v[98:113], v[138:141], v[154:157], v[98:113]
	v_add_f32_e32 v2, v72, v2
	v_add_f32_e32 v2, v73, v2
	v_add_f32_e32 v2, v74, v2
	v_add_f32_e32 v2, v75, v2
	v_cvt_pk_bf16_f32 v8, v70, v71
	v_cvt_pk_bf16_f32 v9, v72, v73
	ds_read_b64_tr_b16 v[70:71], v195 offset:27648
	ds_read_b64_tr_b16 v[72:73], v195 offset:28160
	v_add_f32_e32 v2, v76, v2
	v_add_f32_e32 v2, v77, v2
	v_add_f32_e32 v2, v78, v2
	v_add_f32_e32 v94, v79, v2
	v_cvt_pk_bf16_f32 v2, v74, v75
	v_cvt_pk_bf16_f32 v3, v76, v77
	s_waitcnt lgkmcnt(14)
	v_mfma_f32_32x32x16_bf16 v[114:129], v[134:137], v[150:153], v[114:129]
	ds_read_b64_tr_b16 v[74:75], v195 offset:31744
	ds_read_b64_tr_b16 v[76:77], v195 offset:32256
	v_mfma_f32_32x32x16_bf16 v[98:113], v[130:133], v[150:153], v[98:113]
	v_add_f32_e32 v4, v80, v94
	v_add_f32_e32 v4, v81, v4
	v_add_f32_e32 v195, 0, v4
	v_cvt_pk_bf16_f32 v4, v78, v79
	v_cvt_pk_bf16_f32 v5, v80, v81
	s_add_u32 s31, s2, s16
	s_addc_u32 s34, s22, s17
	s_add_u32 s36, s31, 0xe520300
	s_addc_u32 s37, s34, 0
	s_add_i32 s30, s29, s26
	s_mov_b32 s35, m0
	s_mov_b32 m0, s30
	s_nop 0
	global_load_lds_dwordx4 v193, s[36:37]
	s_mov_b32 m0, s35
	s_add_u32 s35, s23, s16
	s_addc_u32 s36, s24, s17
	s_add_u32 s38, s35, 0xe491100
	s_addc_u32 s39, s36, 0
	s_add_i32 s30, s28, s20
	s_mov_b32 s37, m0
	s_mov_b32 m0, s30
	s_nop 0
	global_load_lds_dwordx4 v192, s[38:39]
	s_mov_b32 m0, s37
	s_waitcnt lgkmcnt(14)
	v_mfma_f32_32x32x16_bf16 v[18:33], v[146:149], v[182:185], v[18:33]
	v_exp_f32_e32 v114, v114
	v_exp_f32_e32 v115, v115
	v_exp_f32_e32 v116, v116
	v_exp_f32_e32 v117, v117
	s_waitcnt lgkmcnt(12)
	v_mfma_f32_32x32x16_bf16 v[34:49], v[146:149], v[178:181], v[34:49]
	v_exp_f32_e32 v118, v118
	v_exp_f32_e32 v119, v119
	v_exp_f32_e32 v120, v120
	v_exp_f32_e32 v121, v121
	v_add_u32_e32 v94, s28, v191
	ds_read_b128 v[78:81], v94
	ds_read_b128 v[134:137], v94 offset:512
	s_waitcnt lgkmcnt(12)
	v_mfma_f32_32x32x16_bf16 v[18:33], v[10:13], v[82:85], v[18:33]
	v_exp_f32_e32 v122, v122
	v_exp_f32_e32 v123, v123
	v_exp_f32_e32 v124, v124
	v_exp_f32_e32 v125, v125
	ds_read_b128 v[138:141], v94 offset:2048
	ds_read_b128 v[142:145], v94 offset:2560
	s_waitcnt lgkmcnt(12)
	v_mfma_f32_32x32x16_bf16 v[34:49], v[10:13], v[86:89], v[34:49]
	v_exp_f32_e32 v126, v126
	v_exp_f32_e32 v127, v127
	v_exp_f32_e32 v128, v128
	v_exp_f32_e32 v129, v129
	ds_read_b128 v[166:169], v94 offset:4096
	ds_read_b128 v[170:173], v94 offset:4608
	s_waitcnt lgkmcnt(12)
	v_mfma_f32_32x32x16_bf16 v[18:33], v[6:9], v[90:93], v[18:33]
	v_exp_f32_e32 v98, v98
	v_exp_f32_e32 v99, v99
	v_exp_f32_e32 v100, v100
	v_exp_f32_e32 v101, v101
	ds_read_b128 v[174:177], v94 offset:6144
	ds_read_b128 v[130:133], v94 offset:6656
	s_waitcnt lgkmcnt(12)
	v_mfma_f32_32x32x16_bf16 v[34:49], v[6:9], v[66:69], v[34:49]
	v_exp_f32_e32 v102, v102
	v_exp_f32_e32 v103, v103
	v_exp_f32_e32 v104, v104
	v_exp_f32_e32 v105, v105
	s_waitcnt lgkmcnt(10)
	v_mfma_f32_32x32x16_bf16 v[18:33], v[2:5], v[70:73], v[18:33]
	v_exp_f32_e32 v106, v106
	v_exp_f32_e32 v107, v107
	v_exp_f32_e32 v108, v108
	v_exp_f32_e32 v109, v109
	s_waitcnt lgkmcnt(8)
	v_mfma_f32_32x32x16_bf16 v[34:49], v[2:5], v[74:77], v[34:49]
	v_exp_f32_e32 v110, v110
	v_exp_f32_e32 v111, v111
	v_exp_f32_e32 v112, v112
	v_exp_f32_e32 v113, v113
	s_waitcnt vmcnt(2) lgkmcnt(0)
	s_barrier
; #define WAIT_BAR(N) asm volatile("s_waitcnt vmcnt(" #N ") lgkmcnt(0)\n\ts_barrier" ::: "memory")
; #define RESC() do { if (resc) { asm volatile("s_waitcnt lgkmcnt(0)" ::: "memory"); \
;       _Pragma("unroll") for (int d_ = 0; d_ < 2; ++d_) _Pragma("unroll") for (int r = 0; r < 16; ++r) o[d_][r] *= wsf[crow(r, hi)]; } } while (0)
; #define ROT() do { sl_prev = sl_cur; sl_cur = sl_next; sl_next = (sl_next == (NSLOT - 1) * SLOTB) ? 0 : sl_next + SLOTB; } while (0)
;     ...
;     int t = 1;
;     for (; t + 5 < NT; t += 2) {
;         STEP(pB0, pB1, pA0, pA1, t, true, true, true);     WAIT_BAR(2); RESC(); ROT();
;         STEP(pA0, pA1, pB0, pB1, t + 1, true, true, true); WAIT_BAR(2); RESC(); ROT();
;     }
	s_add_i32 s30, s28, 0x2000
	s_cmpk_lg_i32 s28, 0x4000
	s_cselect_b32 s30, s30, 0
	v_add_u32_e32 v196, s29, v190
	ds_read_b64_tr_b16 v[178:179], v196 offset:24576
	ds_read_b64_tr_b16 v[180:181], v196 offset:25088
	s_waitcnt lgkmcnt(9)
	v_mfma_f32_32x32x16_bf16 v[82:97], v[78:81], v[162:165], v[50:65]
	v_add_f32_e32 v2, v114, v115
	v_add_f32_e32 v2, v116, v2
	v_add_f32_e32 v2, v117, v2
	v_add_f32_e32 v2, v118, v2
	v_add_f32_e32 v2, v119, v2
	v_cvt_pk_bf16_f32 v146, v114, v115
	v_cvt_pk_bf16_f32 v147, v116, v117
	ds_read_b64_tr_b16 v[182:183], v196 offset:28672
	ds_read_b64_tr_b16 v[184:185], v196 offset:29184
	s_waitcnt lgkmcnt(10)
	v_mfma_f32_32x32x16_bf16 v[66:81], v[134:137], v[162:165], v[50:65]
	v_add_f32_e32 v2, v120, v2
	v_add_f32_e32 v2, v121, v2
	v_add_f32_e32 v2, v122, v2
	v_add_f32_e32 v2, v123, v2
	v_cvt_pk_bf16_f32 v148, v118, v119
	v_cvt_pk_bf16_f32 v149, v120, v121
	ds_read_b64_tr_b16 v[114:115], v196 offset:25600
	ds_read_b64_tr_b16 v[116:117], v196 offset:26112
	s_waitcnt lgkmcnt(11)
	v_mfma_f32_32x32x16_bf16 v[82:97], v[138:141], v[158:161], v[82:97]
	v_add_f32_e32 v2, v124, v2
	v_add_f32_e32 v2, v125, v2
	v_add_f32_e32 v2, v126, v2
	v_add_f32_e32 v2, v127, v2
	v_cvt_pk_bf16_f32 v10, v122, v123
	v_cvt_pk_bf16_f32 v11, v124, v125
	ds_read_b64_tr_b16 v[118:119], v196 offset:29696
	ds_read_b64_tr_b16 v[120:121], v196 offset:30208
	s_waitcnt lgkmcnt(12)
	v_mfma_f32_32x32x16_bf16 v[66:81], v[142:145], v[158:161], v[66:81]
	v_add_f32_e32 v2, v128, v2
	v_add_f32_e32 v2, v129, v2
	v_add_f32_e32 v2, v98, v2
	v_add_f32_e32 v2, v99, v2
	v_cvt_pk_bf16_f32 v12, v126, v127
	v_cvt_pk_bf16_f32 v13, v128, v129
	ds_read_b64_tr_b16 v[122:123], v196 offset:26624
	ds_read_b64_tr_b16 v[124:125], v196 offset:27136
	s_waitcnt lgkmcnt(13)
	v_mfma_f32_32x32x16_bf16 v[82:97], v[166:169], v[154:157], v[82:97]
	v_add_f32_e32 v2, v100, v2
	v_add_f32_e32 v2, v101, v2
	v_add_f32_e32 v2, v102, v2
	v_add_f32_e32 v2, v103, v2
	v_cvt_pk_bf16_f32 v6, v98, v99
	v_cvt_pk_bf16_f32 v7, v100, v101
	ds_read_b64_tr_b16 v[126:127], v196 offset:30720
	ds_read_b64_tr_b16 v[128:129], v196 offset:31232
	s_waitcnt lgkmcnt(14)
	v_mfma_f32_32x32x16_bf16 v[66:81], v[170:173], v[154:157], v[66:81]
	v_add_f32_e32 v2, v104, v2
	v_add_f32_e32 v2, v105, v2
	v_add_f32_e32 v2, v106, v2
	v_add_f32_e32 v2, v107, v2
	v_cvt_pk_bf16_f32 v8, v102, v103
	v_cvt_pk_bf16_f32 v9, v104, v105
	ds_read_b64_tr_b16 v[102:103], v196 offset:27648
	ds_read_b64_tr_b16 v[104:105], v196 offset:28160
	s_waitcnt lgkmcnt(14)
	v_mfma_f32_32x32x16_bf16 v[82:97], v[174:177], v[150:153], v[82:97]
	v_add_f32_e32 v2, v108, v2
	v_add_f32_e32 v2, v109, v2
	v_add_f32_e32 v2, v110, v2
	v_add_f32_e32 v98, v111, v2
	v_cvt_pk_bf16_f32 v2, v106, v107
	v_cvt_pk_bf16_f32 v3, v108, v109
	ds_read_b64_tr_b16 v[106:107], v196 offset:31744
	ds_read_b64_tr_b16 v[108:109], v196 offset:32256
	v_mfma_f32_32x32x16_bf16 v[66:81], v[130:133], v[150:153], v[66:81]
	v_add_f32_e32 v4, v112, v98
	v_add_f32_e32 v4, v113, v4
	v_add_f32_e32 v196, 0, v4
	v_cvt_pk_bf16_f32 v4, v110, v111
	v_cvt_pk_bf16_f32 v5, v112, v113
	s_add_u32 s38, s31, 0xe568300
	s_addc_u32 s39, s34, 0
	s_add_i32 s29, s28, s26
	s_mov_b32 s31, m0
	s_mov_b32 m0, s29
	s_nop 0
	global_load_lds_dwordx4 v193, s[38:39]
	s_mov_b32 m0, s31
	s_add_u32 s34, s35, 0xe4d9100
	s_addc_u32 s35, s36, 0
	s_add_i32 s29, s30, s20
	s_mov_b32 s31, m0
	s_mov_b32 m0, s29
	s_nop 0
	global_load_lds_dwordx4 v192, s[34:35]
	s_mov_b32 m0, s31
	s_waitcnt lgkmcnt(14)
	v_mfma_f32_32x32x16_bf16 v[18:33], v[146:149], v[178:181], v[18:33]
	v_exp_f32_e32 v82, v82
	v_exp_f32_e32 v83, v83
	v_exp_f32_e32 v84, v84
	v_exp_f32_e32 v85, v85
	s_waitcnt lgkmcnt(12)
	v_mfma_f32_32x32x16_bf16 v[34:49], v[146:149], v[182:185], v[34:49]
	v_exp_f32_e32 v86, v86
	v_exp_f32_e32 v87, v87
	v_exp_f32_e32 v88, v88
	v_exp_f32_e32 v89, v89
	v_add_u32_e32 v110, s30, v191
	ds_read_b128 v[98:101], v110
	ds_read_b128 v[170:173], v110 offset:512
	s_waitcnt lgkmcnt(12)
	v_mfma_f32_32x32x16_bf16 v[18:33], v[10:13], v[114:117], v[18:33]
	v_exp_f32_e32 v90, v90
	v_exp_f32_e32 v91, v91
	v_exp_f32_e32 v92, v92
	v_exp_f32_e32 v93, v93
	ds_read_b128 v[174:177], v110 offset:2048
	ds_read_b128 v[166:169], v110 offset:2560
	s_waitcnt lgkmcnt(12)
	v_mfma_f32_32x32x16_bf16 v[34:49], v[10:13], v[118:121], v[34:49]
	v_exp_f32_e32 v94, v94
	v_exp_f32_e32 v95, v95
	v_exp_f32_e32 v96, v96
	v_exp_f32_e32 v97, v97
	ds_read_b128 v[142:145], v110 offset:4096
	ds_read_b128 v[138:141], v110 offset:4608
	s_waitcnt lgkmcnt(12)
	v_mfma_f32_32x32x16_bf16 v[18:33], v[6:9], v[122:125], v[18:33]
	v_exp_f32_e32 v66, v66
	v_exp_f32_e32 v67, v67
	v_exp_f32_e32 v68, v68
	v_exp_f32_e32 v69, v69
	ds_read_b128 v[134:137], v110 offset:6144
	ds_read_b128 v[130:133], v110 offset:6656
	s_waitcnt lgkmcnt(12)
	v_mfma_f32_32x32x16_bf16 v[34:49], v[6:9], v[126:129], v[34:49]
	v_exp_f32_e32 v70, v70
	v_exp_f32_e32 v71, v71
	v_exp_f32_e32 v72, v72
	v_exp_f32_e32 v73, v73
	s_waitcnt lgkmcnt(10)
	v_mfma_f32_32x32x16_bf16 v[18:33], v[2:5], v[102:105], v[18:33]
	v_exp_f32_e32 v74, v74
	v_exp_f32_e32 v75, v75
	v_exp_f32_e32 v76, v76
	v_exp_f32_e32 v77, v77
	s_waitcnt lgkmcnt(8)
	v_mfma_f32_32x32x16_bf16 v[34:49], v[2:5], v[106:109], v[34:49]
	v_exp_f32_e32 v78, v78
	v_exp_f32_e32 v79, v79
	v_exp_f32_e32 v80, v80
	v_exp_f32_e32 v81, v81
	s_add_i32 s34, s30, 0x2000
	s_cmpk_lg_i32 s30, 0x4000
	s_mov_b32 s31, s28
	s_cselect_b32 s28, s34, 0
	s_add_i32 s27, s27, 2
	s_add_u32 s23, s23, 0x90000
	s_addc_u32 s24, s24, 0
	s_waitcnt vmcnt(2) lgkmcnt(0)
	s_barrier
	s_add_u32 s2, s2, 0x90000
	v_add_f32_e32 v2, v194, v195
	s_addc_u32 s22, s22, 0
	s_mov_b32 s29, s30
	v_add_f32_e32 v194, v2, v196
	s_cmpk_gt_u32 s27, 0x7c
	s_cbranch_scc0 .LBB0_876
; #define WAIT_BAR(N) asm volatile("s_waitcnt vmcnt(" #N ") lgkmcnt(0)\n\ts_barrier" ::: "memory")
; #define RESC() do { if (resc) { asm volatile("s_waitcnt lgkmcnt(0)" ::: "memory"); \
;       _Pragma("unroll") for (int d_ = 0; d_ < 2; ++d_) _Pragma("unroll") for (int r = 0; r < 16; ++r) o[d_][r] *= wsf[crow(r, hi)]; } } while (0)
; #define ROT() do { sl_prev = sl_cur; sl_cur = sl_next; sl_next = (sl_next == (NSLOT - 1) * SLOTB) ? 0 : sl_next + SLOTB; } while (0)
; #define ENDW(tt) do { if ((tt) + 3 < NT) { WAIT_BAR(2); } else if ((tt) + 2 < NT) { WAIT_BAR(1); } else { WAIT_BAR(0); } } while (0)
;     ...
;     int t = 1;
;     for (; t + 5 < NT; t += 2) {
;         STEP(pB0, pB1, pA0, pA1, t, true, true, true);     WAIT_BAR(2); RESC(); ROT();
;         STEP(pA0, pA1, pB0, pB1, t + 1, true, true, true); WAIT_BAR(2); RESC(); ROT();
;     }
;     ...
;     for (; t + 1 < NT; t += 2) {
;         STEP(pB0, pB1, pA0, pA1, t, (t + 3 < NT), (t + 1 < NT), (t + 1 < NT));         ENDW(t);     RESC(); ROT();
;         STEP(pA0, pA1, pB0, pB1, t + 1, (t + 4 < NT), (t + 2 < NT), (t + 2 < NT));     ENDW(t + 1); RESC(); ROT();
	s_and_b32 s2, s25, 0x3fffffc0
	s_lshl_b32 s2, s2, 2
	s_add_i32 s2, s2, 0
	ds_read_b64_tr_b16 v[182:183], v190 offset:24576
	ds_read_b64_tr_b16 v[184:185], v190 offset:25088
	v_add_f32_e32 v2, v82, v83
	v_add_f32_e32 v2, v84, v2
	v_add_f32_e32 v2, v85, v2
	v_add_f32_e32 v2, v86, v2
	v_add_f32_e32 v2, v87, v2
	v_cvt_pk_bf16_f32 v146, v82, v83
	v_cvt_pk_bf16_f32 v147, v84, v85
	s_waitcnt lgkmcnt(9)
	v_mfma_f32_32x32x16_bf16 v[114:129], v[98:101], v[162:165], v[50:65]
	ds_read_b64_tr_b16 v[178:179], v190 offset:28672
	ds_read_b64_tr_b16 v[180:181], v190 offset:29184
	v_add_f32_e32 v2, v88, v2
	v_add_f32_e32 v2, v89, v2
	v_add_f32_e32 v2, v90, v2
	v_add_f32_e32 v2, v91, v2
	v_cvt_pk_bf16_f32 v148, v86, v87
	v_cvt_pk_bf16_f32 v149, v88, v89
	s_waitcnt lgkmcnt(10)
	v_mfma_f32_32x32x16_bf16 v[98:113], v[170:173], v[162:165], v[50:65]
	ds_read_b64_tr_b16 v[82:83], v190 offset:25600
	ds_read_b64_tr_b16 v[84:85], v190 offset:26112
	v_add_f32_e32 v2, v92, v2
	v_add_f32_e32 v2, v93, v2
	v_add_f32_e32 v2, v94, v2
	v_add_f32_e32 v2, v95, v2
	v_cvt_pk_bf16_f32 v10, v90, v91
	v_cvt_pk_bf16_f32 v11, v92, v93
	s_waitcnt lgkmcnt(11)
	v_mfma_f32_32x32x16_bf16 v[114:129], v[174:177], v[158:161], v[114:129]
	ds_read_b64_tr_b16 v[86:87], v190 offset:29696
	ds_read_b64_tr_b16 v[88:89], v190 offset:30208
	v_add_f32_e32 v2, v96, v2
	v_add_f32_e32 v2, v97, v2
	v_add_f32_e32 v2, v66, v2
	v_add_f32_e32 v2, v67, v2
	v_cvt_pk_bf16_f32 v12, v94, v95
	v_cvt_pk_bf16_f32 v13, v96, v97
	s_waitcnt lgkmcnt(12)
	v_mfma_f32_32x32x16_bf16 v[98:113], v[166:169], v[158:161], v[98:113]
	ds_read_b64_tr_b16 v[90:91], v190 offset:26624
	ds_read_b64_tr_b16 v[92:93], v190 offset:27136
	v_add_f32_e32 v2, v68, v2
	v_add_f32_e32 v2, v69, v2
	v_add_f32_e32 v2, v70, v2
	v_add_f32_e32 v2, v71, v2
	v_cvt_pk_bf16_f32 v6, v66, v67
	v_cvt_pk_bf16_f32 v7, v68, v69
	s_waitcnt lgkmcnt(13)
	v_mfma_f32_32x32x16_bf16 v[114:129], v[142:145], v[154:157], v[114:129]
	ds_read_b64_tr_b16 v[66:67], v190 offset:30720
	ds_read_b64_tr_b16 v[68:69], v190 offset:31232
	v_add_f32_e32 v2, v72, v2
	v_add_f32_e32 v2, v73, v2
	v_add_f32_e32 v2, v74, v2
	v_add_f32_e32 v2, v75, v2
	v_cvt_pk_bf16_f32 v8, v70, v71
	v_cvt_pk_bf16_f32 v9, v72, v73
	s_waitcnt lgkmcnt(14)
	v_mfma_f32_32x32x16_bf16 v[98:113], v[138:141], v[154:157], v[98:113]
	ds_read_b64_tr_b16 v[70:71], v190 offset:27648
	ds_read_b64_tr_b16 v[72:73], v190 offset:28160
	v_add_f32_e32 v2, v76, v2
	v_add_f32_e32 v2, v77, v2
	v_add_f32_e32 v2, v78, v2
	v_add_f32_e32 v94, v79, v2
	v_cvt_pk_bf16_f32 v2, v74, v75
	v_cvt_pk_bf16_f32 v3, v76, v77
	s_waitcnt lgkmcnt(14)
	v_mfma_f32_32x32x16_bf16 v[114:129], v[134:137], v[150:153], v[114:129]
	ds_read_b64_tr_b16 v[74:75], v190 offset:31744
	ds_read_b64_tr_b16 v[76:77], v190 offset:32256
	v_add_f32_e32 v4, v80, v94
	v_add_f32_e32 v4, v81, v4
	v_add_f32_e32 v94, 0, v4
	v_cvt_pk_bf16_f32 v4, v78, v79
	v_cvt_pk_bf16_f32 v5, v80, v81
	v_mfma_f32_32x32x16_bf16 v[98:113], v[130:133], v[150:153], v[98:113]
	s_add_u32 s16, s14, 0x2490000
	s_addc_u32 s17, s15, 0
	s_cmp_lg_u32 0, -1
	s_cselect_b32 s23, 0, 0
	s_add_i32 s22, s23, s21
	s_add_i32 s24, s22, 0x2000
	s_mov_b32 s25, m0
	s_mov_b32 m0, s24
	s_nop 0
	global_load_lds_dwordx4 v193, s[16:17]
	s_mov_b32 m0, s25
	s_add_u32 s24, s12, 0x2400000
	s_addc_u32 s25, s13, 0
	s_add_i32 s16, s23, 0xa000
	s_add_i32 s17, s21, s16
	s_mov_b32 s21, m0
	s_mov_b32 m0, s17
	s_nop 0
	global_load_lds_dwordx4 v192, s[24:25]
	s_mov_b32 m0, s21
	v_add_f32_e32 v194, v194, v94
	s_waitcnt lgkmcnt(14)
	v_mfma_f32_32x32x16_bf16 v[18:33], v[146:149], v[182:185], v[18:33]
	v_exp_f32_e32 v114, v114
	v_exp_f32_e32 v115, v115
	v_exp_f32_e32 v116, v116
	v_exp_f32_e32 v117, v117
	s_waitcnt lgkmcnt(12)
	v_mfma_f32_32x32x16_bf16 v[34:49], v[146:149], v[178:181], v[34:49]
	v_exp_f32_e32 v118, v118
	v_exp_f32_e32 v119, v119
	v_exp_f32_e32 v120, v120
	v_exp_f32_e32 v121, v121
	ds_read_b128 v[78:81], v191 offset:16384
	ds_read_b128 v[94:97], v191 offset:16896
	s_waitcnt lgkmcnt(12)
	v_mfma_f32_32x32x16_bf16 v[18:33], v[10:13], v[82:85], v[18:33]
	v_exp_f32_e32 v122, v122
	v_exp_f32_e32 v123, v123
	v_exp_f32_e32 v124, v124
	v_exp_f32_e32 v125, v125
	ds_read_b128 v[166:169], v191 offset:18432
	ds_read_b128 v[170:173], v191 offset:18944
	s_waitcnt lgkmcnt(12)
	v_mfma_f32_32x32x16_bf16 v[34:49], v[10:13], v[86:89], v[34:49]
	v_exp_f32_e32 v126, v126
	v_exp_f32_e32 v127, v127
	v_exp_f32_e32 v128, v128
	v_exp_f32_e32 v129, v129
	ds_read_b128 v[174:177], v191 offset:20480
	ds_read_b128 v[178:181], v191 offset:20992
	s_waitcnt lgkmcnt(12)
	v_mfma_f32_32x32x16_bf16 v[18:33], v[6:9], v[90:93], v[18:33]
	v_exp_f32_e32 v98, v98
	v_exp_f32_e32 v99, v99
	v_exp_f32_e32 v100, v100
	v_exp_f32_e32 v101, v101
	ds_read_b128 v[90:93], v191 offset:22528
	ds_read_b128 v[82:85], v191 offset:23040
	s_waitcnt lgkmcnt(12)
	v_mfma_f32_32x32x16_bf16 v[34:49], v[6:9], v[66:69], v[34:49]
	v_exp_f32_e32 v102, v102
	v_exp_f32_e32 v103, v103
	v_exp_f32_e32 v104, v104
	v_exp_f32_e32 v105, v105
	s_waitcnt lgkmcnt(10)
	v_mfma_f32_32x32x16_bf16 v[18:33], v[2:5], v[70:73], v[18:33]
	v_exp_f32_e32 v106, v106
	v_exp_f32_e32 v107, v107
	v_exp_f32_e32 v108, v108
	v_exp_f32_e32 v109, v109
	s_waitcnt lgkmcnt(8)
	v_mfma_f32_32x32x16_bf16 v[34:49], v[2:5], v[74:77], v[34:49]
	v_exp_f32_e32 v110, v110
	v_exp_f32_e32 v111, v111
	v_exp_f32_e32 v112, v112
	v_exp_f32_e32 v113, v113
	s_waitcnt vmcnt(2) lgkmcnt(0)
	s_barrier
; #define WAIT_BAR(N) asm volatile("s_waitcnt vmcnt(" #N ") lgkmcnt(0)\n\ts_barrier" ::: "memory")
; #define RESC() do { if (resc) { asm volatile("s_waitcnt lgkmcnt(0)" ::: "memory"); \
;       _Pragma("unroll") for (int d_ = 0; d_ < 2; ++d_) _Pragma("unroll") for (int r = 0; r < 16; ++r) o[d_][r] *= wsf[crow(r, hi)]; } } while (0)
; #define ROT() do { sl_prev = sl_cur; sl_cur = sl_next; sl_next = (sl_next == (NSLOT - 1) * SLOTB) ? 0 : sl_next + SLOTB; } while (0)
; #define ENDW(tt) do { if ((tt) + 3 < NT) { WAIT_BAR(2); } else if ((tt) + 2 < NT) { WAIT_BAR(1); } else { WAIT_BAR(0); } } while (0)
;     ...
;     int t = 1;
;     for (; t + 5 < NT; t += 2) {
;         STEP(pB0, pB1, pA0, pA1, t, true, true, true);     WAIT_BAR(2); RESC(); ROT();
;         STEP(pA0, pA1, pB0, pB1, t + 1, true, true, true); WAIT_BAR(2); RESC(); ROT();
;     }
;     ...
;     for (; t + 1 < NT; t += 2) {
;         STEP(pB0, pB1, pA0, pA1, t, (t + 3 < NT), (t + 1 < NT), (t + 1 < NT));         ENDW(t);     RESC(); ROT();
;         STEP(pA0, pA1, pB0, pB1, t + 1, (t + 4 < NT), (t + 2 < NT), (t + 2 < NT));     ENDW(t + 1); RESC(); ROT();
	ds_read_b64_tr_b16 v[182:183], v190 offset:32768
	ds_read_b64_tr_b16 v[184:185], v190 offset:33280
	v_add_f32_e32 v2, v114, v115
	v_add_f32_e32 v2, v116, v2
	v_add_f32_e32 v2, v117, v2
	v_add_f32_e32 v2, v118, v2
	v_add_f32_e32 v2, v119, v2
	v_cvt_pk_bf16_f32 v146, v114, v115
	v_cvt_pk_bf16_f32 v147, v116, v117
	s_waitcnt lgkmcnt(9)
	v_mfma_f32_32x32x16_bf16 v[130:145], v[78:81], v[162:165], v[50:65]
	ds_read_b64_tr_b16 v[114:115], v190 offset:36864
	ds_read_b64_tr_b16 v[116:117], v190 offset:37376
	s_waitcnt lgkmcnt(10)
	v_mfma_f32_32x32x16_bf16 v[66:81], v[94:97], v[162:165], v[50:65]
	v_add_f32_e32 v2, v120, v2
	v_add_f32_e32 v2, v121, v2
	v_add_f32_e32 v2, v122, v2
	v_add_f32_e32 v2, v123, v2
	v_cvt_pk_bf16_f32 v148, v118, v119
	v_cvt_pk_bf16_f32 v149, v120, v121
	ds_read_b64_tr_b16 v[86:87], v190 offset:33792
	ds_read_b64_tr_b16 v[88:89], v190 offset:34304
	v_add_f32_e32 v2, v124, v2
	v_add_f32_e32 v2, v125, v2
	v_add_f32_e32 v2, v126, v2
	v_add_f32_e32 v2, v127, v2
	v_cvt_pk_bf16_f32 v10, v122, v123
	v_cvt_pk_bf16_f32 v11, v124, v125
	s_waitcnt lgkmcnt(11)
	v_mfma_f32_32x32x16_bf16 v[130:145], v[166:169], v[158:161], v[130:145]
	ds_read_b64_tr_b16 v[94:95], v190 offset:37888
	ds_read_b64_tr_b16 v[96:97], v190 offset:38400
	s_waitcnt lgkmcnt(12)
	v_mfma_f32_32x32x16_bf16 v[66:81], v[170:173], v[158:161], v[66:81]
	v_add_f32_e32 v2, v128, v2
	v_add_f32_e32 v2, v129, v2
	v_add_f32_e32 v2, v98, v2
	v_add_f32_e32 v2, v99, v2
	v_cvt_pk_bf16_f32 v12, v126, v127
	v_cvt_pk_bf16_f32 v13, v128, v129
	ds_read_b64_tr_b16 v[118:119], v190 offset:34816
	ds_read_b64_tr_b16 v[120:121], v190 offset:35328
	v_add_f32_e32 v2, v100, v2
	v_add_f32_e32 v2, v101, v2
	v_add_f32_e32 v2, v102, v2
	v_add_f32_e32 v2, v103, v2
	v_cvt_pk_bf16_f32 v6, v98, v99
	v_cvt_pk_bf16_f32 v7, v100, v101
	s_waitcnt lgkmcnt(13)
	v_mfma_f32_32x32x16_bf16 v[130:145], v[174:177], v[154:157], v[130:145]
	ds_read_b64_tr_b16 v[122:123], v190 offset:38912
	ds_read_b64_tr_b16 v[124:125], v190 offset:39424
	s_waitcnt lgkmcnt(14)
	v_mfma_f32_32x32x16_bf16 v[66:81], v[178:181], v[154:157], v[66:81]
	v_add_f32_e32 v2, v104, v2
	v_add_f32_e32 v2, v105, v2
	v_add_f32_e32 v2, v106, v2
	v_add_f32_e32 v2, v107, v2
	v_cvt_pk_bf16_f32 v8, v102, v103
	v_cvt_pk_bf16_f32 v9, v104, v105
	ds_read_b64_tr_b16 v[102:103], v190 offset:35840
	ds_read_b64_tr_b16 v[104:105], v190 offset:36352
	v_add_f32_e32 v2, v108, v2
	v_add_f32_e32 v2, v109, v2
	v_add_f32_e32 v2, v110, v2
	v_add_f32_e32 v98, v111, v2
	v_cvt_pk_bf16_f32 v2, v106, v107
	v_cvt_pk_bf16_f32 v3, v108, v109
	s_waitcnt lgkmcnt(14)
	v_mfma_f32_32x32x16_bf16 v[130:145], v[90:93], v[150:153], v[130:145]
	ds_read_b64_tr_b16 v[90:91], v190 offset:39936
	ds_read_b64_tr_b16 v[92:93], v190 offset:40448
	v_mfma_f32_32x32x16_bf16 v[66:81], v[82:85], v[150:153], v[66:81]
	v_add_f32_e32 v4, v112, v98
	v_add_f32_e32 v4, v113, v4
	v_add_f32_e32 v82, 0, v4
	v_cvt_pk_bf16_f32 v4, v110, v111
	v_cvt_pk_bf16_f32 v5, v112, v113
	s_add_u32 s14, s14, 0x24d8000
	s_addc_u32 s15, s15, 0
	s_add_i32 s21, s22, 0x4000
	s_mov_b32 s23, m0
	s_mov_b32 m0, s21
	s_nop 0
	global_load_lds_dwordx4 v193, s[14:15]
	s_mov_b32 m0, s23
	s_add_u32 s14, s12, 0x2448000
	s_addc_u32 s15, s13, 0
	s_mov_b32 s21, m0
	s_mov_b32 m0, s20
	s_nop 0
	global_load_lds_dwordx4 v192, s[14:15]
	s_mov_b32 m0, s21
	v_add_f32_e32 v194, v194, v82
	s_waitcnt lgkmcnt(14)
	v_mfma_f32_32x32x16_bf16 v[18:33], v[146:149], v[182:185], v[18:33]
	v_exp_f32_e32 v130, v130
	v_exp_f32_e32 v131, v131
	v_exp_f32_e32 v132, v132
	v_exp_f32_e32 v133, v133
	s_waitcnt lgkmcnt(12)
	v_mfma_f32_32x32x16_bf16 v[34:49], v[146:149], v[114:117], v[34:49]
	v_exp_f32_e32 v134, v134
	v_exp_f32_e32 v135, v135
	v_exp_f32_e32 v136, v136
	v_exp_f32_e32 v137, v137
	ds_read_b128 v[82:85], v191
	ds_read_b128 v[106:109], v191 offset:512
	s_waitcnt lgkmcnt(12)
	v_mfma_f32_32x32x16_bf16 v[18:33], v[10:13], v[86:89], v[18:33]
	v_exp_f32_e32 v138, v138
	v_exp_f32_e32 v139, v139
	v_exp_f32_e32 v140, v140
	v_exp_f32_e32 v141, v141
	ds_read_b128 v[110:113], v191 offset:2048
	ds_read_b128 v[166:169], v191 offset:2560
	s_waitcnt lgkmcnt(12)
	v_mfma_f32_32x32x16_bf16 v[34:49], v[10:13], v[94:97], v[34:49]
	v_exp_f32_e32 v142, v142
	v_exp_f32_e32 v143, v143
	v_exp_f32_e32 v144, v144
	v_exp_f32_e32 v145, v145
	ds_read_b128 v[170:173], v191 offset:4096
	ds_read_b128 v[174:177], v191 offset:4608
	s_waitcnt lgkmcnt(12)
	v_mfma_f32_32x32x16_bf16 v[18:33], v[6:9], v[118:121], v[18:33]
	v_exp_f32_e32 v66, v66
	v_exp_f32_e32 v67, v67
	v_exp_f32_e32 v68, v68
	v_exp_f32_e32 v69, v69
	ds_read_b128 v[178:181], v191 offset:6144
	ds_read_b128 v[98:101], v191 offset:6656
	s_waitcnt lgkmcnt(12)
	v_mfma_f32_32x32x16_bf16 v[34:49], v[6:9], v[122:125], v[34:49]
	v_exp_f32_e32 v70, v70
	v_exp_f32_e32 v71, v71
	v_exp_f32_e32 v72, v72
	v_exp_f32_e32 v73, v73
	s_waitcnt lgkmcnt(10)
	v_mfma_f32_32x32x16_bf16 v[18:33], v[2:5], v[102:105], v[18:33]
	v_exp_f32_e32 v74, v74
	v_exp_f32_e32 v75, v75
	v_exp_f32_e32 v76, v76
	v_exp_f32_e32 v77, v77
	s_waitcnt lgkmcnt(8)
	v_mfma_f32_32x32x16_bf16 v[34:49], v[2:5], v[90:93], v[34:49]
	v_exp_f32_e32 v78, v78
	v_exp_f32_e32 v79, v79
	v_exp_f32_e32 v80, v80
	v_exp_f32_e32 v81, v81
	s_waitcnt vmcnt(2) lgkmcnt(0)
	s_barrier
; #define WAIT_BAR(N) asm volatile("s_waitcnt vmcnt(" #N ") lgkmcnt(0)\n\ts_barrier" ::: "memory")
; #define RESC() do { if (resc) { asm volatile("s_waitcnt lgkmcnt(0)" ::: "memory"); \
;       _Pragma("unroll") for (int d_ = 0; d_ < 2; ++d_) _Pragma("unroll") for (int r = 0; r < 16; ++r) o[d_][r] *= wsf[crow(r, hi)]; } } while (0)
; #define ROT() do { sl_prev = sl_cur; sl_cur = sl_next; sl_next = (sl_next == (NSLOT - 1) * SLOTB) ? 0 : sl_next + SLOTB; } while (0)
; #define ENDW(tt) do { if ((tt) + 3 < NT) { WAIT_BAR(2); } else if ((tt) + 2 < NT) { WAIT_BAR(1); } else { WAIT_BAR(0); } } while (0)
;     ...
;     int t = 1;
;     for (; t + 5 < NT; t += 2) {
;         STEP(pB0, pB1, pA0, pA1, t, true, true, true);     WAIT_BAR(2); RESC(); ROT();
;         STEP(pA0, pA1, pB0, pB1, t + 1, true, true, true); WAIT_BAR(2); RESC(); ROT();
;     }
;     ...
;     for (; t + 1 < NT; t += 2) {
;         STEP(pB0, pB1, pA0, pA1, t, (t + 3 < NT), (t + 1 < NT), (t + 1 < NT));         ENDW(t);     RESC(); ROT();
;         STEP(pA0, pA1, pB0, pB1, t + 1, (t + 4 < NT), (t + 2 < NT), (t + 2 < NT));     ENDW(t + 1); RESC(); ROT();
	ds_read_b64_tr_b16 v[102:103], v190 offset:40960
	ds_read_b64_tr_b16 v[104:105], v190 offset:41472
	v_add_f32_e32 v2, v130, v131
	v_add_f32_e32 v2, v132, v2
	v_add_f32_e32 v2, v133, v2
	v_add_f32_e32 v2, v134, v2
	v_add_f32_e32 v2, v135, v2
	v_cvt_pk_bf16_f32 v146, v130, v131
	v_cvt_pk_bf16_f32 v147, v132, v133
	s_waitcnt lgkmcnt(9)
	v_mfma_f32_32x32x16_bf16 v[114:129], v[82:85], v[162:165], v[50:65]
	ds_read_b64_tr_b16 v[130:131], v190 offset:45056
	ds_read_b64_tr_b16 v[132:133], v190 offset:45568
	v_add_f32_e32 v2, v136, v2
	v_add_f32_e32 v2, v137, v2
	v_add_f32_e32 v2, v138, v2
	v_add_f32_e32 v2, v139, v2
	v_cvt_pk_bf16_f32 v148, v134, v135
	v_cvt_pk_bf16_f32 v149, v136, v137
	s_waitcnt lgkmcnt(10)
	v_mfma_f32_32x32x16_bf16 v[82:97], v[106:109], v[162:165], v[50:65]
	ds_read_b64_tr_b16 v[106:107], v190 offset:41984
	ds_read_b64_tr_b16 v[108:109], v190 offset:42496
	v_add_f32_e32 v2, v140, v2
	v_add_f32_e32 v2, v141, v2
	v_add_f32_e32 v2, v142, v2
	v_add_f32_e32 v2, v143, v2
	v_cvt_pk_bf16_f32 v10, v138, v139
	v_cvt_pk_bf16_f32 v11, v140, v141
	s_waitcnt lgkmcnt(11)
	v_mfma_f32_32x32x16_bf16 v[114:129], v[110:113], v[158:161], v[114:129]
	ds_read_b64_tr_b16 v[110:111], v190 offset:46080
	ds_read_b64_tr_b16 v[112:113], v190 offset:46592
	v_add_f32_e32 v2, v144, v2
	v_add_f32_e32 v2, v145, v2
	v_add_f32_e32 v2, v66, v2
	v_add_f32_e32 v2, v67, v2
	v_cvt_pk_bf16_f32 v12, v142, v143
	v_cvt_pk_bf16_f32 v13, v144, v145
	s_waitcnt lgkmcnt(12)
	v_mfma_f32_32x32x16_bf16 v[82:97], v[166:169], v[158:161], v[82:97]
	ds_read_b64_tr_b16 v[134:135], v190 offset:43008
	ds_read_b64_tr_b16 v[136:137], v190 offset:43520
	v_add_f32_e32 v2, v68, v2
	v_add_f32_e32 v2, v69, v2
	v_add_f32_e32 v2, v70, v2
	v_add_f32_e32 v2, v71, v2
	v_cvt_pk_bf16_f32 v6, v66, v67
	v_cvt_pk_bf16_f32 v7, v68, v69
	s_waitcnt lgkmcnt(13)
	v_mfma_f32_32x32x16_bf16 v[114:129], v[170:173], v[154:157], v[114:129]
	ds_read_b64_tr_b16 v[66:67], v190 offset:47104
	ds_read_b64_tr_b16 v[68:69], v190 offset:47616
	v_add_f32_e32 v2, v72, v2
	v_add_f32_e32 v2, v73, v2
	v_add_f32_e32 v2, v74, v2
	v_add_f32_e32 v2, v75, v2
	v_cvt_pk_bf16_f32 v8, v70, v71
	v_cvt_pk_bf16_f32 v9, v72, v73
	s_waitcnt lgkmcnt(14)
	v_mfma_f32_32x32x16_bf16 v[82:97], v[174:177], v[154:157], v[82:97]
	ds_read_b64_tr_b16 v[70:71], v190 offset:44032
	ds_read_b64_tr_b16 v[72:73], v190 offset:44544
	v_add_f32_e32 v2, v76, v2
	v_add_f32_e32 v2, v77, v2
	v_add_f32_e32 v2, v78, v2
	v_add_f32_e32 v138, v79, v2
	v_cvt_pk_bf16_f32 v2, v74, v75
	v_cvt_pk_bf16_f32 v3, v76, v77
	s_waitcnt lgkmcnt(14)
	v_mfma_f32_32x32x16_bf16 v[114:129], v[178:181], v[150:153], v[114:129]
	ds_read_b64_tr_b16 v[74:75], v190 offset:48128
	ds_read_b64_tr_b16 v[76:77], v190 offset:48640
	v_add_f32_e32 v4, v80, v138
	v_add_f32_e32 v4, v81, v4
	v_mfma_f32_32x32x16_bf16 v[82:97], v[98:101], v[150:153], v[82:97]
	v_add_f32_e32 v98, 0, v4
	v_cvt_pk_bf16_f32 v4, v78, v79
	v_cvt_pk_bf16_f32 v5, v80, v81
	s_add_u32 s14, s12, 0x2490000
	s_addc_u32 s15, s13, 0
	s_add_i32 s22, s22, 0x8000
	s_mov_b32 s20, m0
	s_mov_b32 m0, s22
	s_nop 0
	global_load_lds_dwordx4 v192, s[14:15]
	s_mov_b32 m0, s20
	v_add_f32_e32 v182, v194, v98
	s_waitcnt lgkmcnt(14)
	v_mfma_f32_32x32x16_bf16 v[18:33], v[146:149], v[102:105], v[18:33]
	v_exp_f32_e32 v114, v114
	v_exp_f32_e32 v115, v115
	v_exp_f32_e32 v116, v116
	v_exp_f32_e32 v117, v117
	s_waitcnt lgkmcnt(12)
	v_mfma_f32_32x32x16_bf16 v[34:49], v[146:149], v[130:133], v[34:49]
	v_exp_f32_e32 v118, v118
	v_exp_f32_e32 v119, v119
	v_exp_f32_e32 v120, v120
	v_exp_f32_e32 v121, v121
	ds_read_b128 v[78:81], v191 offset:8192
	ds_read_b128 v[138:141], v191 offset:8704
	s_waitcnt lgkmcnt(12)
	v_mfma_f32_32x32x16_bf16 v[18:33], v[10:13], v[106:109], v[18:33]
	v_exp_f32_e32 v122, v122
	v_exp_f32_e32 v123, v123
	v_exp_f32_e32 v124, v124
	v_exp_f32_e32 v125, v125
	ds_read_b128 v[142:145], v191 offset:10240
	ds_read_b128 v[166:169], v191 offset:10752
	s_waitcnt lgkmcnt(12)
	v_mfma_f32_32x32x16_bf16 v[34:49], v[10:13], v[110:113], v[34:49]
	v_exp_f32_e32 v126, v126
	v_exp_f32_e32 v127, v127
	v_exp_f32_e32 v128, v128
	v_exp_f32_e32 v129, v129
	ds_read_b128 v[170:173], v191 offset:12288
	ds_read_b128 v[174:177], v191 offset:12800
	s_waitcnt lgkmcnt(12)
	v_mfma_f32_32x32x16_bf16 v[18:33], v[6:9], v[134:137], v[18:33]
	v_exp_f32_e32 v82, v82
	v_exp_f32_e32 v83, v83
	v_exp_f32_e32 v84, v84
	v_exp_f32_e32 v85, v85
	ds_read_b128 v[134:137], v191 offset:14336
	ds_read_b128 v[130:133], v191 offset:14848
	s_waitcnt lgkmcnt(12)
	v_mfma_f32_32x32x16_bf16 v[34:49], v[6:9], v[66:69], v[34:49]
	v_exp_f32_e32 v86, v86
	v_exp_f32_e32 v87, v87
	v_exp_f32_e32 v88, v88
	v_exp_f32_e32 v89, v89
	s_waitcnt lgkmcnt(10)
	v_mfma_f32_32x32x16_bf16 v[18:33], v[2:5], v[70:73], v[18:33]
	v_exp_f32_e32 v90, v90
	v_exp_f32_e32 v91, v91
	v_exp_f32_e32 v92, v92
	v_exp_f32_e32 v93, v93
	s_waitcnt lgkmcnt(8)
	v_mfma_f32_32x32x16_bf16 v[34:49], v[2:5], v[74:77], v[34:49]
	v_exp_f32_e32 v94, v94
	v_exp_f32_e32 v95, v95
	v_exp_f32_e32 v96, v96
	v_exp_f32_e32 v97, v97
	s_waitcnt vmcnt(1) lgkmcnt(0)
	s_barrier
; #define WAIT_BAR(N) asm volatile("s_waitcnt vmcnt(" #N ") lgkmcnt(0)\n\ts_barrier" ::: "memory")
; #define RESC() do { if (resc) { asm volatile("s_waitcnt lgkmcnt(0)" ::: "memory"); \
;       _Pragma("unroll") for (int d_ = 0; d_ < 2; ++d_) _Pragma("unroll") for (int r = 0; r < 16; ++r) o[d_][r] *= wsf[crow(r, hi)]; } } while (0)
; #define ROT() do { sl_prev = sl_cur; sl_cur = sl_next; sl_next = (sl_next == (NSLOT - 1) * SLOTB) ? 0 : sl_next + SLOTB; } while (0)
; #define ENDW(tt) do { if ((tt) + 3 < NT) { WAIT_BAR(2); } else if ((tt) + 2 < NT) { WAIT_BAR(1); } else { WAIT_BAR(0); } } while (0)
;     ...
;     int t = 1;
;     for (; t + 5 < NT; t += 2) {
;         STEP(pB0, pB1, pA0, pA1, t, true, true, true);     WAIT_BAR(2); RESC(); ROT();
;         STEP(pA0, pA1, pB0, pB1, t + 1, true, true, true); WAIT_BAR(2); RESC(); ROT();
;     }
;     ...
;     for (; t + 1 < NT; t += 2) {
;         STEP(pB0, pB1, pA0, pA1, t, (t + 3 < NT), (t + 1 < NT), (t + 1 < NT));         ENDW(t);     RESC(); ROT();
;         STEP(pA0, pA1, pB0, pB1, t + 1, (t + 4 < NT), (t + 2 < NT), (t + 2 < NT));     ENDW(t + 1); RESC(); ROT();
	ds_read_b64_tr_b16 v[178:179], v190 offset:24576
	ds_read_b64_tr_b16 v[180:181], v190 offset:25088
	v_add_f32_e32 v2, v114, v115
	v_add_f32_e32 v2, v116, v2
	v_add_f32_e32 v2, v117, v2
	v_add_f32_e32 v2, v118, v2
	v_add_f32_e32 v2, v119, v2
	v_cvt_pk_bf16_f32 v146, v114, v115
	v_cvt_pk_bf16_f32 v147, v116, v117
	s_waitcnt lgkmcnt(9)
	v_mfma_f32_32x32x16_bf16 v[98:113], v[78:81], v[162:165], v[50:65]
	ds_read_b64_tr_b16 v[114:115], v190 offset:28672
	ds_read_b64_tr_b16 v[116:117], v190 offset:29184
	s_waitcnt lgkmcnt(10)
	v_mfma_f32_32x32x16_bf16 v[66:81], v[138:141], v[162:165], v[50:65]
	v_add_f32_e32 v2, v120, v2
	v_add_f32_e32 v2, v121, v2
	v_add_f32_e32 v2, v122, v2
	v_add_f32_e32 v2, v123, v2
	v_cvt_pk_bf16_f32 v148, v118, v119
	v_cvt_pk_bf16_f32 v149, v120, v121
	ds_read_b64_tr_b16 v[118:119], v190 offset:25600
	ds_read_b64_tr_b16 v[120:121], v190 offset:26112
	v_add_f32_e32 v2, v124, v2
	v_add_f32_e32 v2, v125, v2
	v_add_f32_e32 v2, v126, v2
	v_add_f32_e32 v2, v127, v2
	v_cvt_pk_bf16_f32 v10, v122, v123
	v_cvt_pk_bf16_f32 v11, v124, v125
	s_waitcnt lgkmcnt(11)
	v_mfma_f32_32x32x16_bf16 v[98:113], v[142:145], v[158:161], v[98:113]
	ds_read_b64_tr_b16 v[122:123], v190 offset:29696
	ds_read_b64_tr_b16 v[124:125], v190 offset:30208
	s_waitcnt lgkmcnt(12)
	v_mfma_f32_32x32x16_bf16 v[66:81], v[166:169], v[158:161], v[66:81]
	v_add_f32_e32 v2, v128, v2
	v_add_f32_e32 v2, v129, v2
	v_add_f32_e32 v2, v82, v2
	v_add_f32_e32 v2, v83, v2
	v_cvt_pk_bf16_f32 v12, v126, v127
	v_cvt_pk_bf16_f32 v13, v128, v129
	ds_read_b64_tr_b16 v[138:139], v190 offset:26624
	ds_read_b64_tr_b16 v[140:141], v190 offset:27136
	v_add_f32_e32 v2, v84, v2
	v_add_f32_e32 v2, v85, v2
	v_add_f32_e32 v2, v86, v2
	v_add_f32_e32 v2, v87, v2
	v_cvt_pk_bf16_f32 v6, v82, v83
	v_cvt_pk_bf16_f32 v7, v84, v85
	s_waitcnt lgkmcnt(13)
	v_mfma_f32_32x32x16_bf16 v[98:113], v[170:173], v[154:157], v[98:113]
	ds_read_b64_tr_b16 v[82:83], v190 offset:30720
	ds_read_b64_tr_b16 v[84:85], v190 offset:31232
	s_waitcnt lgkmcnt(14)
	v_mfma_f32_32x32x16_bf16 v[66:81], v[174:177], v[154:157], v[66:81]
	v_add_f32_e32 v2, v88, v2
	v_add_f32_e32 v2, v89, v2
	v_add_f32_e32 v2, v90, v2
	v_add_f32_e32 v2, v91, v2
	v_cvt_pk_bf16_f32 v8, v86, v87
	v_cvt_pk_bf16_f32 v9, v88, v89
	ds_read_b64_tr_b16 v[86:87], v190 offset:27648
	ds_read_b64_tr_b16 v[88:89], v190 offset:28160
	v_add_f32_e32 v2, v92, v2
	v_add_f32_e32 v2, v93, v2
	v_add_f32_e32 v2, v94, v2
	v_add_f32_e32 v126, v95, v2
	v_cvt_pk_bf16_f32 v2, v90, v91
	v_cvt_pk_bf16_f32 v3, v92, v93
	s_waitcnt lgkmcnt(14)
	v_mfma_f32_32x32x16_bf16 v[98:113], v[134:137], v[150:153], v[98:113]
	ds_read_b64_tr_b16 v[90:91], v190 offset:31744
	ds_read_b64_tr_b16 v[92:93], v190 offset:32256
	v_mfma_f32_32x32x16_bf16 v[66:81], v[130:133], v[150:153], v[66:81]
	v_add_f32_e32 v4, v96, v126
	v_add_f32_e32 v4, v97, v4
	v_add_f32_e32 v126, 0, v4
	v_cvt_pk_bf16_f32 v4, v94, v95
	v_cvt_pk_bf16_f32 v5, v96, v97
	s_add_u32 s12, s12, 0x24d8000
	s_addc_u32 s13, s13, 0
	s_mov_b32 s14, m0
	s_mov_b32 m0, s17
	s_nop 0
	global_load_lds_dwordx4 v192, s[12:13]
	s_mov_b32 m0, s14
	v_add_f32_e32 v126, v182, v126
	s_waitcnt lgkmcnt(14)
	v_mfma_f32_32x32x16_bf16 v[18:33], v[146:149], v[178:181], v[18:33]
	v_exp_f32_e32 v98, v98
	v_exp_f32_e32 v99, v99
	v_exp_f32_e32 v100, v100
	v_exp_f32_e32 v101, v101
	s_waitcnt lgkmcnt(12)
	v_mfma_f32_32x32x16_bf16 v[34:49], v[146:149], v[114:117], v[34:49]
	v_exp_f32_e32 v102, v102
	v_exp_f32_e32 v103, v103
	v_exp_f32_e32 v104, v104
	v_exp_f32_e32 v105, v105
	ds_read_b128 v[128:131], v191 offset:16384
	ds_read_b128 v[132:135], v191 offset:16896
	s_waitcnt lgkmcnt(12)
	v_mfma_f32_32x32x16_bf16 v[18:33], v[10:13], v[118:121], v[18:33]
	v_exp_f32_e32 v106, v106
	v_exp_f32_e32 v107, v107
	v_exp_f32_e32 v108, v108
	v_exp_f32_e32 v109, v109
	ds_read_b128 v[142:145], v191 offset:18432
	ds_read_b128 v[166:169], v191 offset:18944
	s_waitcnt lgkmcnt(12)
	v_mfma_f32_32x32x16_bf16 v[34:49], v[10:13], v[122:125], v[34:49]
	v_exp_f32_e32 v110, v110
	v_exp_f32_e32 v111, v111
	v_exp_f32_e32 v112, v112
	v_exp_f32_e32 v113, v113
	ds_read_b128 v[170:173], v191 offset:20480
	ds_read_b128 v[174:177], v191 offset:20992
	s_waitcnt lgkmcnt(12)
	v_mfma_f32_32x32x16_bf16 v[18:33], v[6:9], v[138:141], v[18:33]
	v_exp_f32_e32 v66, v66
	v_exp_f32_e32 v67, v67
	v_exp_f32_e32 v68, v68
	v_exp_f32_e32 v69, v69
	ds_read_b128 v[136:139], v191 offset:22528
	ds_read_b128 v[122:125], v191 offset:23040
	s_waitcnt lgkmcnt(12)
	v_mfma_f32_32x32x16_bf16 v[34:49], v[6:9], v[82:85], v[34:49]
	v_exp_f32_e32 v70, v70
	v_exp_f32_e32 v71, v71
	v_exp_f32_e32 v72, v72
	v_exp_f32_e32 v73, v73
	s_waitcnt lgkmcnt(10)
	v_mfma_f32_32x32x16_bf16 v[18:33], v[2:5], v[86:89], v[18:33]
	v_exp_f32_e32 v74, v74
	v_exp_f32_e32 v75, v75
	v_exp_f32_e32 v76, v76
	v_exp_f32_e32 v77, v77
	s_waitcnt lgkmcnt(8)
	v_mfma_f32_32x32x16_bf16 v[34:49], v[2:5], v[90:93], v[34:49]
	v_exp_f32_e32 v78, v78
	v_exp_f32_e32 v79, v79
	v_exp_f32_e32 v80, v80
	v_exp_f32_e32 v81, v81
	s_waitcnt vmcnt(0) lgkmcnt(0)
	s_barrier
; #define SBAR() __builtin_amdgcn_sched_barrier(0)
; #define WAIT_BAR(N) asm volatile("s_waitcnt vmcnt(" #N ") lgkmcnt(0)\n\ts_barrier" ::: "memory")
; #define RESC() do { if (resc) { asm volatile("s_waitcnt lgkmcnt(0)" ::: "memory"); \
;       _Pragma("unroll") for (int d_ = 0; d_ < 2; ++d_) _Pragma("unroll") for (int r = 0; r < 16; ++r) o[d_][r] *= wsf[crow(r, hi)]; } } while (0)
; #define ROT() do { sl_prev = sl_cur; sl_cur = sl_next; sl_next = (sl_next == (NSLOT - 1) * SLOTB) ? 0 : sl_next + SLOTB; } while (0)
; #define PKW(P, B) cvtpk_s(P[B], P[B + 1])
; #define ENDW(tt) do { if ((tt) + 3 < NT) { WAIT_BAR(2); } else if ((tt) + 2 < NT) { WAIT_BAR(1); } else { WAIT_BAR(0); } } while (0)
;     ...
;     int t = 1;
;     for (; t + 5 < NT; t += 2) {
;         STEP(pB0, pB1, pA0, pA1, t, true, true, true);     WAIT_BAR(2); RESC(); ROT();
;         STEP(pA0, pA1, pB0, pB1, t + 1, true, true, true); WAIT_BAR(2); RESC(); ROT();
;     }
;     ...
;     for (; t + 1 < NT; t += 2) {
;         STEP(pB0, pB1, pA0, pA1, t, (t + 3 < NT), (t + 1 < NT), (t + 1 < NT));         ENDW(t);     RESC(); ROT();
;         STEP(pA0, pA1, pB0, pB1, t + 1, (t + 4 < NT), (t + 2 < NT), (t + 2 < NT));     ENDW(t + 1); RESC(); ROT();
;     }
;     STEP(pB0, pB1, pA0, pA1, NT - 1, false, false, false); RESC();
;     { float sacc = pB0[0] + pB0[1]; _Pragma("unroll") for (int r = 2; r < 16; ++r) sacc += pB0[r]; _Pragma("unroll") for (int r = 0; r < 16; ++r) sacc += pB1[r]; l_reg += sacc;
;       pw0 = (u32x4){PKW(pB0, 0), PKW(pB0, 2), PKW(pB0, 4), PKW(pB0, 6)}; pw1 = (u32x4){PKW(pB0, 8), PKW(pB0, 10), PKW(pB0, 12), PKW(pB0, 14)}; pw2 = (u32x4){PKW(pB1, 0), PKW(pB1, 2), PKW(pB1, 4), PKW(pB1, 6)}; pw3 = (u32x4){PKW(pB1, 8), PKW(pB1, 10), PKW(pB1, 12), PKW(pB1, 14)};
;       SBAR(); const int vb0 = (int)(lds0 + LDS_V) + ((lane >> 4) & 1) * 32 + (lane & 3) * 8 + (4 * hi + ((lane & 15) >> 2)) * 64;
;       at::pv(o, vb0 + sl_cur, PAF(0), PAF(1), PAF(2), PAF(3)); }
	ds_read_b64_tr_b16 v[114:115], v190 offset:32768
	ds_read_b64_tr_b16 v[116:117], v190 offset:33280
	v_add_f32_e32 v2, v98, v99
	v_add_f32_e32 v2, v100, v2
	v_add_f32_e32 v2, v101, v2
	v_add_f32_e32 v2, v102, v2
	v_add_f32_e32 v2, v103, v2
	v_cvt_pk_bf16_f32 v146, v98, v99
	v_cvt_pk_bf16_f32 v147, v100, v101
	s_waitcnt lgkmcnt(9)
	v_mfma_f32_32x32x16_bf16 v[82:97], v[128:131], v[162:165], v[50:65]
	ds_read_b64_tr_b16 v[98:99], v190 offset:36864
	ds_read_b64_tr_b16 v[100:101], v190 offset:37376
	v_add_f32_e32 v2, v104, v2
	v_add_f32_e32 v2, v105, v2
	v_add_f32_e32 v2, v106, v2
	v_add_f32_e32 v2, v107, v2
	v_cvt_pk_bf16_f32 v148, v102, v103
	v_cvt_pk_bf16_f32 v149, v104, v105
	s_waitcnt lgkmcnt(10)
	v_mfma_f32_32x32x16_bf16 v[50:65], v[132:135], v[162:165], v[50:65]
	ds_read_b64_tr_b16 v[118:119], v190 offset:33792
	ds_read_b64_tr_b16 v[120:121], v190 offset:34304
	v_add_f32_e32 v2, v108, v2
	v_add_f32_e32 v2, v109, v2
	v_add_f32_e32 v2, v110, v2
	v_add_f32_e32 v2, v111, v2
	v_cvt_pk_bf16_f32 v10, v106, v107
	v_cvt_pk_bf16_f32 v11, v108, v109
	s_waitcnt lgkmcnt(11)
	v_mfma_f32_32x32x16_bf16 v[82:97], v[142:145], v[158:161], v[82:97]
	ds_read_b64_tr_b16 v[102:103], v190 offset:37888
	ds_read_b64_tr_b16 v[104:105], v190 offset:38400
	v_add_f32_e32 v2, v112, v2
	v_add_f32_e32 v2, v113, v2
	v_add_f32_e32 v2, v66, v2
	v_add_f32_e32 v2, v67, v2
	v_cvt_pk_bf16_f32 v12, v110, v111
	v_cvt_pk_bf16_f32 v13, v112, v113
	s_waitcnt lgkmcnt(12)
	v_mfma_f32_32x32x16_bf16 v[50:65], v[166:169], v[158:161], v[50:65]
	ds_read_b64_tr_b16 v[106:107], v190 offset:34816
	ds_read_b64_tr_b16 v[108:109], v190 offset:35328
	v_add_f32_e32 v2, v68, v2
	v_add_f32_e32 v2, v69, v2
	v_add_f32_e32 v2, v70, v2
	v_add_f32_e32 v2, v71, v2
	v_cvt_pk_bf16_f32 v6, v66, v67
	v_cvt_pk_bf16_f32 v7, v68, v69
	s_waitcnt lgkmcnt(13)
	v_mfma_f32_32x32x16_bf16 v[82:97], v[170:173], v[154:157], v[82:97]
	ds_read_b64_tr_b16 v[66:67], v190 offset:38912
	ds_read_b64_tr_b16 v[68:69], v190 offset:39424
	v_add_f32_e32 v2, v72, v2
	v_add_f32_e32 v2, v73, v2
	v_add_f32_e32 v2, v74, v2
	v_add_f32_e32 v2, v75, v2
	v_cvt_pk_bf16_f32 v8, v70, v71
	v_cvt_pk_bf16_f32 v9, v72, v73
	s_waitcnt lgkmcnt(14)
	v_mfma_f32_32x32x16_bf16 v[50:65], v[174:177], v[154:157], v[50:65]
	ds_read_b64_tr_b16 v[110:111], v190 offset:35840
	ds_read_b64_tr_b16 v[112:113], v190 offset:36352
	v_add_f32_e32 v2, v76, v2
	v_add_f32_e32 v2, v77, v2
	v_add_f32_e32 v2, v78, v2
	v_add_f32_e32 v127, v79, v2
	v_cvt_pk_bf16_f32 v2, v74, v75
	v_cvt_pk_bf16_f32 v3, v76, v77
	s_waitcnt lgkmcnt(14)
	v_mfma_f32_32x32x16_bf16 v[82:97], v[136:139], v[150:153], v[82:97]
	ds_read_b64_tr_b16 v[70:71], v190 offset:39936
	ds_read_b64_tr_b16 v[72:73], v190 offset:40448
	v_add_f32_e32 v4, v80, v127
	v_add_f32_e32 v4, v81, v4
	v_add_f32_e32 v74, 0, v4
	v_cvt_pk_bf16_f32 v4, v78, v79
	v_cvt_pk_bf16_f32 v5, v80, v81
	v_mfma_f32_32x32x16_bf16 v[50:65], v[122:125], v[150:153], v[50:65]
	s_nop 3
	v_exp_f32_e32 v82, v82
	v_exp_f32_e32 v83, v83
	v_exp_f32_e32 v84, v84
	v_exp_f32_e32 v85, v85
	s_nop 0
	v_exp_f32_e32 v86, v86
	v_exp_f32_e32 v87, v87
	v_exp_f32_e32 v88, v88
	v_exp_f32_e32 v89, v89
	s_nop 0
	v_exp_f32_e32 v90, v90
	v_exp_f32_e32 v91, v91
	v_exp_f32_e32 v92, v92
	v_exp_f32_e32 v93, v93
	s_nop 0
	v_exp_f32_e32 v94, v94
	v_exp_f32_e32 v95, v95
	v_exp_f32_e32 v96, v96
	v_exp_f32_e32 v97, v97
	v_exp_f32_e32 v50, v50
	v_exp_f32_e32 v51, v51
	v_exp_f32_e32 v52, v52
	v_exp_f32_e32 v53, v53
	s_nop 0
	v_exp_f32_e32 v54, v54
	v_exp_f32_e32 v55, v55
	v_exp_f32_e32 v56, v56
	v_exp_f32_e32 v57, v57
	s_nop 0
	v_exp_f32_e32 v58, v58
	v_exp_f32_e32 v59, v59
	v_exp_f32_e32 v60, v60
	v_exp_f32_e32 v61, v61
	s_nop 0
	v_exp_f32_e32 v62, v62
	v_exp_f32_e32 v63, v63
	v_exp_f32_e32 v64, v64
	v_exp_f32_e32 v65, v65
	s_waitcnt lgkmcnt(14)
	v_mfma_f32_32x32x16_bf16 v[18:33], v[146:149], v[114:117], v[18:33]
	v_add_f32_e32 v75, v82, v83
	v_add_f32_e32 v75, v84, v75
	v_add_f32_e32 v75, v85, v75
	v_add_f32_e32 v75, v86, v75
	v_add_f32_e32 v75, v87, v75
	v_add_f32_e32 v75, v88, v75
	v_add_f32_e32 v75, v89, v75
	s_waitcnt lgkmcnt(12)
	v_mfma_f32_32x32x16_bf16 v[34:49], v[146:149], v[98:101], v[34:49]
	v_add_f32_e32 v75, v90, v75
	v_add_f32_e32 v75, v91, v75
	v_add_f32_e32 v75, v92, v75
	v_add_f32_e32 v75, v93, v75
	v_add_f32_e32 v75, v94, v75
	v_add_f32_e32 v75, v95, v75
	v_add_f32_e32 v75, v96, v75
	s_waitcnt lgkmcnt(10)
	v_mfma_f32_32x32x16_bf16 v[18:33], v[10:13], v[118:121], v[18:33]
	v_add_f32_e32 v75, v97, v75
	v_add_f32_e32 v75, v50, v75
	v_add_f32_e32 v75, v51, v75
	v_add_f32_e32 v75, v52, v75
	v_add_f32_e32 v75, v53, v75
	v_add_f32_e32 v75, v54, v75
	v_add_f32_e32 v75, v55, v75
	s_waitcnt lgkmcnt(8)
	v_mfma_f32_32x32x16_bf16 v[34:49], v[10:13], v[102:105], v[34:49]
	v_add_f32_e32 v75, v56, v75
	v_add_f32_e32 v75, v57, v75
	v_add_f32_e32 v75, v58, v75
	v_add_f32_e32 v75, v59, v75
	v_add_f32_e32 v75, v60, v75
	v_add_f32_e32 v75, v61, v75
	v_add_f32_e32 v75, v62, v75
	s_waitcnt lgkmcnt(6)
	v_mfma_f32_32x32x16_bf16 v[18:33], v[6:9], v[106:109], v[18:33]
	v_add_f32_e32 v75, v63, v75
	v_add_f32_e32 v75, v64, v75
	v_add_f32_e32 v75, v65, v75
	v_add_f32_e32 v74, v126, v74
	v_add_f32_e32 v74, v74, v75
	v_cvt_pk_bf16_f32 v76, v82, v83
	v_cvt_pk_bf16_f32 v77, v84, v85
	s_waitcnt lgkmcnt(4)
	v_mfma_f32_32x32x16_bf16 v[34:49], v[6:9], v[66:69], v[34:49]
	v_cvt_pk_bf16_f32 v78, v86, v87
	v_cvt_pk_bf16_f32 v79, v88, v89
	v_cvt_pk_bf16_f32 v10, v90, v91
	v_cvt_pk_bf16_f32 v11, v92, v93
	v_cvt_pk_bf16_f32 v12, v94, v95
	v_cvt_pk_bf16_f32 v13, v96, v97
	v_cvt_pk_bf16_f32 v6, v50, v51
	s_waitcnt lgkmcnt(2)
; __device__ __forceinline__ int crow(int r, int hi) { return (r & 3) + 8 * (r >> 2) + 4 * hi; }
; #define AT_SBAR() __builtin_amdgcn_sched_barrier(0)
; __device__ __forceinline__ void pv(f32x16* o, int vb, bf16x8 pa0, bf16x8 pa1, bf16x8 pa2, bf16x8 pa3) {
; #pragma unroll
;     for (int d0 = 0; d0 < 2; ++d0) { s16x4 lo[4], hi[4];
; #pragma unroll
;         for (int ks = 0; ks < 4; ++ks) {
;             asm volatile("ds_read_b64_tr_b16 %0,%1 offset:%c2" : "=&v"(lo[ks]) : "v"(vb), "i"(d0 * 4096 + ks * 1024) : "memory");
;             asm volatile("ds_read_b64_tr_b16 %0,%1 offset:%c2" : "=&v"(hi[ks]) : "v"(vb), "i"(d0 * 4096 + ks * 1024 + 512) : "memory"); }
;         asm volatile("s_waitcnt lgkmcnt(0)" ::: "memory"); AT_SBAR();
;     ...
;         o[d0] = __builtin_amdgcn_mfma_f32_32x32x16_bf16(pa0, AT_PK(0), o[d0], 0, 0, 0);
;         o[d0] = __builtin_amdgcn_mfma_f32_32x32x16_bf16(pa1, AT_PK(1), o[d0], 0, 0, 0);
;         o[d0] = __builtin_amdgcn_mfma_f32_32x32x16_bf16(pa2, AT_PK(2), o[d0], 0, 0, 0);
;         o[d0] = __builtin_amdgcn_mfma_f32_32x32x16_bf16(pa3, AT_PK(3), o[d0], 0, 0, 0);
;     ...
;     }
; }
;     ...
;     STEP(pB0, pB1, pA0, pA1, NT - 1, false, false, false); RESC();
;     { float sacc = pB0[0] + pB0[1]; _Pragma("unroll") for (int r = 2; r < 16; ++r) sacc += pB0[r]; _Pragma("unroll") for (int r = 0; r < 16; ++r) sacc += pB1[r]; l_reg += sacc;
;       pw0 = (u32x4){PKW(pB0, 0), PKW(pB0, 2), PKW(pB0, 4), PKW(pB0, 6)}; pw1 = (u32x4){PKW(pB0, 8), PKW(pB0, 10), PKW(pB0, 12), PKW(pB0, 14)}; pw2 = (u32x4){PKW(pB1, 0), PKW(pB1, 2), PKW(pB1, 4), PKW(pB1, 6)}; pw3 = (u32x4){PKW(pB1, 8), PKW(pB1, 10), PKW(pB1, 12), PKW(pB1, 14)};
;       SBAR(); const int vb0 = (int)(lds0 + LDS_V) + ((lane >> 4) & 1) * 32 + (lane & 3) * 8 + (4 * hi + ((lane & 15) >> 2)) * 64;
;       at::pv(o, vb0 + sl_cur, PAF(0), PAF(1), PAF(2), PAF(3)); }
;     ...
;     { auto rr = __builtin_amdgcn_permlane32_swap(__float_as_uint(l_reg), __float_as_uint(l_reg), false, false); l_reg = __uint_as_float(rr[0]) + __uint_as_float(rr[1]); }
;     if (hi == 0) wsf[32 + r32] = l_reg; asm volatile("s_waitcnt lgkmcnt(0)" ::: "memory");
;     float rli[16];
; #pragma unroll
;     for (int r = 0; r < 16; ++r) rli[r] = __builtin_amdgcn_rcpf(wsf[32 + crow(r, hi)]);
;     at::store_tile(o, rli, (bf16_t*)(shm + LDS_OST) + wid * 2048, O + (long)(wid * QBLK) * OPITCH, OPITCH, ss + (long)(wid * QBLK) * 4, lane, r32, hi);
	v_mfma_f32_32x32x16_bf16 v[18:33], v[2:5], v[110:113], v[18:33]
	v_cvt_pk_bf16_f32 v7, v52, v53
	v_cvt_pk_bf16_f32 v8, v54, v55
	v_cvt_pk_bf16_f32 v9, v56, v57
	v_cvt_pk_bf16_f32 v50, v58, v59
	v_cvt_pk_bf16_f32 v51, v60, v61
	v_cvt_pk_bf16_f32 v52, v62, v63
	v_cvt_pk_bf16_f32 v53, v64, v65
	s_waitcnt lgkmcnt(0)
	v_mfma_f32_32x32x16_bf16 v[34:49], v[2:5], v[70:73], v[34:49]
	v_add_u32_e32 v2, s16, v188
	v_add3_u32 v66, v2, v187, v189
	ds_read_b64_tr_b16 v[2:3],v66 offset:0
	ds_read_b64_tr_b16 v[4:5],v66 offset:512
	ds_read_b64_tr_b16 v[54:55],v66 offset:1024
	ds_read_b64_tr_b16 v[56:57],v66 offset:1536
	ds_read_b64_tr_b16 v[58:59],v66 offset:2048
	ds_read_b64_tr_b16 v[60:61],v66 offset:2560
	ds_read_b64_tr_b16 v[62:63],v66 offset:3072
	ds_read_b64_tr_b16 v[64:65],v66 offset:3584
	s_waitcnt lgkmcnt(0)
	s_nop 0
	v_mfma_f32_32x32x16_bf16 v[18:33], v[76:79], v[2:5], v[18:33]
	ds_read_b64_tr_b16 v[2:3],v66 offset:4096
	ds_read_b64_tr_b16 v[4:5],v66 offset:4608
	v_mfma_f32_32x32x16_bf16 v[18:33], v[10:13], v[54:57], v[18:33]
	ds_read_b64_tr_b16 v[54:55],v66 offset:5120
	ds_read_b64_tr_b16 v[56:57],v66 offset:5632
	v_mfma_f32_32x32x16_bf16 v[18:33], v[6:9], v[58:61], v[18:33]
	ds_read_b64_tr_b16 v[58:59],v66 offset:6144
	ds_read_b64_tr_b16 v[60:61],v66 offset:6656
	v_mfma_f32_32x32x16_bf16 v[18:33], v[50:53], v[62:65], v[18:33]
	ds_read_b64_tr_b16 v[62:63],v66 offset:7168
	ds_read_b64_tr_b16 v[64:65],v66 offset:7680
	s_waitcnt lgkmcnt(0)
	v_mfma_f32_32x32x16_bf16 v[34:49], v[76:79], v[2:5], v[34:49]
	v_mov_b32_e32 v2, v74
	s_nop 1
	v_permlane32_swap_b32_e32 v74, v2
	v_cmp_gt_u32_e32 vcc, 32, v15
	v_mfma_f32_32x32x16_bf16 v[34:49], v[10:13], v[54:57], v[34:49]
	v_mfma_f32_32x32x16_bf16 v[34:49], v[6:9], v[58:61], v[34:49]
	v_mfma_f32_32x32x16_bf16 v[34:49], v[50:53], v[62:65], v[34:49]
	s_setprio 0
	s_and_saveexec_b64 s[12:13], vcc
	v_add_f32_e32 v2, v74, v2
	v_lshl_add_u32 v3, v17, 2, s2
	ds_write_b32 v3, v2 offset:49280
	s_or_b64 exec, exec, s[12:13]
	s_waitcnt lgkmcnt(0)
	v_lshl_add_u32 v10, v186, 4, s2
	ds_read_b128 v[2:5], v10 offset:49280
	ds_read_b128 v[6:9], v10 offset:49312
	s_lshl_b64 s[12:13], s[4:5], 11
	s_add_u32 s10, s10, s12
	s_addc_u32 s11, s11, s13
	s_lshl_b64 s[4:5], s[4:5], 4
	s_add_u32 s8, s8, s4
	s_waitcnt lgkmcnt(1)
	v_rcp_f32_e32 v11, v2
	s_addc_u32 s2, s9, s5
	s_add_u32 s6, s10, s6
	s_addc_u32 s7, s11, s7
	s_lshl_b32 s4, s19, 12
	v_rcp_f32_e32 v12, v3
	v_rcp_f32_e32 v13, v4
	v_rcp_f32_e32 v50, v5
	s_waitcnt lgkmcnt(0)
	v_rcp_f32_e32 v51, v6
	ds_read_b128 v[2:5], v10 offset:49344
	v_rcp_f32_e32 v52, v7
	v_rcp_f32_e32 v53, v8
	v_rcp_f32_e32 v54, v9
	ds_read_b128 v[6:9], v10 offset:49376
	s_add_i32 s9, s4, 0
	v_mul_f32_e32 v10, v18, v11
	v_lshlrev_b32_e32 v0, 1, v0
	v_lshlrev_b32_e32 v17, 1, v17
	v_cvt_pk_bf16_f32 v10, v10, s0
	v_add3_u32 v0, s9, v0, v17
	ds_write_b16 v0, v10 offset:51200
	v_mul_f32_e32 v10, v34, v11
	v_cvt_pk_bf16_f32 v10, v10, s0
	ds_write_b16 v0, v10 offset:51264
	v_mul_f32_e32 v10, v19, v12
	v_cvt_pk_bf16_f32 v10, v10, s0
	ds_write_b16 v0, v10 offset:51328
	v_mul_f32_e32 v10, v35, v12
	v_cvt_pk_bf16_f32 v10, v10, s0
	ds_write_b16 v0, v10 offset:51392
	v_mul_f32_e32 v10, v20, v13
	v_cvt_pk_bf16_f32 v10, v10, s0
	ds_write_b16 v0, v10 offset:51456
	v_mul_f32_e32 v10, v36, v13
	v_cvt_pk_bf16_f32 v10, v10, s0
	ds_write_b16 v0, v10 offset:51520
	v_mul_f32_e32 v10, v21, v50
	v_cvt_pk_bf16_f32 v10, v10, s0
	ds_write_b16 v0, v10 offset:51584
	v_mul_f32_e32 v10, v37, v50
	v_cvt_pk_bf16_f32 v10, v10, s0
	ds_write_b16 v0, v10 offset:51648
	v_mul_f32_e32 v10, v22, v51
	v_cvt_pk_bf16_f32 v10, v10, s0
	ds_write_b16 v0, v10 offset:52224
	v_mul_f32_e32 v10, v38, v51
	v_cvt_pk_bf16_f32 v10, v10, s0
	ds_write_b16 v0, v10 offset:52288
	v_mul_f32_e32 v10, v23, v52
	v_cvt_pk_bf16_f32 v10, v10, s0
	ds_write_b16 v0, v10 offset:52352
	v_mul_f32_e32 v10, v39, v52
	v_cvt_pk_bf16_f32 v10, v10, s0
	ds_write_b16 v0, v10 offset:52416
	v_mul_f32_e32 v10, v24, v53
	v_cvt_pk_bf16_f32 v10, v10, s0
	ds_write_b16 v0, v10 offset:52480
	v_mul_f32_e32 v10, v40, v53
	v_cvt_pk_bf16_f32 v10, v10, s0
	s_waitcnt lgkmcnt(14)
; __device__ __forceinline__ int crow(int r, int hi) { return (r & 3) + 8 * (r >> 2) + 4 * hi; }
; __device__ __forceinline__ unsigned cvtpk_s(float lo, float hi) { typedef __bf16 bf16x2_t __attribute__((ext_vector_type(2))); f32x2 v = {lo, hi}; bf16x2_t b = __builtin_convertvector(v, bf16x2_t); return __builtin_bit_cast(unsigned, b); }
; __device__ __forceinline__ void store_tile(const f32x16* o, const float* rli, bf16_t* stg, bf16_t* Ow, int pitch, float* ss, int lane, int r32, int hi) {
;     ...
;     for (int r = 0; r < 16; ++r) { const int orow = crow(r, hi);
; #pragma unroll
;         for (int d0 = 0; d0 < 2; ++d0) stg[orow * 64 + d0 * 32 + r32] = (bf16_t)(cvtpk_s(o[d0][r] * rli[r], 0.f) & 0xffffu); }
;     asm volatile("s_waitcnt lgkmcnt(0)" ::: "memory");
; #pragma unroll
;     for (int i = 0; i < 4; ++i) { const int row = i * 8 + (lane >> 3), ch = lane & 7; const u32x4 v = *(const u32x4*)(stg + row * 64 + ch * 8);
;         { const bf16_t* gp_ = Ow + (long)row * pitch + ch * 8; asm volatile("global_store_dwordx4 %0, %1, off sc0 sc1\n\ts_nop 1" :: "v"(gp_), "v"(v) : "memory"); }
;         float s = 0.f;
; #pragma unroll
;         for (int j = 0; j < 4; ++j) { const float a = __uint_as_float(v[j] << 16), b = __uint_as_float(v[j] & 0xffff0000u); s += a * a + b * b; }
;         s += __shfl_xor(s, 1); s += __shfl_xor(s, 2); s += __shfl_xor(s, 4);
;         if (ch == 0) atomicAdd(ss + (long)row * 4, s); }
	v_rcp_f32_e32 v2, v2
	ds_write_b16 v0, v10 offset:52544
	v_mul_f32_e32 v10, v25, v54
	v_cvt_pk_bf16_f32 v10, v10, s0
	v_rcp_f32_e32 v3, v3
	ds_write_b16 v0, v10 offset:52608
	v_mul_f32_e32 v10, v41, v54
	v_cvt_pk_bf16_f32 v10, v10, s0
	ds_write_b16 v0, v10 offset:52672
	v_mul_f32_e32 v10, v26, v2
	v_mul_f32_e32 v2, v42, v2
	v_cvt_pk_bf16_f32 v2, v2, s0
	v_rcp_f32_e32 v4, v4
	ds_write_b16 v0, v2 offset:53312
	v_mul_f32_e32 v2, v27, v3
	v_cvt_pk_bf16_f32 v2, v2, s0
	ds_write_b16 v0, v2 offset:53376
	v_mul_f32_e32 v2, v43, v3
	v_cvt_pk_bf16_f32 v2, v2, s0
	v_rcp_f32_e32 v5, v5
	ds_write_b16 v0, v2 offset:53440
	v_mul_f32_e32 v2, v28, v4
	v_cvt_pk_bf16_f32 v2, v2, s0
	ds_write_b16 v0, v2 offset:53504
	v_mul_f32_e32 v2, v44, v4
	v_cvt_pk_bf16_f32 v2, v2, s0
	s_waitcnt lgkmcnt(14)
	v_rcp_f32_e32 v6, v6
	ds_write_b16 v0, v2 offset:53568
	v_mul_f32_e32 v2, v29, v5
	v_cvt_pk_bf16_f32 v2, v2, s0
	ds_write_b16 v0, v2 offset:53632
	v_mul_f32_e32 v2, v45, v5
	v_cvt_pk_bf16_f32 v2, v2, s0
	v_rcp_f32_e32 v7, v7
	ds_write_b16 v0, v2 offset:53696
	v_mul_f32_e32 v2, v30, v6
	v_cvt_pk_bf16_f32 v2, v2, s0
	ds_write_b16 v0, v2 offset:54272
	v_mul_f32_e32 v2, v46, v6
	v_cvt_pk_bf16_f32 v2, v2, s0
	v_rcp_f32_e32 v8, v8
	ds_write_b16 v0, v2 offset:54336
	v_mul_f32_e32 v2, v31, v7
	v_cvt_pk_bf16_f32 v2, v2, s0
	ds_write_b16 v0, v2 offset:54400
	v_mul_f32_e32 v2, v47, v7
	v_cvt_pk_bf16_f32 v2, v2, s0
	v_rcp_f32_e32 v9, v9
	ds_write_b16 v0, v2 offset:54464
	v_mul_f32_e32 v2, v32, v8
	v_cvt_pk_bf16_f32 v2, v2, s0
	ds_write_b16 v0, v2 offset:54528
	v_mul_f32_e32 v2, v48, v8
	v_cvt_pk_bf16_f32 v2, v2, s0
	ds_write_b16 v0, v2 offset:54592
	v_mul_f32_e32 v2, v33, v9
	v_cvt_pk_bf16_f32 v2, v2, s0
	ds_write_b16 v0, v2 offset:54656
	v_mul_f32_e32 v2, v49, v9
	v_cvt_pk_bf16_f32 v10, v10, s0
	v_cvt_pk_bf16_f32 v2, v2, s0
	v_and_b32_e32 v6, 7, v14
	ds_write_b16 v0, v10 offset:53248
	ds_write_b16 v0, v2 offset:54720
	v_lshlrev_b32_e32 v0, 4, v6
	v_lshrrev_b32_e32 v7, 3, v15
	v_add_u32_e32 v8, s9, v0
	s_waitcnt lgkmcnt(0)
	v_lshl_add_u32 v2, v7, 7, v8
	ds_read_b128 v[12:15], v2 offset:51200
	s_lshl_b64 s[4:5], s[0:1], 11
	s_add_u32 s6, s6, s4
	s_addc_u32 s7, s7, s5
	s_lshl_b64 s[0:1], s[0:1], 4
	s_waitcnt lgkmcnt(0)
	v_and_b32_e32 v3, 0xffff0000, v12
	v_lshlrev_b32_e32 v2, 16, v12
	v_mul_f32_e32 v3, v3, v3
	v_and_b32_e32 v4, 0xffff0000, v13
	v_fmac_f32_e32 v3, v2, v2
	v_lshlrev_b32_e32 v2, 16, v13
	v_mul_f32_e32 v4, v4, v4
	v_fmac_f32_e32 v4, v2, v2
	v_add_f32_e32 v2, v3, v4
	v_and_b32_e32 v4, 0xffff0000, v14
	v_lshlrev_b32_e32 v3, 16, v14
	v_mul_f32_e32 v4, v4, v4
	v_fmac_f32_e32 v4, v3, v3
	v_add_f32_e32 v2, v4, v2
	v_and_b32_e32 v4, 0xffff0000, v15
	v_lshlrev_b32_e32 v3, 16, v15
	v_mul_f32_e32 v4, v4, v4
	v_fmac_f32_e32 v4, v3, v3
	v_and_b32_e32 v3, 64, v220
	v_add_f32_e32 v5, v4, v2
	v_xor_b32_e32 v2, 1, v220
	v_add_u32_e32 v10, 64, v3
	v_cmp_lt_i32_e32 vcc, v2, v10
	s_add_u32 s0, s8, s0
	s_addc_u32 s1, s2, s1
	v_cndmask_b32_e32 v2, v220, v2, vcc
	v_lshlrev_b32_e32 v4, 2, v2
	s_nop 1
	v_mov_b32_dpp v9, v5 quad_perm:[1,0,3,2] row_mask:0xf bank_mask:0xf
	v_lshl_add_u64 v[2:3], s[6:7], 0, v[0:1]
	v_xor_b32_e32 v0, 2, v220
	v_cmp_lt_i32_e32 vcc, v0, v10
	s_add_u32 s4, s0, 0x200008
	s_waitcnt lgkmcnt(0)
	v_add_f32_e32 v9, v5, v9
	v_cndmask_b32_e32 v0, v220, v0, vcc
	v_lshlrev_b32_e32 v5, 2, v0
	s_addc_u32 s5, s1, 0
	s_nop 1
	v_mov_b32_dpp v11, v9 quad_perm:[2,3,0,1] row_mask:0xf bank_mask:0xf
	s_mov_b64 s[0:1], 0x12e40500
	v_lshl_add_u64 v[2:3], v[2:3], 0, s[0:1]
	v_lshlrev_b32_e32 v0, 11, v7
	v_lshl_add_u64 v[18:19], v[2:3], 0, v[0:1]
	v_xor_b32_e32 v0, 4, v220
	v_cmp_lt_i32_e64 s[0:1], v0, v10
	v_cmp_eq_u32_e32 vcc, 0, v6
	s_waitcnt lgkmcnt(0)
	v_add_f32_e32 v9, v9, v11
	v_cndmask_b32_e64 v0, v220, v0, s[0:1]
	v_lshlrev_b32_e32 v6, 2, v0
	s_nop 1
	v_mov_b32_dpp v10, v9 row_half_mirror row_mask:0xf bank_mask:0xf
	global_store_dwordx4 v[18:19], v[12:15], off sc0 sc1
	s_nop 1
	s_and_saveexec_b64 s[0:1], vcc
	v_readlane_b32 s36, v253, 25
	v_readlane_b32 s37, v253, 26
	v_readlane_b32 s38, v253, 27
	v_readlane_b32 s39, v253, 28
	v_readlane_b32 s40, v253, 29
	v_readlane_b32 s41, v253, 30
	v_readlane_b32 s42, v253, 31
	v_readlane_b32 s43, v253, 32
	v_readlane_b32 s44, v253, 33
	v_readlane_b32 s45, v253, 34
	v_readlane_b32 s46, v253, 35
	v_readlane_b32 s47, v253, 36
	v_readlane_b32 s48, v253, 37
	v_readlane_b32 s49, v253, 38
	v_readlane_b32 s50, v253, 39
	v_readlane_b32 s51, v253, 40
	s_cbranch_execz .LBB0_881
	v_lshlrev_b32_e32 v0, 4, v7
	v_lshl_add_u64 v[12:13], s[4:5], 0, v[0:1]
	s_waitcnt lgkmcnt(0)
	v_add_f32_e32 v0, v9, v10
	flat_atomic_add_f32 v[12:13], v0
